# drop redundant lgkmcnt waits and setprio pairs in MMA blocks; zero accumulators with v_mov_b64; write-through MG stores in M7
# speedup vs baseline: 1.0061x; 1.0019x over previous
;     __device__ __forceinline__ const char* pa(const Gemm& g, const Unit& u, size_t tstep) const { return (const char*)g.A + (size_t)u.pm * tstep; }
;     __device__ __forceinline__ const char* pb(const Gemm& g, const Unit& u, size_t tstep) const { return (const char*)g.Bt + (size_t)u.pn * tstep; }
;     __device__ __forceinline__ const char* pa(const Gemm& g, const Unit& u, size_t tstep) const { return (const char*)g.A + (size_t)(u.pn >> 1) * 512 + (size_t)u.pm * tstep; }
;     __device__ __forceinline__ bool next(int i, Unit& u) const { const int ti = i / 3, sg = i - 3 * ti; if (!StaticOrder::next(ti, u)) return false; u.seg = sg; return true; }
;     __device__ __forceinline__ const char* pa(const Gemm& g, const Unit& u, size_t tstep) const { return (const char*)g.A + (size_t)u.seg * astride + (size_t)u.pm * tstep; }
;     __device__ __forceinline__ const char* pb(const Gemm& g, const Unit& u, size_t tstep) const { return (const char*)g.Bt + (size_t)u.seg * bstride + (size_t)u.pn * tstep; }
; #define PG8_LDA(dst, b, h) do { _Pragma("unroll") for (int m = 0; m < 4; ++m) _Pragma("unroll") for (int k = 0; k < 2; ++k) dst[m][k] = *(const PG8_LAS bf16x8*)(lds + PG8_SA(b, h) + aoff + m * 2048 + k * 1024); } while (0)
;     ...
;         const bool has_next = S.next(ui + 1, nxt);
;         const char* nA = has_next ? S.pa(g, nxt, tstepA) : cA; const char* nB = has_next ? S.pb(g, nxt, tstepB) : cB;
;         for (int t = 0; t < nt; t += 2) {
;             const bool last = (t == nt - 2);
;             const char* a1 = cA + (size_t)(t + 1) * kstep;
;             const char* a2 = last ? nA : cA + (size_t)(t + 2) * kstep; const char* b2 = last ? nB : cB + (size_t)(t + 2) * kstep;
;             const char* a3 = a2 + kstep; const char* b3 = b2 + kstep;
;             if (last && has_next) S.a_ready(nxt);
;             if constexpr (SP2) {
;             PG8_LDB(B0, 0, 0); PG8_LDB(B1, 0, 1); PG8_SCHED; PG8_LDA(At, 0, 0); PG8_STAGE(PG8_SA(1, 1), a1 + hstepA, voffA);
;             PG8_WAIT_V(8); PG8_WAIT_L(0); PG8_BAR; PG8_MMA(0, 0, At, B0); PG8_MMA(0, 1, At, B1); PG8_BAR; PG8_SCHED;
;     ...
; #pragma unroll
;         for (int a = 0; a < 2; ++a)
; #pragma unroll
;             for (int b = 0; b < 2; ++b)
; #pragma unroll
;                 for (int m = 0; m < 4; ++m)
; #pragma unroll
;                     for (int n = 0; n < 2; ++n) acc[a][b][m][n] = (f32x4){0.f, 0.f, 0.f, 0.f};
.LBB0_537:
	s_ashr_i32 s57, s56, 31
	s_lshl_b64 s[34:35], s[56:57], 19
	s_add_u32 s58, s11, s34
	s_addc_u32 s59, s24, s35
	s_and_b64 s[34:35], s[42:43], exec
	s_cselect_b32 s6, s59, s65
	s_cselect_b32 s15, s58, s64
	s_ashr_i32 s55, s54, 31
	s_lshl_b64 s[34:35], s[54:55], 19
	s_add_u32 s60, s79, s34
	s_addc_u32 s61, s80, s35
	s_and_b64 s[34:35], s[42:43], exec
	s_cselect_b32 s34, s61, s67
	s_cselect_b32 s35, s60, s66
	s_add_u32 s64, s64, 0x40080
	s_addc_u32 s65, s65, 0
	s_add_u32 s45, s66, 0x100
	v_mov_b32_e32 v2, 0
	s_addc_u32 s55, s67, 0
	s_mov_b32 s57, -2
	s_waitcnt lgkmcnt(0)
	v_mov_b32_e32 v3, v2
	v_mov_b64_e32 v[4:5], 0
	v_mov_b64_e32 v[6:7], 0
	v_mov_b64_e32 v[8:9], 0
	v_mov_b64_e32 v[10:11], 0
	v_mov_b64_e32 v[12:13], 0
	v_mov_b64_e32 v[14:15], 0
	v_mov_b64_e32 v[16:17], 0
	v_mov_b64_e32 v[18:19], 0
	v_mov_b64_e32 v[20:21], 0
	v_mov_b64_e32 v[22:23], 0
	v_mov_b64_e32 v[24:25], 0
	v_mov_b64_e32 v[26:27], 0
	v_mov_b64_e32 v[28:29], 0
	v_mov_b64_e32 v[30:31], 0
	v_mov_b64_e32 v[32:33], 0
	v_mov_b64_e32 v[36:37], 0
	v_mov_b64_e32 v[38:39], 0
	v_mov_b64_e32 v[40:41], 0
	v_mov_b64_e32 v[42:43], 0
	v_mov_b64_e32 v[44:45], 0
	v_mov_b64_e32 v[46:47], 0
	v_mov_b64_e32 v[48:49], 0
	v_mov_b64_e32 v[50:51], 0
	v_mov_b64_e32 v[52:53], 0
	v_mov_b64_e32 v[54:55], 0
	v_mov_b64_e32 v[56:57], 0
	v_mov_b64_e32 v[58:59], 0
	v_mov_b64_e32 v[60:61], 0
	v_mov_b64_e32 v[62:63], 0
	v_mov_b64_e32 v[64:65], 0
	v_mov_b64_e32 v[66:67], 0
	v_mov_b64_e32 v[68:69], 0
	v_mov_b64_e32 v[70:71], 0
	v_mov_b64_e32 v[72:73], 0
	v_mov_b64_e32 v[74:75], 0
	v_mov_b64_e32 v[76:77], 0
	v_mov_b64_e32 v[78:79], 0
	v_mov_b64_e32 v[80:81], 0
	v_mov_b64_e32 v[82:83], 0
	v_mov_b64_e32 v[84:85], 0
	v_mov_b64_e32 v[86:87], 0
	v_mov_b64_e32 v[88:89], 0
	v_mov_b64_e32 v[90:91], 0
	v_mov_b64_e32 v[92:93], 0
	v_mov_b64_e32 v[94:95], 0
	v_mov_b64_e32 v[96:97], 0
	v_mov_b64_e32 v[98:99], 0
	v_mov_b64_e32 v[100:101], 0
	v_mov_b64_e32 v[102:103], 0
	v_mov_b64_e32 v[104:105], 0
	v_mov_b64_e32 v[106:107], 0
	v_mov_b64_e32 v[108:109], 0
	v_mov_b64_e32 v[110:111], 0
	v_mov_b64_e32 v[112:113], 0
	v_mov_b64_e32 v[114:115], 0
	v_mov_b64_e32 v[116:117], 0
	v_mov_b64_e32 v[118:119], 0
	v_mov_b64_e32 v[120:121], 0
	v_mov_b64_e32 v[122:123], 0
	v_mov_b64_e32 v[124:125], 0
	v_mov_b64_e32 v[126:127], 0
	v_mov_b64_e32 v[128:129], 0
	v_mov_b64_e32 v[130:131], 0
.LBB0_538:
	s_add_u32 s63, s64, 0xfffc0080
	s_addc_u32 s66, s65, -1
	s_add_i32 s68, 0, 0x10000
	s_cmp_eq_u32 s57, 12
	s_cselect_b32 s75, s6, s66
	s_cselect_b32 s74, s15, s63
	v_add_u32_e32 v157, s68, v153
	s_cselect_b32 s67, s34, s55
	s_cselect_b32 s66, s35, s45
	s_add_i32 s63, 0, 0x14000
	ds_read_b128 v[142:145], v157
	ds_read_b128 v[146:149], v157 offset:1024
	ds_read_b128 v[158:161], v157 offset:2048
	ds_read_b128 v[186:189], v157 offset:3072
	v_add_u32_e32 v157, s63, v153
	ds_read_b128 v[190:193], v157
	ds_read_b128 v[194:197], v157 offset:1024
	ds_read_b128 v[198:201], v157 offset:2048
	ds_read_b128 v[202:205], v157 offset:3072
	v_lshl_add_u64 v[162:163], s[64:65], 0, v[138:139]
	s_add_i32 m0, s81, 0xc000
	ds_read_b128 v[206:209], v156
	ds_read_b128 v[210:213], v156 offset:1024
	ds_read_b128 v[214:217], v156 offset:2048
	ds_read_b128 v[218:221], v156 offset:3072
	ds_read_b128 v[222:225], v156 offset:4096
	ds_read_b128 v[234:237], v156 offset:5120
	ds_read_b128 v[238:241], v156 offset:6144
	ds_read_b128 v[242:245], v156 offset:7168
	global_load_lds_dwordx4 v[162:163], off
	v_lshl_add_u64 v[162:163], s[64:65], 0, v[140:141]
	s_add_i32 m0, s81, 0xe000
	s_nop 0
	global_load_lds_dwordx4 v[162:163], off
	s_waitcnt vmcnt(8)
	s_waitcnt lgkmcnt(0)
	s_barrier
	s_setprio 1
	v_mfma_i32_16x16x64_i8 v[128:131], v[142:145], v[206:209], v[128:131]
	v_mfma_i32_16x16x64_i8 v[120:123], v[158:161], v[206:209], v[120:123]
	v_mfma_i32_16x16x64_i8 v[112:115], v[142:145], v[214:217], v[112:115]
	v_mfma_i32_16x16x64_i8 v[104:107], v[158:161], v[214:217], v[104:107]
	v_mfma_i32_16x16x64_i8 v[96:99], v[142:145], v[222:225], v[96:99]
	v_mfma_i32_16x16x64_i8 v[88:91], v[158:161], v[222:225], v[88:91]
	v_mfma_i32_16x16x64_i8 v[80:83], v[142:145], v[238:241], v[80:83]
	v_mfma_i32_16x16x64_i8 v[72:75], v[158:161], v[238:241], v[72:75]
	v_mfma_i32_16x16x64_i8 v[128:131], v[146:149], v[210:213], v[128:131]
	v_mfma_i32_16x16x64_i8 v[120:123], v[186:189], v[210:213], v[120:123]
	v_mfma_i32_16x16x64_i8 v[112:115], v[146:149], v[218:221], v[112:115]
	v_mfma_i32_16x16x64_i8 v[104:107], v[186:189], v[218:221], v[104:107]
	v_mfma_i32_16x16x64_i8 v[96:99], v[146:149], v[234:237], v[96:99]
	v_mfma_i32_16x16x64_i8 v[88:91], v[186:189], v[234:237], v[88:91]
	v_mfma_i32_16x16x64_i8 v[80:83], v[146:149], v[242:245], v[80:83]
	v_mfma_i32_16x16x64_i8 v[72:75], v[186:189], v[242:245], v[72:75]
	v_mfma_i32_16x16x64_i8 v[124:127], v[190:193], v[206:209], v[124:127]
	v_mfma_i32_16x16x64_i8 v[116:119], v[198:201], v[206:209], v[116:119]
	v_mfma_i32_16x16x64_i8 v[108:111], v[190:193], v[214:217], v[108:111]
	v_mfma_i32_16x16x64_i8 v[100:103], v[198:201], v[214:217], v[100:103]
	v_mfma_i32_16x16x64_i8 v[92:95], v[190:193], v[222:225], v[92:95]
	v_mfma_i32_16x16x64_i8 v[84:87], v[198:201], v[222:225], v[84:87]
	v_mfma_i32_16x16x64_i8 v[76:79], v[190:193], v[238:241], v[76:79]
	v_mfma_i32_16x16x64_i8 v[68:71], v[198:201], v[238:241], v[68:71]
	v_mfma_i32_16x16x64_i8 v[124:127], v[194:197], v[210:213], v[124:127]
	v_mfma_i32_16x16x64_i8 v[116:119], v[202:205], v[210:213], v[116:119]
	v_mfma_i32_16x16x64_i8 v[108:111], v[194:197], v[218:221], v[108:111]
	v_mfma_i32_16x16x64_i8 v[100:103], v[202:205], v[218:221], v[100:103]
	v_mfma_i32_16x16x64_i8 v[92:95], v[194:197], v[234:237], v[92:95]
	v_mfma_i32_16x16x64_i8 v[84:87], v[202:205], v[234:237], v[84:87]
	v_mfma_i32_16x16x64_i8 v[76:79], v[194:197], v[242:245], v[76:79]
	v_mfma_i32_16x16x64_i8 v[68:71], v[202:205], v[242:245], v[68:71]
	s_setprio 0
	s_barrier
; #define PG8_STAGE(bufoff, gbase, voff) do { _Pragma("unroll") for (int _i = 0; _i < 2; ++_i) \
;         __builtin_amdgcn_global_load_lds((const unsigned*)((const char*)(gbase) + (voff)[_i]), (PG8_LAS unsigned*)(lds + (bufoff) + ldsw + _i * 8192), 16, 0, 0); } while (0)
; #define PG8_LDA(dst, b, h) do { _Pragma("unroll") for (int m = 0; m < 4; ++m) _Pragma("unroll") for (int k = 0; k < 2; ++k) dst[m][k] = *(const PG8_LAS bf16x8*)(lds + PG8_SA(b, h) + aoff + m * 2048 + k * 1024); } while (0)
; #define PG8_LDB(dst, b, h) do { _Pragma("unroll") for (int n = 0; n < 2; ++n) _Pragma("unroll") for (int k = 0; k < 2; ++k) dst[n][k] = *(const PG8_LAS bf16x8*)(lds + PG8_SB(b, h) + boff + n * 2048 + k * 1024); } while (0)
; #define PG8_WAIT_V(n) asm volatile("s_waitcnt vmcnt(" #n ")" ::: "memory")
; #define PG8_WAIT_L(n) asm volatile("s_waitcnt lgkmcnt(" #n ")" ::: "memory")
; #define PG8_BAR __builtin_amdgcn_s_barrier()
; #define PG8_SCHED __builtin_amdgcn_sched_barrier(0)
;     ...
;             PG8_LDA(At, 0, 1); PG8_STAGE(PG8_SB(0, 0), b2, voffB); PG8_STAGE(PG8_SB(0, 1), b2 + hstepB, voffB); PG8_STAGE(PG8_SA(0, 0), a2, voffA);
;             PG8_WAIT_V(8); PG8_WAIT_L(0); PG8_BAR; PG8_MMA(1, 0, At, B0); PG8_MMA(1, 1, At, B1); PG8_BAR; PG8_SCHED;
;             PG8_LDB(B0, 1, 0); PG8_LDB(B1, 1, 1); PG8_SCHED; PG8_LDA(At, 1, 0); PG8_STAGE(PG8_SA(0, 1), a2 + hstepA, voffA);
;             PG8_WAIT_V(8); PG8_WAIT_L(0); PG8_BAR; PG8_MMA(0, 0, At, B0); PG8_MMA(0, 1, At, B1); PG8_BAR; PG8_SCHED;
	s_add_i32 s68, s68, s10
	v_lshl_add_u64 v[162:163], s[66:67], 0, v[34:35]
	s_mov_b32 m0, s68
	ds_read_b128 v[206:209], v156 offset:16384
	ds_read_b128 v[210:213], v156 offset:17408
	ds_read_b128 v[214:217], v156 offset:18432
	ds_read_b128 v[218:221], v156 offset:19456
	ds_read_b128 v[222:225], v156 offset:20480
	ds_read_b128 v[234:237], v156 offset:21504
	ds_read_b128 v[238:241], v156 offset:22528
	ds_read_b128 v[242:245], v156 offset:23552
	global_load_lds_dwordx4 v[162:163], off
	s_add_i32 m0, s68, 0x2000
	s_add_u32 s70, s66, 0x40000
	v_lshl_add_u64 v[226:227], s[66:67], 0, v[136:137]
	s_addc_u32 s71, s67, 0
	s_add_i32 s63, s63, s10
	global_load_lds_dwordx4 v[226:227], off
	v_lshl_add_u64 v[246:247], s[70:71], 0, v[34:35]
	s_mov_b32 m0, s63
	v_lshl_add_u64 v[248:249], s[74:75], 0, v[134:135]
	global_load_lds_dwordx4 v[246:247], off
	v_lshl_add_u64 v[246:247], s[70:71], 0, v[136:137]
	s_add_i32 m0, s63, 0x2000
	s_nop 0
	global_load_lds_dwordx4 v[246:247], off
	v_lshl_add_u64 v[246:247], s[74:75], 0, v[132:133]
	s_mov_b32 m0, s81
	s_nop 0
	global_load_lds_dwordx4 v[246:247], off
	s_mov_b32 m0, s82
	s_nop 0
	global_load_lds_dwordx4 v[248:249], off
	s_waitcnt vmcnt(8)
	s_waitcnt lgkmcnt(0)
	s_barrier
	s_setprio 1
	v_mfma_i32_16x16x64_i8 v[64:67], v[142:145], v[206:209], v[64:67]
	v_mfma_i32_16x16x64_i8 v[56:59], v[158:161], v[206:209], v[56:59]
	v_mfma_i32_16x16x64_i8 v[48:51], v[142:145], v[214:217], v[48:51]
	v_mfma_i32_16x16x64_i8 v[40:43], v[158:161], v[214:217], v[40:43]
	v_mfma_i32_16x16x64_i8 v[30:33], v[142:145], v[222:225], v[30:33]
	v_mfma_i32_16x16x64_i8 v[22:25], v[158:161], v[222:225], v[22:25]
	v_mfma_i32_16x16x64_i8 v[14:17], v[142:145], v[238:241], v[14:17]
	v_mfma_i32_16x16x64_i8 v[6:9], v[158:161], v[238:241], v[6:9]
	v_mfma_i32_16x16x64_i8 v[64:67], v[146:149], v[210:213], v[64:67]
	v_mfma_i32_16x16x64_i8 v[56:59], v[186:189], v[210:213], v[56:59]
	v_mfma_i32_16x16x64_i8 v[48:51], v[146:149], v[218:221], v[48:51]
	v_mfma_i32_16x16x64_i8 v[40:43], v[186:189], v[218:221], v[40:43]
	v_mfma_i32_16x16x64_i8 v[30:33], v[146:149], v[234:237], v[30:33]
	v_mfma_i32_16x16x64_i8 v[22:25], v[186:189], v[234:237], v[22:25]
	v_mfma_i32_16x16x64_i8 v[14:17], v[146:149], v[242:245], v[14:17]
	v_mfma_i32_16x16x64_i8 v[6:9], v[186:189], v[242:245], v[6:9]
	v_mfma_i32_16x16x64_i8 v[60:63], v[190:193], v[206:209], v[60:63]
	v_mfma_i32_16x16x64_i8 v[52:55], v[198:201], v[206:209], v[52:55]
	v_mfma_i32_16x16x64_i8 v[44:47], v[190:193], v[214:217], v[44:47]
	v_mfma_i32_16x16x64_i8 v[36:39], v[198:201], v[214:217], v[36:39]
	v_mfma_i32_16x16x64_i8 v[26:29], v[190:193], v[222:225], v[26:29]
	v_mfma_i32_16x16x64_i8 v[18:21], v[198:201], v[222:225], v[18:21]
	v_mfma_i32_16x16x64_i8 v[10:13], v[190:193], v[238:241], v[10:13]
	v_mfma_i32_16x16x64_i8 v[2:5], v[198:201], v[238:241], v[2:5]
	v_mfma_i32_16x16x64_i8 v[60:63], v[194:197], v[210:213], v[60:63]
	v_mfma_i32_16x16x64_i8 v[52:55], v[202:205], v[210:213], v[52:55]
	v_mfma_i32_16x16x64_i8 v[44:47], v[194:197], v[218:221], v[44:47]
	v_mfma_i32_16x16x64_i8 v[36:39], v[202:205], v[218:221], v[36:39]
	v_mfma_i32_16x16x64_i8 v[26:29], v[194:197], v[234:237], v[26:29]
	v_mfma_i32_16x16x64_i8 v[18:21], v[202:205], v[234:237], v[18:21]
	v_mfma_i32_16x16x64_i8 v[10:13], v[194:197], v[242:245], v[10:13]
	v_mfma_i32_16x16x64_i8 v[2:5], v[202:205], v[242:245], v[2:5]
	s_setprio 0
	s_barrier
	s_add_i32 s63, 0, 0x18000
	v_add_u32_e32 v157, s63, v153
	s_add_i32 s68, 0, 0x1c000
	ds_read_b128 v[142:145], v157
	ds_read_b128 v[146:149], v157 offset:1024
	ds_read_b128 v[158:161], v157 offset:2048
	ds_read_b128 v[186:189], v157 offset:3072
	v_add_u32_e32 v157, s68, v153
	ds_read_b128 v[190:193], v157
	ds_read_b128 v[194:197], v157 offset:1024
	ds_read_b128 v[198:201], v157 offset:2048
	ds_read_b128 v[202:205], v157 offset:3072
	s_add_u32 s70, s74, 0x40000
	s_addc_u32 s71, s75, 0
	s_mov_b32 m0, s83
	v_lshl_add_u64 v[250:251], s[70:71], 0, v[132:133]
	ds_read_b128 v[206:209], v156 offset:32768
	ds_read_b128 v[210:213], v156 offset:33792
	ds_read_b128 v[214:217], v156 offset:34816
	ds_read_b128 v[218:221], v156 offset:35840
	ds_read_b128 v[222:225], v156 offset:36864
	ds_read_b128 v[234:237], v156 offset:37888
	ds_read_b128 v[238:241], v156 offset:38912
	ds_read_b128 v[242:245], v156 offset:39936
	global_load_lds_dwordx4 v[250:251], off
	v_lshl_add_u64 v[250:251], s[70:71], 0, v[134:135]
	s_mov_b32 m0, s84
	s_nop 0
	global_load_lds_dwordx4 v[250:251], off
	s_waitcnt vmcnt(8)
	s_waitcnt lgkmcnt(0)
	s_barrier
; #define PG8_STAGE(bufoff, gbase, voff) do { _Pragma("unroll") for (int _i = 0; _i < 2; ++_i) \
;         __builtin_amdgcn_global_load_lds((const unsigned*)((const char*)(gbase) + (voff)[_i]), (PG8_LAS unsigned*)(lds + (bufoff) + ldsw + _i * 8192), 16, 0, 0); } while (0)
; #define PG8_LDA(dst, b, h) do { _Pragma("unroll") for (int m = 0; m < 4; ++m) _Pragma("unroll") for (int k = 0; k < 2; ++k) dst[m][k] = *(const PG8_LAS bf16x8*)(lds + PG8_SA(b, h) + aoff + m * 2048 + k * 1024); } while (0)
; #define PG8_WAIT_V(n) asm volatile("s_waitcnt vmcnt(" #n ")" ::: "memory")
; #define PG8_WAIT_L(n) asm volatile("s_waitcnt lgkmcnt(" #n ")" ::: "memory")
; #define PG8_BAR __builtin_amdgcn_s_barrier()
; #define PG8_SCHED __builtin_amdgcn_sched_barrier(0)
;     __device__ __forceinline__ void operator()(const f32x4 (&acc)[2][2][4][2], const Unit& u, int wr, int wc, int fr, int fq) const {
;     ...
;                 float r[8]; const float scr_ = rs ? rs[row0 + ai * HALF + m * 16] * sc : sc;
;     ...
;             PG8_LDA(At, 1, 1); PG8_STAGE(PG8_SB(1, 0), b3, voffB); PG8_STAGE(PG8_SB(1, 1), b3 + hstepB, voffB); PG8_STAGE(PG8_SA(1, 0), a3, voffA);
;             PG8_WAIT_V(8); PG8_WAIT_L(0); PG8_BAR; PG8_MMA(1, 0, At, B0); PG8_MMA(1, 1, At, B1); PG8_BAR; PG8_SCHED;
	s_setprio 1
	v_mfma_i32_16x16x64_i8 v[128:131], v[142:145], v[206:209], v[128:131]
	v_mfma_i32_16x16x64_i8 v[120:123], v[158:161], v[206:209], v[120:123]
	v_mfma_i32_16x16x64_i8 v[112:115], v[142:145], v[214:217], v[112:115]
	v_mfma_i32_16x16x64_i8 v[104:107], v[158:161], v[214:217], v[104:107]
	v_mfma_i32_16x16x64_i8 v[96:99], v[142:145], v[222:225], v[96:99]
	v_mfma_i32_16x16x64_i8 v[88:91], v[158:161], v[222:225], v[88:91]
	v_mfma_i32_16x16x64_i8 v[80:83], v[142:145], v[238:241], v[80:83]
	v_mfma_i32_16x16x64_i8 v[72:75], v[158:161], v[238:241], v[72:75]
	v_mfma_i32_16x16x64_i8 v[128:131], v[146:149], v[210:213], v[128:131]
	v_mfma_i32_16x16x64_i8 v[120:123], v[186:189], v[210:213], v[120:123]
	v_mfma_i32_16x16x64_i8 v[112:115], v[146:149], v[218:221], v[112:115]
	v_mfma_i32_16x16x64_i8 v[104:107], v[186:189], v[218:221], v[104:107]
	v_mfma_i32_16x16x64_i8 v[96:99], v[146:149], v[234:237], v[96:99]
	v_mfma_i32_16x16x64_i8 v[88:91], v[186:189], v[234:237], v[88:91]
	v_mfma_i32_16x16x64_i8 v[80:83], v[146:149], v[242:245], v[80:83]
	v_mfma_i32_16x16x64_i8 v[72:75], v[186:189], v[242:245], v[72:75]
	v_mfma_i32_16x16x64_i8 v[124:127], v[190:193], v[206:209], v[124:127]
	v_mfma_i32_16x16x64_i8 v[116:119], v[198:201], v[206:209], v[116:119]
	v_mfma_i32_16x16x64_i8 v[108:111], v[190:193], v[214:217], v[108:111]
	v_mfma_i32_16x16x64_i8 v[100:103], v[198:201], v[214:217], v[100:103]
	v_mfma_i32_16x16x64_i8 v[92:95], v[190:193], v[222:225], v[92:95]
	v_mfma_i32_16x16x64_i8 v[84:87], v[198:201], v[222:225], v[84:87]
	v_mfma_i32_16x16x64_i8 v[76:79], v[190:193], v[238:241], v[76:79]
	v_mfma_i32_16x16x64_i8 v[68:71], v[198:201], v[238:241], v[68:71]
	v_mfma_i32_16x16x64_i8 v[124:127], v[194:197], v[210:213], v[124:127]
	v_mfma_i32_16x16x64_i8 v[116:119], v[202:205], v[210:213], v[116:119]
	v_mfma_i32_16x16x64_i8 v[108:111], v[194:197], v[218:221], v[108:111]
	v_mfma_i32_16x16x64_i8 v[100:103], v[202:205], v[218:221], v[100:103]
	v_mfma_i32_16x16x64_i8 v[92:95], v[194:197], v[234:237], v[92:95]
	v_mfma_i32_16x16x64_i8 v[84:87], v[202:205], v[234:237], v[84:87]
	v_mfma_i32_16x16x64_i8 v[76:79], v[194:197], v[242:245], v[76:79]
	v_mfma_i32_16x16x64_i8 v[68:71], v[202:205], v[242:245], v[68:71]
	s_setprio 0
	s_barrier
	s_add_i32 s63, s63, s10
	v_lshl_add_u64 v[162:163], v[162:163], 0, s[22:23]
	s_mov_b32 m0, s63
	ds_read_b128 v[206:209], v156 offset:49152
	ds_read_b128 v[210:213], v156 offset:50176
	ds_read_b128 v[214:217], v156 offset:51200
	ds_read_b128 v[218:221], v156 offset:52224
	ds_read_b128 v[222:225], v156 offset:53248
	ds_read_b128 v[234:237], v156 offset:54272
	ds_read_b128 v[238:241], v156 offset:55296
	ds_read_b128 v[242:245], v156 offset:56320
	global_load_lds_dwordx4 v[162:163], off
	s_add_i32 m0, s63, 0x2000
	s_add_u32 s66, s66, 0x40080
	v_lshl_add_u64 v[162:163], v[226:227], 0, s[22:23]
	s_addc_u32 s67, s67, 0
	s_add_i32 s63, s68, s10
	global_load_lds_dwordx4 v[162:163], off
	v_lshl_add_u64 v[162:163], s[66:67], 0, v[34:35]
	s_mov_b32 m0, s63
	s_nop 0
	global_load_lds_dwordx4 v[162:163], off
	v_lshl_add_u64 v[162:163], s[66:67], 0, v[136:137]
	s_add_i32 m0, s63, 0x2000
	s_nop 0
	global_load_lds_dwordx4 v[162:163], off
	v_lshl_add_u64 v[162:163], v[246:247], 0, s[22:23]
	s_mov_b32 m0, s86
	s_nop 0
	global_load_lds_dwordx4 v[162:163], off
	v_lshl_add_u64 v[162:163], v[248:249], 0, s[22:23]
	s_mov_b32 m0, s87
	s_nop 0
	global_load_lds_dwordx4 v[162:163], off
	s_waitcnt vmcnt(8)
	s_waitcnt lgkmcnt(0)
	s_barrier
	s_setprio 1
	v_mfma_i32_16x16x64_i8 v[64:67], v[142:145], v[206:209], v[64:67]
	v_mfma_i32_16x16x64_i8 v[56:59], v[158:161], v[206:209], v[56:59]
	v_mfma_i32_16x16x64_i8 v[48:51], v[142:145], v[214:217], v[48:51]
	v_mfma_i32_16x16x64_i8 v[40:43], v[158:161], v[214:217], v[40:43]
	v_mfma_i32_16x16x64_i8 v[30:33], v[142:145], v[222:225], v[30:33]
	v_mfma_i32_16x16x64_i8 v[22:25], v[158:161], v[222:225], v[22:25]
	v_mfma_i32_16x16x64_i8 v[14:17], v[142:145], v[238:241], v[14:17]
	v_mfma_i32_16x16x64_i8 v[6:9], v[158:161], v[238:241], v[6:9]
	v_mfma_i32_16x16x64_i8 v[64:67], v[146:149], v[210:213], v[64:67]
	v_mfma_i32_16x16x64_i8 v[56:59], v[186:189], v[210:213], v[56:59]
	v_mfma_i32_16x16x64_i8 v[48:51], v[146:149], v[218:221], v[48:51]
	v_mfma_i32_16x16x64_i8 v[40:43], v[186:189], v[218:221], v[40:43]
	v_mfma_i32_16x16x64_i8 v[30:33], v[146:149], v[234:237], v[30:33]
	v_mfma_i32_16x16x64_i8 v[22:25], v[186:189], v[234:237], v[22:25]
	v_mfma_i32_16x16x64_i8 v[14:17], v[146:149], v[242:245], v[14:17]
	v_mfma_i32_16x16x64_i8 v[6:9], v[186:189], v[242:245], v[6:9]
	v_mfma_i32_16x16x64_i8 v[60:63], v[190:193], v[206:209], v[60:63]
	v_mfma_i32_16x16x64_i8 v[52:55], v[198:201], v[206:209], v[52:55]
	v_mfma_i32_16x16x64_i8 v[44:47], v[190:193], v[214:217], v[44:47]
	v_mfma_i32_16x16x64_i8 v[36:39], v[198:201], v[214:217], v[36:39]
	v_mfma_i32_16x16x64_i8 v[26:29], v[190:193], v[222:225], v[26:29]
	v_mfma_i32_16x16x64_i8 v[18:21], v[198:201], v[222:225], v[18:21]
	v_mfma_i32_16x16x64_i8 v[10:13], v[190:193], v[238:241], v[10:13]
	v_mfma_i32_16x16x64_i8 v[2:5], v[198:201], v[238:241], v[2:5]
	v_mfma_i32_16x16x64_i8 v[60:63], v[194:197], v[210:213], v[60:63]
	v_mfma_i32_16x16x64_i8 v[52:55], v[202:205], v[210:213], v[52:55]
	v_mfma_i32_16x16x64_i8 v[44:47], v[194:197], v[218:221], v[44:47]
	v_mfma_i32_16x16x64_i8 v[36:39], v[202:205], v[218:221], v[36:39]
	v_mfma_i32_16x16x64_i8 v[26:29], v[194:197], v[234:237], v[26:29]
	v_mfma_i32_16x16x64_i8 v[18:21], v[202:205], v[234:237], v[18:21]
	v_mfma_i32_16x16x64_i8 v[10:13], v[194:197], v[242:245], v[10:13]
	v_mfma_i32_16x16x64_i8 v[2:5], v[202:205], v[242:245], v[2:5]
	s_setprio 0
	s_barrier
	s_add_i32 s57, s57, 2
	s_add_u32 s64, s64, 0x100
	s_addc_u32 s65, s65, 0
	s_add_u32 s45, s45, 0x100
	s_addc_u32 s55, s55, 0
	s_cmp_gt_u32 s57, 13
	s_cbranch_scc0 .LBB0_538
	v_lshl_add_u32 v144, s62, 8, v152
	v_ashrrev_i32_e32 v145, 31, v144
	v_lshl_add_u64 v[146:147], v[144:145], 2, s[50:51]
	global_load_dword v186, v[146:147], off
	global_load_dword v187, v[146:147], off offset:64
	global_load_dword v188, v[146:147], off offset:128
	global_load_dword v189, v[146:147], off offset:192
	global_load_dword v190, v[146:147], off offset:512
	global_load_dword v191, v[146:147], off offset:576
	global_load_dword v192, v[146:147], off offset:640
	global_load_dword v193, v[146:147], off offset:704
	s_and_b64 vcc, exec, s[52:53]
	s_cbranch_vccz .LBB0_541
	s_barrier

;     __device__ __forceinline__ const char* pa(const Gemm& g, const Unit& u, size_t tstep) const { return (const char*)g.A + (size_t)u.pm * tstep; }
;     __device__ __forceinline__ const char* pb(const Gemm& g, const Unit& u, size_t tstep) const { return (const char*)g.Bt + (size_t)u.pn * tstep; }
;     __device__ __forceinline__ const char* pa(const Gemm& g, const Unit& u, size_t tstep) const { return (const char*)g.A + (size_t)(u.pn >> 1) * 512 + (size_t)u.pm * tstep; }
;     __device__ __forceinline__ bool next(int i, Unit& u) const { const int ti = i / 3, sg = i - 3 * ti; if (!StaticOrder::next(ti, u)) return false; u.seg = sg; return true; }
;     __device__ __forceinline__ const char* pa(const Gemm& g, const Unit& u, size_t tstep) const { return (const char*)g.A + (size_t)u.seg * astride + (size_t)u.pm * tstep; }
;     __device__ __forceinline__ const char* pb(const Gemm& g, const Unit& u, size_t tstep) const { return (const char*)g.Bt + (size_t)u.seg * bstride + (size_t)u.pn * tstep; }
; #define PG8_LDA(dst, b, h) do { _Pragma("unroll") for (int m = 0; m < 4; ++m) _Pragma("unroll") for (int k = 0; k < 2; ++k) dst[m][k] = *(const PG8_LAS bf16x8*)(lds + PG8_SA(b, h) + aoff + m * 2048 + k * 1024); } while (0)
;     ...
;         const bool has_next = S.next(ui + 1, nxt);
;         const char* nA = has_next ? S.pa(g, nxt, tstepA) : cA; const char* nB = has_next ? S.pb(g, nxt, tstepB) : cB;
;         for (int t = 0; t < nt; t += 2) {
;             const bool last = (t == nt - 2);
;             const char* a1 = cA + (size_t)(t + 1) * kstep;
;             const char* a2 = last ? nA : cA + (size_t)(t + 2) * kstep; const char* b2 = last ? nB : cB + (size_t)(t + 2) * kstep;
;             const char* a3 = a2 + kstep; const char* b3 = b2 + kstep;
;             if (last && has_next) S.a_ready(nxt);
;             if constexpr (SP2) {
;             PG8_LDB(B0, 0, 0); PG8_LDB(B1, 0, 1); PG8_SCHED; PG8_LDA(At, 0, 0); PG8_STAGE(PG8_SA(1, 1), a1 + hstepA, voffA);
;             PG8_WAIT_V(8); PG8_WAIT_L(0); PG8_BAR; PG8_MMA(0, 0, At, B0); PG8_MMA(0, 1, At, B1); PG8_BAR; PG8_SCHED;
;     ...
; #pragma unroll
;         for (int a = 0; a < 2; ++a)
; #pragma unroll
;             for (int b = 0; b < 2; ++b)
; #pragma unroll
;                 for (int m = 0; m < 4; ++m)
; #pragma unroll
;                     for (int n = 0; n < 2; ++n) acc[a][b][m][n] = (f32x4){0.f, 0.f, 0.f, 0.f};
.LBB0_607:
	s_ashr_i32 s37, s36, 31
	s_lshl_b64 s[40:41], s[36:37], 20
	s_add_u32 s40, s8, s40
	s_addc_u32 s41, s10, s41
	s_and_b64 s[42:43], s[38:39], exec
	s_cselect_b32 s37, s41, s51
	s_cselect_b32 s58, s40, s50
	s_ashr_i32 s31, s30, 31
	s_lshl_b64 s[42:43], s[30:31], 20
	s_add_u32 s42, s9, s42
	s_addc_u32 s43, s76, s43
	s_and_b64 s[54:55], s[38:39], exec
	s_cselect_b32 s31, s43, s53
	s_cselect_b32 s59, s42, s52
	s_add_u32 s50, s50, 0x80080
	s_addc_u32 s51, s51, 0
	s_add_u32 s60, s52, 0x100
	v_mov_b32_e32 v2, 0
	s_addc_u32 s61, s53, 0
	s_mov_b32 s62, -2
	v_mov_b32_e32 v3, v2
	v_mov_b64_e32 v[4:5], 0
	v_mov_b64_e32 v[6:7], 0
	v_mov_b64_e32 v[8:9], 0
	v_mov_b64_e32 v[10:11], 0
	v_mov_b64_e32 v[12:13], 0
	v_mov_b64_e32 v[14:15], 0
	v_mov_b64_e32 v[16:17], 0
	v_mov_b64_e32 v[18:19], 0
	v_mov_b64_e32 v[20:21], 0
	v_mov_b64_e32 v[22:23], 0
	v_mov_b64_e32 v[24:25], 0
	v_mov_b64_e32 v[26:27], 0
	v_mov_b64_e32 v[28:29], 0
	v_mov_b64_e32 v[30:31], 0
	v_mov_b64_e32 v[32:33], 0
	v_mov_b64_e32 v[36:37], 0
	v_mov_b64_e32 v[38:39], 0
	v_mov_b64_e32 v[40:41], 0
	v_mov_b64_e32 v[42:43], 0
	v_mov_b64_e32 v[44:45], 0
	v_mov_b64_e32 v[46:47], 0
	v_mov_b64_e32 v[48:49], 0
	v_mov_b64_e32 v[50:51], 0
	v_mov_b64_e32 v[52:53], 0
	v_mov_b64_e32 v[54:55], 0
	v_mov_b64_e32 v[56:57], 0
	v_mov_b64_e32 v[58:59], 0
	v_mov_b64_e32 v[60:61], 0
	v_mov_b64_e32 v[62:63], 0
	v_mov_b64_e32 v[64:65], 0
	v_mov_b64_e32 v[66:67], 0
	v_mov_b64_e32 v[68:69], 0
	v_mov_b64_e32 v[70:71], 0
	v_mov_b64_e32 v[72:73], 0
	v_mov_b64_e32 v[74:75], 0
	v_mov_b64_e32 v[76:77], 0
	v_mov_b64_e32 v[78:79], 0
	v_mov_b64_e32 v[80:81], 0
	v_mov_b64_e32 v[82:83], 0
	v_mov_b64_e32 v[84:85], 0
	v_mov_b64_e32 v[86:87], 0
	v_mov_b64_e32 v[88:89], 0
	v_mov_b64_e32 v[90:91], 0
	v_mov_b64_e32 v[92:93], 0
	v_mov_b64_e32 v[94:95], 0
	v_mov_b64_e32 v[96:97], 0
	v_mov_b64_e32 v[98:99], 0
	v_mov_b64_e32 v[100:101], 0
	v_mov_b64_e32 v[102:103], 0
	v_mov_b64_e32 v[104:105], 0
	v_mov_b64_e32 v[106:107], 0
	v_mov_b64_e32 v[108:109], 0
	v_mov_b64_e32 v[110:111], 0
	v_mov_b64_e32 v[112:113], 0
	v_mov_b64_e32 v[114:115], 0
	v_mov_b64_e32 v[116:117], 0
	v_mov_b64_e32 v[118:119], 0
	v_mov_b64_e32 v[120:121], 0
	v_mov_b64_e32 v[122:123], 0
	v_mov_b64_e32 v[124:125], 0
	v_mov_b64_e32 v[126:127], 0
	v_mov_b64_e32 v[128:129], 0
	v_mov_b64_e32 v[130:131], 0
.LBB0_608:
	s_add_u32 s52, s50, 0xfff80080
	s_addc_u32 s53, s51, -1
	s_add_i32 s63, 0, 0x10000
	s_cmp_eq_u32 s62, 28
	s_cselect_b32 s55, s37, s53
	s_cselect_b32 s54, s58, s52
	v_add_u32_e32 v142, s63, v145
	s_cselect_b32 s53, s31, s61
	s_cselect_b32 s52, s59, s60
	s_add_i32 s66, 0, 0x14000
	ds_read_b128 v[148:151], v142
	ds_read_b128 v[152:155], v142 offset:1024
	ds_read_b128 v[156:159], v142 offset:2048
	ds_read_b128 v[160:163], v142 offset:3072
	v_add_u32_e32 v142, s66, v145
	ds_read_b128 v[186:189], v142
	ds_read_b128 v[190:193], v142 offset:1024
	ds_read_b128 v[194:197], v142 offset:2048
	ds_read_b128 v[198:201], v142 offset:3072
	v_lshl_add_u64 v[142:143], s[50:51], 0, v[138:139]
	s_add_i32 m0, s12, 0xc000
	ds_read_b128 v[202:205], v147
	ds_read_b128 v[206:209], v147 offset:1024
	ds_read_b128 v[210:213], v147 offset:2048
	ds_read_b128 v[214:217], v147 offset:3072
	ds_read_b128 v[218:221], v147 offset:4096
	ds_read_b128 v[222:225], v147 offset:5120
	ds_read_b128 v[234:237], v147 offset:6144
	ds_read_b128 v[238:241], v147 offset:7168
	global_load_lds_dwordx4 v[142:143], off
	v_lshl_add_u64 v[142:143], s[50:51], 0, v[140:141]
	s_add_i32 m0, s12, 0xe000
	s_nop 0
	global_load_lds_dwordx4 v[142:143], off
	s_waitcnt vmcnt(8)
	s_waitcnt lgkmcnt(0)
	s_barrier
	s_setprio 1
	v_mfma_f32_16x16x32_bf16 v[128:131], v[148:151], v[202:205], v[128:131]
	v_mfma_f32_16x16x32_bf16 v[124:127], v[156:159], v[202:205], v[124:127]
	v_mfma_f32_16x16x32_bf16 v[112:115], v[148:151], v[210:213], v[112:115]
	v_mfma_f32_16x16x32_bf16 v[108:111], v[156:159], v[210:213], v[108:111]
	v_mfma_f32_16x16x32_bf16 v[96:99], v[148:151], v[218:221], v[96:99]
	v_mfma_f32_16x16x32_bf16 v[92:95], v[156:159], v[218:221], v[92:95]
	v_mfma_f32_16x16x32_bf16 v[80:83], v[148:151], v[234:237], v[80:83]
	v_mfma_f32_16x16x32_bf16 v[76:79], v[156:159], v[234:237], v[76:79]
	v_mfma_f32_16x16x32_bf16 v[128:131], v[152:155], v[206:209], v[128:131]
	v_mfma_f32_16x16x32_bf16 v[124:127], v[160:163], v[206:209], v[124:127]
	v_mfma_f32_16x16x32_bf16 v[112:115], v[152:155], v[214:217], v[112:115]
	v_mfma_f32_16x16x32_bf16 v[108:111], v[160:163], v[214:217], v[108:111]
	v_mfma_f32_16x16x32_bf16 v[96:99], v[152:155], v[222:225], v[96:99]
	v_mfma_f32_16x16x32_bf16 v[92:95], v[160:163], v[222:225], v[92:95]
	v_mfma_f32_16x16x32_bf16 v[80:83], v[152:155], v[238:241], v[80:83]
	v_mfma_f32_16x16x32_bf16 v[76:79], v[160:163], v[238:241], v[76:79]
	v_mfma_f32_16x16x32_bf16 v[120:123], v[186:189], v[202:205], v[120:123]
	v_mfma_f32_16x16x32_bf16 v[116:119], v[194:197], v[202:205], v[116:119]
	v_mfma_f32_16x16x32_bf16 v[104:107], v[186:189], v[210:213], v[104:107]
	v_mfma_f32_16x16x32_bf16 v[100:103], v[194:197], v[210:213], v[100:103]
	v_mfma_f32_16x16x32_bf16 v[88:91], v[186:189], v[218:221], v[88:91]
	v_mfma_f32_16x16x32_bf16 v[84:87], v[194:197], v[218:221], v[84:87]
	v_mfma_f32_16x16x32_bf16 v[72:75], v[186:189], v[234:237], v[72:75]
	v_mfma_f32_16x16x32_bf16 v[68:71], v[194:197], v[234:237], v[68:71]
	v_mfma_f32_16x16x32_bf16 v[120:123], v[190:193], v[206:209], v[120:123]
	v_mfma_f32_16x16x32_bf16 v[116:119], v[198:201], v[206:209], v[116:119]
	v_mfma_f32_16x16x32_bf16 v[104:107], v[190:193], v[214:217], v[104:107]
	v_mfma_f32_16x16x32_bf16 v[100:103], v[198:201], v[214:217], v[100:103]
	v_mfma_f32_16x16x32_bf16 v[88:91], v[190:193], v[222:225], v[88:91]
	v_mfma_f32_16x16x32_bf16 v[84:87], v[198:201], v[222:225], v[84:87]
	v_mfma_f32_16x16x32_bf16 v[72:75], v[190:193], v[238:241], v[72:75]
	v_mfma_f32_16x16x32_bf16 v[68:71], v[198:201], v[238:241], v[68:71]
	s_setprio 0
	s_barrier
; #define PG8_STAGE(bufoff, gbase, voff) do { _Pragma("unroll") for (int _i = 0; _i < 2; ++_i) \
;         __builtin_amdgcn_global_load_lds((const unsigned*)((const char*)(gbase) + (voff)[_i]), (PG8_LAS unsigned*)(lds + (bufoff) + ldsw + _i * 8192), 16, 0, 0); } while (0)
; #define PG8_LDA(dst, b, h) do { _Pragma("unroll") for (int m = 0; m < 4; ++m) _Pragma("unroll") for (int k = 0; k < 2; ++k) dst[m][k] = *(const PG8_LAS bf16x8*)(lds + PG8_SA(b, h) + aoff + m * 2048 + k * 1024); } while (0)
; #define PG8_LDB(dst, b, h) do { _Pragma("unroll") for (int n = 0; n < 2; ++n) _Pragma("unroll") for (int k = 0; k < 2; ++k) dst[n][k] = *(const PG8_LAS bf16x8*)(lds + PG8_SB(b, h) + boff + n * 2048 + k * 1024); } while (0)
; #define PG8_WAIT_V(n) asm volatile("s_waitcnt vmcnt(" #n ")" ::: "memory")
; #define PG8_WAIT_L(n) asm volatile("s_waitcnt lgkmcnt(" #n ")" ::: "memory")
; #define PG8_BAR __builtin_amdgcn_s_barrier()
; #define PG8_SCHED __builtin_amdgcn_sched_barrier(0)
;     ...
;             PG8_LDA(At, 0, 1); PG8_STAGE(PG8_SB(0, 0), b2, voffB); PG8_STAGE(PG8_SB(0, 1), b2 + hstepB, voffB); PG8_STAGE(PG8_SA(0, 0), a2, voffA);
;             PG8_WAIT_V(8); PG8_WAIT_L(0); PG8_BAR; PG8_MMA(1, 0, At, B0); PG8_MMA(1, 1, At, B1); PG8_BAR; PG8_SCHED;
;             PG8_LDB(B0, 1, 0); PG8_LDB(B1, 1, 1); PG8_SCHED; PG8_LDA(At, 1, 0); PG8_STAGE(PG8_SA(0, 1), a2 + hstepA, voffA);
;             PG8_WAIT_V(8); PG8_WAIT_L(0); PG8_BAR; PG8_MMA(0, 0, At, B0); PG8_MMA(0, 1, At, B1); PG8_BAR; PG8_SCHED;
	s_add_i32 s63, s63, s6
	v_lshl_add_u64 v[142:143], s[52:53], 0, v[34:35]
	s_mov_b32 m0, s63
	ds_read_b128 v[202:205], v147 offset:16384
	ds_read_b128 v[206:209], v147 offset:17408
	ds_read_b128 v[210:213], v147 offset:18432
	ds_read_b128 v[214:217], v147 offset:19456
	ds_read_b128 v[218:221], v147 offset:20480
	ds_read_b128 v[222:225], v147 offset:21504
	ds_read_b128 v[234:237], v147 offset:22528
	ds_read_b128 v[238:241], v147 offset:23552
	global_load_lds_dwordx4 v[142:143], off
	s_add_i32 m0, s63, 0x2000
	s_add_u32 s64, s52, 0x80000
	v_lshl_add_u64 v[226:227], s[52:53], 0, v[132:133]
	s_addc_u32 s65, s53, 0
	s_add_i32 s63, s66, s6
	global_load_lds_dwordx4 v[226:227], off
	v_lshl_add_u64 v[242:243], s[64:65], 0, v[34:35]
	s_mov_b32 m0, s63
	v_lshl_add_u64 v[244:245], s[54:55], 0, v[134:135]
	global_load_lds_dwordx4 v[242:243], off
	v_lshl_add_u64 v[242:243], s[64:65], 0, v[132:133]
	s_add_i32 m0, s63, 0x2000
	s_nop 0
	global_load_lds_dwordx4 v[242:243], off
	v_lshl_add_u64 v[242:243], s[54:55], 0, v[136:137]
	s_mov_b32 m0, s12
	s_nop 0
	global_load_lds_dwordx4 v[242:243], off
	s_mov_b32 m0, s13
	s_nop 0
	global_load_lds_dwordx4 v[244:245], off
	s_waitcnt vmcnt(8)
	s_waitcnt lgkmcnt(0)
	s_barrier
	s_setprio 1
	v_mfma_f32_16x16x32_bf16 v[64:67], v[148:151], v[202:205], v[64:67]
	v_mfma_f32_16x16x32_bf16 v[60:63], v[156:159], v[202:205], v[60:63]
	v_mfma_f32_16x16x32_bf16 v[48:51], v[148:151], v[210:213], v[48:51]
	v_mfma_f32_16x16x32_bf16 v[44:47], v[156:159], v[210:213], v[44:47]
	v_mfma_f32_16x16x32_bf16 v[30:33], v[148:151], v[218:221], v[30:33]
	v_mfma_f32_16x16x32_bf16 v[26:29], v[156:159], v[218:221], v[26:29]
	v_mfma_f32_16x16x32_bf16 v[14:17], v[148:151], v[234:237], v[14:17]
	v_mfma_f32_16x16x32_bf16 v[10:13], v[156:159], v[234:237], v[10:13]
	v_mfma_f32_16x16x32_bf16 v[64:67], v[152:155], v[206:209], v[64:67]
	v_mfma_f32_16x16x32_bf16 v[60:63], v[160:163], v[206:209], v[60:63]
	v_mfma_f32_16x16x32_bf16 v[48:51], v[152:155], v[214:217], v[48:51]
	v_mfma_f32_16x16x32_bf16 v[44:47], v[160:163], v[214:217], v[44:47]
	v_mfma_f32_16x16x32_bf16 v[30:33], v[152:155], v[222:225], v[30:33]
	v_mfma_f32_16x16x32_bf16 v[26:29], v[160:163], v[222:225], v[26:29]
	v_mfma_f32_16x16x32_bf16 v[14:17], v[152:155], v[238:241], v[14:17]
	v_mfma_f32_16x16x32_bf16 v[10:13], v[160:163], v[238:241], v[10:13]
	v_mfma_f32_16x16x32_bf16 v[56:59], v[186:189], v[202:205], v[56:59]
	v_mfma_f32_16x16x32_bf16 v[52:55], v[194:197], v[202:205], v[52:55]
	v_mfma_f32_16x16x32_bf16 v[40:43], v[186:189], v[210:213], v[40:43]
	v_mfma_f32_16x16x32_bf16 v[36:39], v[194:197], v[210:213], v[36:39]
	v_mfma_f32_16x16x32_bf16 v[22:25], v[186:189], v[218:221], v[22:25]
	v_mfma_f32_16x16x32_bf16 v[18:21], v[194:197], v[218:221], v[18:21]
	v_mfma_f32_16x16x32_bf16 v[6:9], v[186:189], v[234:237], v[6:9]
	v_mfma_f32_16x16x32_bf16 v[2:5], v[194:197], v[234:237], v[2:5]
	v_mfma_f32_16x16x32_bf16 v[56:59], v[190:193], v[206:209], v[56:59]
	v_mfma_f32_16x16x32_bf16 v[52:55], v[198:201], v[206:209], v[52:55]
	v_mfma_f32_16x16x32_bf16 v[40:43], v[190:193], v[214:217], v[40:43]
	v_mfma_f32_16x16x32_bf16 v[36:39], v[198:201], v[214:217], v[36:39]
	v_mfma_f32_16x16x32_bf16 v[22:25], v[190:193], v[222:225], v[22:25]
	v_mfma_f32_16x16x32_bf16 v[18:21], v[198:201], v[222:225], v[18:21]
	v_mfma_f32_16x16x32_bf16 v[6:9], v[190:193], v[238:241], v[6:9]
	v_mfma_f32_16x16x32_bf16 v[2:5], v[198:201], v[238:241], v[2:5]
	s_setprio 0
	s_barrier
	s_add_i32 s63, 0, 0x18000
	s_add_i32 s64, 0, 0x1c000
	v_add_u32_e32 v160, s63, v145
	v_add_u32_e32 v198, s64, v145
	ds_read_b128 v[148:151], v160
	ds_read_b128 v[152:155], v160 offset:1024
	ds_read_b128 v[156:159], v160 offset:2048
	ds_read_b128 v[160:163], v160 offset:3072
	ds_read_b128 v[186:189], v198
	ds_read_b128 v[190:193], v198 offset:1024
	ds_read_b128 v[194:197], v198 offset:2048
	ds_read_b128 v[198:201], v198 offset:3072
	s_add_u32 s54, s54, 0x80000
	s_addc_u32 s55, s55, 0
	s_mov_b32 m0, s15
	v_lshl_add_u64 v[246:247], s[54:55], 0, v[136:137]
	ds_read_b128 v[202:205], v147 offset:32768
	ds_read_b128 v[206:209], v147 offset:33792
	ds_read_b128 v[210:213], v147 offset:34816
	ds_read_b128 v[214:217], v147 offset:35840
	ds_read_b128 v[218:221], v147 offset:36864
	ds_read_b128 v[222:225], v147 offset:37888
	ds_read_b128 v[234:237], v147 offset:38912
	ds_read_b128 v[238:241], v147 offset:39936
	global_load_lds_dwordx4 v[246:247], off
	v_lshl_add_u64 v[246:247], s[54:55], 0, v[134:135]
	s_mov_b32 m0, s34
	s_nop 0
	global_load_lds_dwordx4 v[246:247], off
	s_waitcnt vmcnt(8)
	s_waitcnt lgkmcnt(0)
	s_barrier
; #define PG8_STAGE(bufoff, gbase, voff) do { _Pragma("unroll") for (int _i = 0; _i < 2; ++_i) \
;         __builtin_amdgcn_global_load_lds((const unsigned*)((const char*)(gbase) + (voff)[_i]), (PG8_LAS unsigned*)(lds + (bufoff) + ldsw + _i * 8192), 16, 0, 0); } while (0)
; #define PG8_LDA(dst, b, h) do { _Pragma("unroll") for (int m = 0; m < 4; ++m) _Pragma("unroll") for (int k = 0; k < 2; ++k) dst[m][k] = *(const PG8_LAS bf16x8*)(lds + PG8_SA(b, h) + aoff + m * 2048 + k * 1024); } while (0)
; #define PG8_WAIT_V(n) asm volatile("s_waitcnt vmcnt(" #n ")" ::: "memory")
; #define PG8_WAIT_L(n) asm volatile("s_waitcnt lgkmcnt(" #n ")" ::: "memory")
; #define PG8_BAR __builtin_amdgcn_s_barrier()
; #define PG8_SCHED __builtin_amdgcn_sched_barrier(0)
;     ...
;             PG8_LDA(At, 1, 1); PG8_STAGE(PG8_SB(1, 0), b3, voffB); PG8_STAGE(PG8_SB(1, 1), b3 + hstepB, voffB); PG8_STAGE(PG8_SA(1, 0), a3, voffA);
;             PG8_WAIT_V(8); PG8_WAIT_L(0); PG8_BAR; PG8_MMA(1, 0, At, B0); PG8_MMA(1, 1, At, B1); PG8_BAR; PG8_SCHED;
	s_setprio 1
	v_mfma_f32_16x16x32_bf16 v[128:131], v[148:151], v[202:205], v[128:131]
	v_mfma_f32_16x16x32_bf16 v[124:127], v[156:159], v[202:205], v[124:127]
	v_mfma_f32_16x16x32_bf16 v[112:115], v[148:151], v[210:213], v[112:115]
	v_mfma_f32_16x16x32_bf16 v[108:111], v[156:159], v[210:213], v[108:111]
	v_mfma_f32_16x16x32_bf16 v[96:99], v[148:151], v[218:221], v[96:99]
	v_mfma_f32_16x16x32_bf16 v[92:95], v[156:159], v[218:221], v[92:95]
	v_mfma_f32_16x16x32_bf16 v[80:83], v[148:151], v[234:237], v[80:83]
	v_mfma_f32_16x16x32_bf16 v[76:79], v[156:159], v[234:237], v[76:79]
	v_mfma_f32_16x16x32_bf16 v[128:131], v[152:155], v[206:209], v[128:131]
	v_mfma_f32_16x16x32_bf16 v[124:127], v[160:163], v[206:209], v[124:127]
	v_mfma_f32_16x16x32_bf16 v[112:115], v[152:155], v[214:217], v[112:115]
	v_mfma_f32_16x16x32_bf16 v[108:111], v[160:163], v[214:217], v[108:111]
	v_mfma_f32_16x16x32_bf16 v[96:99], v[152:155], v[222:225], v[96:99]
	v_mfma_f32_16x16x32_bf16 v[92:95], v[160:163], v[222:225], v[92:95]
	v_mfma_f32_16x16x32_bf16 v[80:83], v[152:155], v[238:241], v[80:83]
	v_mfma_f32_16x16x32_bf16 v[76:79], v[160:163], v[238:241], v[76:79]
	v_mfma_f32_16x16x32_bf16 v[120:123], v[186:189], v[202:205], v[120:123]
	v_mfma_f32_16x16x32_bf16 v[116:119], v[194:197], v[202:205], v[116:119]
	v_mfma_f32_16x16x32_bf16 v[104:107], v[186:189], v[210:213], v[104:107]
	v_mfma_f32_16x16x32_bf16 v[100:103], v[194:197], v[210:213], v[100:103]
	v_mfma_f32_16x16x32_bf16 v[88:91], v[186:189], v[218:221], v[88:91]
	v_mfma_f32_16x16x32_bf16 v[84:87], v[194:197], v[218:221], v[84:87]
	v_mfma_f32_16x16x32_bf16 v[72:75], v[186:189], v[234:237], v[72:75]
	v_mfma_f32_16x16x32_bf16 v[68:71], v[194:197], v[234:237], v[68:71]
	v_mfma_f32_16x16x32_bf16 v[120:123], v[190:193], v[206:209], v[120:123]
	v_mfma_f32_16x16x32_bf16 v[116:119], v[198:201], v[206:209], v[116:119]
	v_mfma_f32_16x16x32_bf16 v[104:107], v[190:193], v[214:217], v[104:107]
	v_mfma_f32_16x16x32_bf16 v[100:103], v[198:201], v[214:217], v[100:103]
	v_mfma_f32_16x16x32_bf16 v[88:91], v[190:193], v[222:225], v[88:91]
	v_mfma_f32_16x16x32_bf16 v[84:87], v[198:201], v[222:225], v[84:87]
	v_mfma_f32_16x16x32_bf16 v[72:75], v[190:193], v[238:241], v[72:75]
	v_mfma_f32_16x16x32_bf16 v[68:71], v[198:201], v[238:241], v[68:71]
	s_setprio 0
	s_barrier
	s_add_i32 s54, s63, s6
	v_lshl_add_u64 v[142:143], v[142:143], 0, s[22:23]
	s_mov_b32 m0, s54
	ds_read_b128 v[202:205], v147 offset:49152
	ds_read_b128 v[206:209], v147 offset:50176
	ds_read_b128 v[210:213], v147 offset:51200
	ds_read_b128 v[214:217], v147 offset:52224
	ds_read_b128 v[218:221], v147 offset:53248
	ds_read_b128 v[222:225], v147 offset:54272
	ds_read_b128 v[234:237], v147 offset:55296
	ds_read_b128 v[238:241], v147 offset:56320
	global_load_lds_dwordx4 v[142:143], off
	s_add_i32 m0, s54, 0x2000
	s_add_u32 s52, s52, 0x80080
	v_lshl_add_u64 v[142:143], v[226:227], 0, s[22:23]
	s_addc_u32 s53, s53, 0
	s_add_i32 s54, s64, s6
	global_load_lds_dwordx4 v[142:143], off
	v_lshl_add_u64 v[142:143], s[52:53], 0, v[34:35]
	s_mov_b32 m0, s54
	s_nop 0
	global_load_lds_dwordx4 v[142:143], off
	v_lshl_add_u64 v[142:143], s[52:53], 0, v[132:133]
	s_add_i32 m0, s54, 0x2000
	s_nop 0
	global_load_lds_dwordx4 v[142:143], off
	v_lshl_add_u64 v[142:143], v[242:243], 0, s[22:23]
	s_mov_b32 m0, s24
	s_nop 0
	global_load_lds_dwordx4 v[142:143], off
	v_lshl_add_u64 v[142:143], v[244:245], 0, s[22:23]
	s_mov_b32 m0, s35
	s_nop 0
	global_load_lds_dwordx4 v[142:143], off
	s_waitcnt vmcnt(8)
	s_waitcnt lgkmcnt(0)
	s_barrier
	s_setprio 1
	v_mfma_f32_16x16x32_bf16 v[64:67], v[148:151], v[202:205], v[64:67]
	v_mfma_f32_16x16x32_bf16 v[60:63], v[156:159], v[202:205], v[60:63]
	v_mfma_f32_16x16x32_bf16 v[48:51], v[148:151], v[210:213], v[48:51]
	v_mfma_f32_16x16x32_bf16 v[44:47], v[156:159], v[210:213], v[44:47]
	v_mfma_f32_16x16x32_bf16 v[30:33], v[148:151], v[218:221], v[30:33]
	v_mfma_f32_16x16x32_bf16 v[26:29], v[156:159], v[218:221], v[26:29]
	v_mfma_f32_16x16x32_bf16 v[14:17], v[148:151], v[234:237], v[14:17]
	v_mfma_f32_16x16x32_bf16 v[10:13], v[156:159], v[234:237], v[10:13]
	v_mfma_f32_16x16x32_bf16 v[64:67], v[152:155], v[206:209], v[64:67]
	v_mfma_f32_16x16x32_bf16 v[60:63], v[160:163], v[206:209], v[60:63]
	v_mfma_f32_16x16x32_bf16 v[48:51], v[152:155], v[214:217], v[48:51]
	v_mfma_f32_16x16x32_bf16 v[44:47], v[160:163], v[214:217], v[44:47]
	v_mfma_f32_16x16x32_bf16 v[30:33], v[152:155], v[222:225], v[30:33]
	v_mfma_f32_16x16x32_bf16 v[26:29], v[160:163], v[222:225], v[26:29]
	v_mfma_f32_16x16x32_bf16 v[14:17], v[152:155], v[238:241], v[14:17]
	v_mfma_f32_16x16x32_bf16 v[10:13], v[160:163], v[238:241], v[10:13]
	v_mfma_f32_16x16x32_bf16 v[56:59], v[186:189], v[202:205], v[56:59]
	v_mfma_f32_16x16x32_bf16 v[52:55], v[194:197], v[202:205], v[52:55]
	v_mfma_f32_16x16x32_bf16 v[40:43], v[186:189], v[210:213], v[40:43]
	v_mfma_f32_16x16x32_bf16 v[36:39], v[194:197], v[210:213], v[36:39]
	v_mfma_f32_16x16x32_bf16 v[22:25], v[186:189], v[218:221], v[22:25]
	v_mfma_f32_16x16x32_bf16 v[18:21], v[194:197], v[218:221], v[18:21]
	v_mfma_f32_16x16x32_bf16 v[6:9], v[186:189], v[234:237], v[6:9]
	v_mfma_f32_16x16x32_bf16 v[2:5], v[194:197], v[234:237], v[2:5]
	v_mfma_f32_16x16x32_bf16 v[56:59], v[190:193], v[206:209], v[56:59]
	v_mfma_f32_16x16x32_bf16 v[52:55], v[198:201], v[206:209], v[52:55]
	v_mfma_f32_16x16x32_bf16 v[40:43], v[190:193], v[214:217], v[40:43]
	v_mfma_f32_16x16x32_bf16 v[36:39], v[198:201], v[214:217], v[36:39]
	v_mfma_f32_16x16x32_bf16 v[22:25], v[190:193], v[222:225], v[22:25]
	v_mfma_f32_16x16x32_bf16 v[18:21], v[198:201], v[222:225], v[18:21]
	v_mfma_f32_16x16x32_bf16 v[6:9], v[190:193], v[238:241], v[6:9]
	v_mfma_f32_16x16x32_bf16 v[2:5], v[198:201], v[238:241], v[2:5]
	s_setprio 0
	s_barrier
	s_add_i32 s62, s62, 2
	s_add_u32 s50, s50, 0x100
	s_addc_u32 s51, s51, 0
	s_add_u32 s60, s60, 0x100
	s_addc_u32 s61, s61, 0
	s_cmp_gt_u32 s62, 29
	s_cbranch_scc0 .LBB0_608
	s_and_b64 vcc, exec, s[28:29]
	s_cbranch_vccz .LBB0_611
	s_barrier

;     __device__ __forceinline__ const char* pa(const Gemm& g, const Unit& u, size_t tstep) const { return (const char*)g.A + (size_t)u.pm * tstep; }
;     __device__ __forceinline__ const char* pb(const Gemm& g, const Unit& u, size_t tstep) const { return (const char*)g.Bt + (size_t)u.pn * tstep; }
;     __device__ __forceinline__ const char* pa(const Gemm& g, const Unit& u, size_t tstep) const { return (const char*)g.A + (size_t)(u.pn >> 1) * 512 + (size_t)u.pm * tstep; }
;     __device__ __forceinline__ bool next(int i, Unit& u) const { const int ti = i / 3, sg = i - 3 * ti; if (!StaticOrder::next(ti, u)) return false; u.seg = sg; return true; }
;     __device__ __forceinline__ const char* pa(const Gemm& g, const Unit& u, size_t tstep) const { return (const char*)g.A + (size_t)u.seg * astride + (size_t)u.pm * tstep; }
;     __device__ __forceinline__ const char* pb(const Gemm& g, const Unit& u, size_t tstep) const { return (const char*)g.Bt + (size_t)u.seg * bstride + (size_t)u.pn * tstep; }
; #define PG8_LDA(dst, b, h) do { _Pragma("unroll") for (int m = 0; m < 4; ++m) _Pragma("unroll") for (int k = 0; k < 2; ++k) dst[m][k] = *(const PG8_LAS bf16x8*)(lds + PG8_SA(b, h) + aoff + m * 2048 + k * 1024); } while (0)
;     ...
;         const bool has_next = S.next(ui + 1, nxt);
;         const char* nA = has_next ? S.pa(g, nxt, tstepA) : cA; const char* nB = has_next ? S.pb(g, nxt, tstepB) : cB;
;         for (int t = 0; t < nt; t += 2) {
;             const bool last = (t == nt - 2);
;             const char* a1 = cA + (size_t)(t + 1) * kstep;
;             const char* a2 = last ? nA : cA + (size_t)(t + 2) * kstep; const char* b2 = last ? nB : cB + (size_t)(t + 2) * kstep;
;             const char* a3 = a2 + kstep; const char* b3 = b2 + kstep;
;             if (last && has_next) S.a_ready(nxt);
;             if constexpr (SP2) {
;             PG8_LDB(B0, 0, 0); PG8_LDB(B1, 0, 1); PG8_SCHED; PG8_LDA(At, 0, 0); PG8_STAGE(PG8_SA(1, 1), a1 + hstepA, voffA);
;             PG8_WAIT_V(8); PG8_WAIT_L(0); PG8_BAR; PG8_MMA(0, 0, At, B0); PG8_MMA(0, 1, At, B1); PG8_BAR; PG8_SCHED;
;     ...
; #pragma unroll
;         for (int a = 0; a < 2; ++a)
; #pragma unroll
;             for (int b = 0; b < 2; ++b)
; #pragma unroll
;                 for (int m = 0; m < 4; ++m)
; #pragma unroll
;                     for (int n = 0; n < 2; ++n) acc[a][b][m][n] = (f32x4){0.f, 0.f, 0.f, 0.f};
.LBB0_693:
	s_add_u32 s64, s44, 0x100
	v_mov_b32_e32 v2, 0
	s_addc_u32 s65, s45, 0
	s_mov_b32 s66, -2
	v_mov_b32_e32 v3, v2
	v_mov_b64_e32 v[4:5], 0
	v_mov_b64_e32 v[6:7], 0
	v_mov_b64_e32 v[8:9], 0
	v_mov_b64_e32 v[10:11], 0
	v_mov_b64_e32 v[12:13], 0
	v_mov_b64_e32 v[14:15], 0
	v_mov_b64_e32 v[16:17], 0
	v_mov_b64_e32 v[18:19], 0
	v_mov_b64_e32 v[20:21], 0
	v_mov_b64_e32 v[22:23], 0
	v_mov_b64_e32 v[24:25], 0
	v_mov_b64_e32 v[26:27], 0
	v_mov_b64_e32 v[28:29], 0
	v_mov_b64_e32 v[30:31], 0
	v_mov_b64_e32 v[32:33], 0
	v_mov_b64_e32 v[36:37], 0
	v_mov_b64_e32 v[38:39], 0
	v_mov_b64_e32 v[40:41], 0
	v_mov_b64_e32 v[42:43], 0
	v_mov_b64_e32 v[44:45], 0
	v_mov_b64_e32 v[46:47], 0
	v_mov_b64_e32 v[48:49], 0
	v_mov_b64_e32 v[50:51], 0
	v_mov_b64_e32 v[52:53], 0
	v_mov_b64_e32 v[54:55], 0
	v_mov_b64_e32 v[56:57], 0
	v_mov_b64_e32 v[58:59], 0
	v_mov_b64_e32 v[60:61], 0
	v_mov_b64_e32 v[62:63], 0
	v_mov_b64_e32 v[64:65], 0
	v_mov_b64_e32 v[66:67], 0
	v_mov_b64_e32 v[68:69], 0
	v_mov_b64_e32 v[70:71], 0
	v_mov_b64_e32 v[72:73], 0
	v_mov_b64_e32 v[74:75], 0
	v_mov_b64_e32 v[76:77], 0
	v_mov_b64_e32 v[78:79], 0
	v_mov_b64_e32 v[80:81], 0
	v_mov_b64_e32 v[82:83], 0
	v_mov_b64_e32 v[84:85], 0
	v_mov_b64_e32 v[86:87], 0
	v_mov_b64_e32 v[88:89], 0
	v_mov_b64_e32 v[90:91], 0
	v_mov_b64_e32 v[92:93], 0
	v_mov_b64_e32 v[94:95], 0
	v_mov_b64_e32 v[96:97], 0
	v_mov_b64_e32 v[98:99], 0
	v_mov_b64_e32 v[100:101], 0
	v_mov_b64_e32 v[102:103], 0
	v_mov_b64_e32 v[104:105], 0
	v_mov_b64_e32 v[106:107], 0
	v_mov_b64_e32 v[108:109], 0
	v_mov_b64_e32 v[110:111], 0
	v_mov_b64_e32 v[112:113], 0
	v_mov_b64_e32 v[114:115], 0
	v_mov_b64_e32 v[116:117], 0
	v_mov_b64_e32 v[118:119], 0
	v_mov_b64_e32 v[120:121], 0
	v_mov_b64_e32 v[122:123], 0
	v_mov_b64_e32 v[124:125], 0
	v_mov_b64_e32 v[126:127], 0
	v_mov_b64_e32 v[128:129], 0
	v_mov_b64_e32 v[130:131], 0
.LBB0_694:
	s_add_u32 s44, s42, 0x100
	s_addc_u32 s45, s43, 0
	s_add_i32 s67, 0, 0x10000
	s_cmpk_eq_i32 s66, 0x54
	s_cselect_b32 s53, s37, s45
	s_cselect_b32 s52, s36, s44
	s_cselect_b32 s51, s41, s65
	s_cselect_b32 s50, s40, s64
	s_add_i32 s68, 0, 0x14000
	v_add_u32_e32 v158, s67, v143
	v_add_u32_e32 v162, s68, v143
	ds_read_b128 v[146:149], v158
	ds_read_b128 v[150:153], v158 offset:1024
	ds_read_b128 v[154:157], v158 offset:2048
	ds_read_b128 v[158:161], v158 offset:3072
	ds_read_b128 v[186:189], v162
	ds_read_b128 v[190:193], v162 offset:1024
	ds_read_b128 v[194:197], v162 offset:2048
	ds_read_b128 v[198:201], v162 offset:3072
	v_lshl_add_u64 v[162:163], s[42:43], 0, v[138:139]
	s_add_i32 m0, s34, 0xc000
	ds_read_b128 v[202:205], v145
	ds_read_b128 v[206:209], v145 offset:1024
	ds_read_b128 v[210:213], v145 offset:2048
	ds_read_b128 v[214:217], v145 offset:3072
	ds_read_b128 v[218:221], v145 offset:4096
	ds_read_b128 v[222:225], v145 offset:5120
	ds_read_b128 v[234:237], v145 offset:6144
	ds_read_b128 v[238:241], v145 offset:7168
	global_load_lds_dwordx4 v[162:163], off
	v_lshl_add_u64 v[162:163], s[42:43], 0, v[140:141]
	s_add_i32 m0, s34, 0xe000
	s_nop 0
	global_load_lds_dwordx4 v[162:163], off
	s_waitcnt vmcnt(8)
	s_waitcnt lgkmcnt(0)
	s_barrier
	s_setprio 1
	v_mfma_f32_16x16x32_bf16 v[128:131], v[146:149], v[202:205], v[128:131]
	v_mfma_f32_16x16x32_bf16 v[124:127], v[154:157], v[202:205], v[124:127]
	v_mfma_f32_16x16x32_bf16 v[120:123], v[146:149], v[210:213], v[120:123]
	v_mfma_f32_16x16x32_bf16 v[116:119], v[154:157], v[210:213], v[116:119]
	v_mfma_f32_16x16x32_bf16 v[104:107], v[146:149], v[218:221], v[104:107]
	v_mfma_f32_16x16x32_bf16 v[100:103], v[154:157], v[218:221], v[100:103]
	v_mfma_f32_16x16x32_bf16 v[88:91], v[146:149], v[234:237], v[88:91]
	v_mfma_f32_16x16x32_bf16 v[84:87], v[154:157], v[234:237], v[84:87]
	v_mfma_f32_16x16x32_bf16 v[128:131], v[150:153], v[206:209], v[128:131]
	v_mfma_f32_16x16x32_bf16 v[124:127], v[158:161], v[206:209], v[124:127]
	v_mfma_f32_16x16x32_bf16 v[120:123], v[150:153], v[214:217], v[120:123]
	v_mfma_f32_16x16x32_bf16 v[116:119], v[158:161], v[214:217], v[116:119]
	v_mfma_f32_16x16x32_bf16 v[104:107], v[150:153], v[222:225], v[104:107]
	v_mfma_f32_16x16x32_bf16 v[100:103], v[158:161], v[222:225], v[100:103]
	v_mfma_f32_16x16x32_bf16 v[88:91], v[150:153], v[238:241], v[88:91]
	v_mfma_f32_16x16x32_bf16 v[84:87], v[158:161], v[238:241], v[84:87]
	v_mfma_f32_16x16x32_bf16 v[112:115], v[186:189], v[202:205], v[112:115]
	v_mfma_f32_16x16x32_bf16 v[108:111], v[194:197], v[202:205], v[108:111]
	v_mfma_f32_16x16x32_bf16 v[96:99], v[186:189], v[210:213], v[96:99]
	v_mfma_f32_16x16x32_bf16 v[92:95], v[194:197], v[210:213], v[92:95]
	v_mfma_f32_16x16x32_bf16 v[80:83], v[186:189], v[218:221], v[80:83]
	v_mfma_f32_16x16x32_bf16 v[76:79], v[194:197], v[218:221], v[76:79]
	v_mfma_f32_16x16x32_bf16 v[72:75], v[186:189], v[234:237], v[72:75]
	v_mfma_f32_16x16x32_bf16 v[68:71], v[194:197], v[234:237], v[68:71]
	v_mfma_f32_16x16x32_bf16 v[112:115], v[190:193], v[206:209], v[112:115]
	v_mfma_f32_16x16x32_bf16 v[108:111], v[198:201], v[206:209], v[108:111]
	v_mfma_f32_16x16x32_bf16 v[96:99], v[190:193], v[214:217], v[96:99]
	v_mfma_f32_16x16x32_bf16 v[92:95], v[198:201], v[214:217], v[92:95]
	v_mfma_f32_16x16x32_bf16 v[80:83], v[190:193], v[222:225], v[80:83]
	v_mfma_f32_16x16x32_bf16 v[76:79], v[198:201], v[222:225], v[76:79]
	v_mfma_f32_16x16x32_bf16 v[72:75], v[190:193], v[238:241], v[72:75]
	v_mfma_f32_16x16x32_bf16 v[68:71], v[198:201], v[238:241], v[68:71]
	s_setprio 0
	s_barrier
; #define PG8_STAGE(bufoff, gbase, voff) do { _Pragma("unroll") for (int _i = 0; _i < 2; ++_i) \
;         __builtin_amdgcn_global_load_lds((const unsigned*)((const char*)(gbase) + (voff)[_i]), (PG8_LAS unsigned*)(lds + (bufoff) + ldsw + _i * 8192), 16, 0, 0); } while (0)
; #define PG8_LDA(dst, b, h) do { _Pragma("unroll") for (int m = 0; m < 4; ++m) _Pragma("unroll") for (int k = 0; k < 2; ++k) dst[m][k] = *(const PG8_LAS bf16x8*)(lds + PG8_SA(b, h) + aoff + m * 2048 + k * 1024); } while (0)
; #define PG8_LDB(dst, b, h) do { _Pragma("unroll") for (int n = 0; n < 2; ++n) _Pragma("unroll") for (int k = 0; k < 2; ++k) dst[n][k] = *(const PG8_LAS bf16x8*)(lds + PG8_SB(b, h) + boff + n * 2048 + k * 1024); } while (0)
; #define PG8_WAIT_V(n) asm volatile("s_waitcnt vmcnt(" #n ")" ::: "memory")
; #define PG8_WAIT_L(n) asm volatile("s_waitcnt lgkmcnt(" #n ")" ::: "memory")
; #define PG8_BAR __builtin_amdgcn_s_barrier()
; #define PG8_SCHED __builtin_amdgcn_sched_barrier(0)
;     ...
;             PG8_LDA(At, 0, 1); PG8_STAGE(PG8_SB(0, 0), b2, voffB); PG8_STAGE(PG8_SB(0, 1), b2 + hstepB, voffB); PG8_STAGE(PG8_SA(0, 0), a2, voffA);
;             PG8_WAIT_V(8); PG8_WAIT_L(0); PG8_BAR; PG8_MMA(1, 0, At, B0); PG8_MMA(1, 1, At, B1); PG8_BAR; PG8_SCHED;
;             PG8_LDB(B0, 1, 0); PG8_LDB(B1, 1, 1); PG8_SCHED; PG8_LDA(At, 1, 0); PG8_STAGE(PG8_SA(0, 1), a2 + hstepA, voffA);
;             PG8_WAIT_V(8); PG8_WAIT_L(0); PG8_BAR; PG8_MMA(0, 0, At, B0); PG8_MMA(0, 1, At, B1); PG8_BAR; PG8_SCHED;
	s_add_i32 s42, s67, s15
	v_lshl_add_u64 v[162:163], s[50:51], 0, v[34:35]
	s_mov_b32 m0, s42
	ds_read_b128 v[202:205], v145 offset:16384
	ds_read_b128 v[206:209], v145 offset:17408
	ds_read_b128 v[210:213], v145 offset:18432
	ds_read_b128 v[214:217], v145 offset:19456
	ds_read_b128 v[218:221], v145 offset:20480
	ds_read_b128 v[222:225], v145 offset:21504
	ds_read_b128 v[234:237], v145 offset:22528
	ds_read_b128 v[238:241], v145 offset:23552
	global_load_lds_dwordx4 v[162:163], off
	s_add_i32 m0, s42, 0x2000
	s_add_u32 s42, s50, 0x160000
	v_lshl_add_u64 v[226:227], s[50:51], 0, v[136:137]
	s_addc_u32 s43, s51, 0
	s_add_i32 s67, s68, s15
	global_load_lds_dwordx4 v[226:227], off
	v_lshl_add_u64 v[242:243], s[42:43], 0, v[34:35]
	s_mov_b32 m0, s67
	v_lshl_add_u64 v[244:245], s[52:53], 0, v[134:135]
	global_load_lds_dwordx4 v[242:243], off
	v_lshl_add_u64 v[242:243], s[42:43], 0, v[136:137]
	s_add_i32 m0, s67, 0x2000
	s_nop 0
	global_load_lds_dwordx4 v[242:243], off
	v_lshl_add_u64 v[242:243], s[52:53], 0, v[132:133]
	s_mov_b32 m0, s34
	s_nop 0
	global_load_lds_dwordx4 v[242:243], off
	s_mov_b32 m0, s35
	s_nop 0
	global_load_lds_dwordx4 v[244:245], off
	s_waitcnt vmcnt(8)
	s_waitcnt lgkmcnt(0)
	s_barrier
	s_setprio 1
	v_mfma_f32_16x16x32_bf16 v[64:67], v[146:149], v[202:205], v[64:67]
	v_mfma_f32_16x16x32_bf16 v[60:63], v[154:157], v[202:205], v[60:63]
	v_mfma_f32_16x16x32_bf16 v[56:59], v[146:149], v[210:213], v[56:59]
	v_mfma_f32_16x16x32_bf16 v[52:55], v[154:157], v[210:213], v[52:55]
	v_mfma_f32_16x16x32_bf16 v[40:43], v[146:149], v[218:221], v[40:43]
	v_mfma_f32_16x16x32_bf16 v[36:39], v[154:157], v[218:221], v[36:39]
	v_mfma_f32_16x16x32_bf16 v[22:25], v[146:149], v[234:237], v[22:25]
	v_mfma_f32_16x16x32_bf16 v[18:21], v[154:157], v[234:237], v[18:21]
	v_mfma_f32_16x16x32_bf16 v[64:67], v[150:153], v[206:209], v[64:67]
	v_mfma_f32_16x16x32_bf16 v[60:63], v[158:161], v[206:209], v[60:63]
	v_mfma_f32_16x16x32_bf16 v[56:59], v[150:153], v[214:217], v[56:59]
	v_mfma_f32_16x16x32_bf16 v[52:55], v[158:161], v[214:217], v[52:55]
	v_mfma_f32_16x16x32_bf16 v[40:43], v[150:153], v[222:225], v[40:43]
	v_mfma_f32_16x16x32_bf16 v[36:39], v[158:161], v[222:225], v[36:39]
	v_mfma_f32_16x16x32_bf16 v[22:25], v[150:153], v[238:241], v[22:25]
	v_mfma_f32_16x16x32_bf16 v[18:21], v[158:161], v[238:241], v[18:21]
	v_mfma_f32_16x16x32_bf16 v[48:51], v[186:189], v[202:205], v[48:51]
	v_mfma_f32_16x16x32_bf16 v[44:47], v[194:197], v[202:205], v[44:47]
	v_mfma_f32_16x16x32_bf16 v[30:33], v[186:189], v[210:213], v[30:33]
	v_mfma_f32_16x16x32_bf16 v[26:29], v[194:197], v[210:213], v[26:29]
	v_mfma_f32_16x16x32_bf16 v[14:17], v[186:189], v[218:221], v[14:17]
	v_mfma_f32_16x16x32_bf16 v[10:13], v[194:197], v[218:221], v[10:13]
	v_mfma_f32_16x16x32_bf16 v[6:9], v[186:189], v[234:237], v[6:9]
	v_mfma_f32_16x16x32_bf16 v[2:5], v[194:197], v[234:237], v[2:5]
	v_mfma_f32_16x16x32_bf16 v[48:51], v[190:193], v[206:209], v[48:51]
	v_mfma_f32_16x16x32_bf16 v[44:47], v[198:201], v[206:209], v[44:47]
	v_mfma_f32_16x16x32_bf16 v[30:33], v[190:193], v[214:217], v[30:33]
	v_mfma_f32_16x16x32_bf16 v[26:29], v[198:201], v[214:217], v[26:29]
	v_mfma_f32_16x16x32_bf16 v[14:17], v[190:193], v[222:225], v[14:17]
	v_mfma_f32_16x16x32_bf16 v[10:13], v[198:201], v[222:225], v[10:13]
	v_mfma_f32_16x16x32_bf16 v[6:9], v[190:193], v[238:241], v[6:9]
	v_mfma_f32_16x16x32_bf16 v[2:5], v[198:201], v[238:241], v[2:5]
	s_setprio 0
	s_barrier
	s_add_i32 s67, 0, 0x18000
	s_add_i32 s68, 0, 0x1c000
	v_add_u32_e32 v158, s67, v143
	v_add_u32_e32 v198, s68, v143
	ds_read_b128 v[146:149], v158
	ds_read_b128 v[150:153], v158 offset:1024
	ds_read_b128 v[154:157], v158 offset:2048
	ds_read_b128 v[158:161], v158 offset:3072
	ds_read_b128 v[186:189], v198
	ds_read_b128 v[190:193], v198 offset:1024
	ds_read_b128 v[194:197], v198 offset:2048
	ds_read_b128 v[198:201], v198 offset:3072
	s_add_u32 s42, s52, 0x160000
	s_addc_u32 s43, s53, 0
	s_mov_b32 m0, s54
	v_lshl_add_u64 v[246:247], s[42:43], 0, v[132:133]
	ds_read_b128 v[202:205], v145 offset:32768
	ds_read_b128 v[206:209], v145 offset:33792
	ds_read_b128 v[210:213], v145 offset:34816
	ds_read_b128 v[214:217], v145 offset:35840
	ds_read_b128 v[218:221], v145 offset:36864
	ds_read_b128 v[222:225], v145 offset:37888
	ds_read_b128 v[234:237], v145 offset:38912
	ds_read_b128 v[238:241], v145 offset:39936
	global_load_lds_dwordx4 v[246:247], off
	v_lshl_add_u64 v[246:247], s[42:43], 0, v[134:135]
	s_mov_b32 m0, s55
	s_nop 0
	global_load_lds_dwordx4 v[246:247], off
	s_waitcnt vmcnt(8)
	s_waitcnt lgkmcnt(0)
	s_barrier
; #define PG8_STAGE(bufoff, gbase, voff) do { _Pragma("unroll") for (int _i = 0; _i < 2; ++_i) \
;         __builtin_amdgcn_global_load_lds((const unsigned*)((const char*)(gbase) + (voff)[_i]), (PG8_LAS unsigned*)(lds + (bufoff) + ldsw + _i * 8192), 16, 0, 0); } while (0)
; #define PG8_LDA(dst, b, h) do { _Pragma("unroll") for (int m = 0; m < 4; ++m) _Pragma("unroll") for (int k = 0; k < 2; ++k) dst[m][k] = *(const PG8_LAS bf16x8*)(lds + PG8_SA(b, h) + aoff + m * 2048 + k * 1024); } while (0)
; #define PG8_WAIT_V(n) asm volatile("s_waitcnt vmcnt(" #n ")" ::: "memory")
; #define PG8_WAIT_L(n) asm volatile("s_waitcnt lgkmcnt(" #n ")" ::: "memory")
; #define PG8_BAR __builtin_amdgcn_s_barrier()
; #define PG8_SCHED __builtin_amdgcn_sched_barrier(0)
;     ...
;             PG8_LDA(At, 1, 1); PG8_STAGE(PG8_SB(1, 0), b3, voffB); PG8_STAGE(PG8_SB(1, 1), b3 + hstepB, voffB); PG8_STAGE(PG8_SA(1, 0), a3, voffA);
;             PG8_WAIT_V(8); PG8_WAIT_L(0); PG8_BAR; PG8_MMA(1, 0, At, B0); PG8_MMA(1, 1, At, B1); PG8_BAR; PG8_SCHED;
	s_setprio 1
	v_mfma_f32_16x16x32_bf16 v[128:131], v[146:149], v[202:205], v[128:131]
	v_mfma_f32_16x16x32_bf16 v[124:127], v[154:157], v[202:205], v[124:127]
	v_mfma_f32_16x16x32_bf16 v[120:123], v[146:149], v[210:213], v[120:123]
	v_mfma_f32_16x16x32_bf16 v[116:119], v[154:157], v[210:213], v[116:119]
	v_mfma_f32_16x16x32_bf16 v[104:107], v[146:149], v[218:221], v[104:107]
	v_mfma_f32_16x16x32_bf16 v[100:103], v[154:157], v[218:221], v[100:103]
	v_mfma_f32_16x16x32_bf16 v[88:91], v[146:149], v[234:237], v[88:91]
	v_mfma_f32_16x16x32_bf16 v[84:87], v[154:157], v[234:237], v[84:87]
	v_mfma_f32_16x16x32_bf16 v[128:131], v[150:153], v[206:209], v[128:131]
	v_mfma_f32_16x16x32_bf16 v[124:127], v[158:161], v[206:209], v[124:127]
	v_mfma_f32_16x16x32_bf16 v[120:123], v[150:153], v[214:217], v[120:123]
	v_mfma_f32_16x16x32_bf16 v[116:119], v[158:161], v[214:217], v[116:119]
	v_mfma_f32_16x16x32_bf16 v[104:107], v[150:153], v[222:225], v[104:107]
	v_mfma_f32_16x16x32_bf16 v[100:103], v[158:161], v[222:225], v[100:103]
	v_mfma_f32_16x16x32_bf16 v[88:91], v[150:153], v[238:241], v[88:91]
	v_mfma_f32_16x16x32_bf16 v[84:87], v[158:161], v[238:241], v[84:87]
	v_mfma_f32_16x16x32_bf16 v[112:115], v[186:189], v[202:205], v[112:115]
	v_mfma_f32_16x16x32_bf16 v[108:111], v[194:197], v[202:205], v[108:111]
	v_mfma_f32_16x16x32_bf16 v[96:99], v[186:189], v[210:213], v[96:99]
	v_mfma_f32_16x16x32_bf16 v[92:95], v[194:197], v[210:213], v[92:95]
	v_mfma_f32_16x16x32_bf16 v[80:83], v[186:189], v[218:221], v[80:83]
	v_mfma_f32_16x16x32_bf16 v[76:79], v[194:197], v[218:221], v[76:79]
	v_mfma_f32_16x16x32_bf16 v[72:75], v[186:189], v[234:237], v[72:75]
	v_mfma_f32_16x16x32_bf16 v[68:71], v[194:197], v[234:237], v[68:71]
	v_mfma_f32_16x16x32_bf16 v[112:115], v[190:193], v[206:209], v[112:115]
	v_mfma_f32_16x16x32_bf16 v[108:111], v[198:201], v[206:209], v[108:111]
	v_mfma_f32_16x16x32_bf16 v[96:99], v[190:193], v[214:217], v[96:99]
	v_mfma_f32_16x16x32_bf16 v[92:95], v[198:201], v[214:217], v[92:95]
	v_mfma_f32_16x16x32_bf16 v[80:83], v[190:193], v[222:225], v[80:83]
	v_mfma_f32_16x16x32_bf16 v[76:79], v[198:201], v[222:225], v[76:79]
	v_mfma_f32_16x16x32_bf16 v[72:75], v[190:193], v[238:241], v[72:75]
	v_mfma_f32_16x16x32_bf16 v[68:71], v[198:201], v[238:241], v[68:71]
	s_setprio 0
	s_barrier
	s_add_i32 s42, s67, s15
	v_lshl_add_u64 v[162:163], v[162:163], 0, s[22:23]
	s_mov_b32 m0, s42
	ds_read_b128 v[202:205], v145 offset:49152
	ds_read_b128 v[206:209], v145 offset:50176
	ds_read_b128 v[210:213], v145 offset:51200
	ds_read_b128 v[214:217], v145 offset:52224
	ds_read_b128 v[218:221], v145 offset:53248
	ds_read_b128 v[222:225], v145 offset:54272
	ds_read_b128 v[234:237], v145 offset:55296
	ds_read_b128 v[238:241], v145 offset:56320
	global_load_lds_dwordx4 v[162:163], off
	s_add_i32 m0, s42, 0x2000
	s_add_u32 s42, s50, 0x160080
	v_lshl_add_u64 v[162:163], v[226:227], 0, s[22:23]
	s_addc_u32 s43, s51, 0
	s_add_i32 s50, s68, s15
	global_load_lds_dwordx4 v[162:163], off
	v_lshl_add_u64 v[162:163], s[42:43], 0, v[34:35]
	s_mov_b32 m0, s50
	s_nop 0
	global_load_lds_dwordx4 v[162:163], off
	v_lshl_add_u64 v[162:163], s[42:43], 0, v[136:137]
	s_add_i32 m0, s50, 0x2000
	s_nop 0
	global_load_lds_dwordx4 v[162:163], off
	v_lshl_add_u64 v[162:163], v[242:243], 0, s[22:23]
	s_mov_b32 m0, s56
	s_nop 0
	global_load_lds_dwordx4 v[162:163], off
	v_lshl_add_u64 v[162:163], v[244:245], 0, s[22:23]
	s_mov_b32 m0, s57
	s_nop 0
	global_load_lds_dwordx4 v[162:163], off
	s_waitcnt vmcnt(8)
	s_waitcnt lgkmcnt(0)
	s_barrier
	s_setprio 1
	v_mfma_f32_16x16x32_bf16 v[64:67], v[146:149], v[202:205], v[64:67]
	v_mfma_f32_16x16x32_bf16 v[60:63], v[154:157], v[202:205], v[60:63]
	v_mfma_f32_16x16x32_bf16 v[56:59], v[146:149], v[210:213], v[56:59]
	v_mfma_f32_16x16x32_bf16 v[52:55], v[154:157], v[210:213], v[52:55]
	v_mfma_f32_16x16x32_bf16 v[40:43], v[146:149], v[218:221], v[40:43]
	v_mfma_f32_16x16x32_bf16 v[36:39], v[154:157], v[218:221], v[36:39]
	v_mfma_f32_16x16x32_bf16 v[22:25], v[146:149], v[234:237], v[22:25]
	v_mfma_f32_16x16x32_bf16 v[18:21], v[154:157], v[234:237], v[18:21]
	v_mfma_f32_16x16x32_bf16 v[64:67], v[150:153], v[206:209], v[64:67]
	v_mfma_f32_16x16x32_bf16 v[60:63], v[158:161], v[206:209], v[60:63]
	v_mfma_f32_16x16x32_bf16 v[56:59], v[150:153], v[214:217], v[56:59]
	v_mfma_f32_16x16x32_bf16 v[52:55], v[158:161], v[214:217], v[52:55]
	v_mfma_f32_16x16x32_bf16 v[40:43], v[150:153], v[222:225], v[40:43]
	v_mfma_f32_16x16x32_bf16 v[36:39], v[158:161], v[222:225], v[36:39]
	v_mfma_f32_16x16x32_bf16 v[22:25], v[150:153], v[238:241], v[22:25]
	v_mfma_f32_16x16x32_bf16 v[18:21], v[158:161], v[238:241], v[18:21]
	v_mfma_f32_16x16x32_bf16 v[48:51], v[186:189], v[202:205], v[48:51]
	v_mfma_f32_16x16x32_bf16 v[44:47], v[194:197], v[202:205], v[44:47]
	v_mfma_f32_16x16x32_bf16 v[30:33], v[186:189], v[210:213], v[30:33]
	v_mfma_f32_16x16x32_bf16 v[26:29], v[194:197], v[210:213], v[26:29]
	v_mfma_f32_16x16x32_bf16 v[14:17], v[186:189], v[218:221], v[14:17]
	v_mfma_f32_16x16x32_bf16 v[10:13], v[194:197], v[218:221], v[10:13]
	v_mfma_f32_16x16x32_bf16 v[6:9], v[186:189], v[234:237], v[6:9]
	v_mfma_f32_16x16x32_bf16 v[2:5], v[194:197], v[234:237], v[2:5]
	v_mfma_f32_16x16x32_bf16 v[48:51], v[190:193], v[206:209], v[48:51]
	v_mfma_f32_16x16x32_bf16 v[44:47], v[198:201], v[206:209], v[44:47]
	v_mfma_f32_16x16x32_bf16 v[30:33], v[190:193], v[214:217], v[30:33]
	v_mfma_f32_16x16x32_bf16 v[26:29], v[198:201], v[214:217], v[26:29]
	v_mfma_f32_16x16x32_bf16 v[14:17], v[190:193], v[222:225], v[14:17]
	v_mfma_f32_16x16x32_bf16 v[10:13], v[198:201], v[222:225], v[10:13]
	v_mfma_f32_16x16x32_bf16 v[6:9], v[190:193], v[238:241], v[6:9]
	v_mfma_f32_16x16x32_bf16 v[2:5], v[198:201], v[238:241], v[2:5]
	s_setprio 0
	s_barrier
	s_add_i32 s66, s66, 2
	s_add_u32 s64, s64, 0x100
	s_addc_u32 s65, s65, 0
	s_cmpk_gt_u32 s66, 0x55
	s_mov_b64 s[42:43], s[44:45]
	s_cbranch_scc0 .LBB0_694
	s_and_b64 vcc, exec, s[30:31]
	s_cbranch_vccz .LBB0_697
	s_barrier

; #define PG8_STAGE(bufoff, gbase, voff) do { _Pragma("unroll") for (int _i = 0; _i < 2; ++_i) \
;         __builtin_amdgcn_global_load_lds((const unsigned*)((const char*)(gbase) + (voff)[_i]), (PG8_LAS unsigned*)(lds + (bufoff) + ldsw + _i * 8192), 16, 0, 0); } while (0)
; #define PG8_LDA(dst, b, h) do { _Pragma("unroll") for (int m = 0; m < 4; ++m) _Pragma("unroll") for (int k = 0; k < 2; ++k) dst[m][k] = *(const PG8_LAS bf16x8*)(lds + PG8_SA(b, h) + aoff + m * 2048 + k * 1024); } while (0)
; #define PG8_LDB(dst, b, h) do { _Pragma("unroll") for (int n = 0; n < 2; ++n) _Pragma("unroll") for (int k = 0; k < 2; ++k) dst[n][k] = *(const PG8_LAS bf16x8*)(lds + PG8_SB(b, h) + boff + n * 2048 + k * 1024); } while (0)
; #define PG8_WAIT_V(n) asm volatile("s_waitcnt vmcnt(" #n ")" ::: "memory")
; #define PG8_WAIT_L(n) asm volatile("s_waitcnt lgkmcnt(" #n ")" ::: "memory")
; #define PG8_BAR __builtin_amdgcn_s_barrier()
; #define PG8_SCHED __builtin_amdgcn_sched_barrier(0)
;     ...
;             PG8_LDB(B0, 0, 0); PG8_LDB(B1, 0, 1); PG8_SCHED; PG8_LDA(At, 0, 0); PG8_STAGE(PG8_SA(1, 1), a1 + hstepA, voffA);
;             PG8_WAIT_V(8); PG8_WAIT_L(0); PG8_BAR; PG8_MMA(0, 0, At, B0); PG8_MMA(0, 1, At, B1); PG8_BAR; PG8_SCHED;
;             PG8_LDA(At, 0, 1); PG8_STAGE(PG8_SB(0, 0), b2, voffB); PG8_STAGE(PG8_SB(0, 1), b2 + hstepB, voffB); PG8_STAGE(PG8_SA(0, 0), a2, voffA);
;             PG8_WAIT_V(8); PG8_WAIT_L(0); PG8_BAR; PG8_MMA(1, 0, At, B0); PG8_MMA(1, 1, At, B1); PG8_BAR; PG8_SCHED;
.LBB0_726:
	s_add_u32 s40, s42, 0x100
	s_addc_u32 s41, s43, 0
	s_add_i32 s64, 0, 0x10000
	s_cmp_eq_u32 s63, 40
	s_cselect_b32 s51, s31, s41
	s_cselect_b32 s50, s30, s40
	s_cselect_b32 s45, s37, s62
	s_cselect_b32 s44, s36, s61
	s_add_i32 s65, 0, 0x14000
	v_add_u32_e32 v2, s64, v209
	v_add_u32_e32 v6, s65, v209
	ds_read_b128 v[26:29], v2
	ds_read_b128 v[30:33], v2 offset:1024
	ds_read_b128 v[18:21], v2 offset:2048
	ds_read_b128 v[22:25], v2 offset:3072
	ds_read_b128 v[10:13], v6
	ds_read_b128 v[14:17], v6 offset:1024
	ds_read_b128 v[2:5], v6 offset:2048
	ds_read_b128 v[6:9], v6 offset:3072
	v_lshl_add_u64 v[242:243], s[42:43], 0, v[196:197]
	s_add_i32 m0, s21, 0xc000
	ds_read_b128 v[200:203], v211
	ds_read_b128 v[204:207], v211 offset:1024
	ds_read_b128 v[212:215], v211 offset:2048
	ds_read_b128 v[216:219], v211 offset:3072
	ds_read_b128 v[220:223], v211 offset:4096
	ds_read_b128 v[224:227], v211 offset:5120
	ds_read_b128 v[234:237], v211 offset:6144
	ds_read_b128 v[238:241], v211 offset:7168
	global_load_lds_dwordx4 v[242:243], off
	v_lshl_add_u64 v[242:243], s[42:43], 0, v[198:199]
	s_add_i32 m0, s21, 0xe000
	s_nop 0
	global_load_lds_dwordx4 v[242:243], off
	s_waitcnt vmcnt(8)
	s_waitcnt lgkmcnt(0)
	s_barrier
	s_setprio 1
	v_mfma_f32_16x16x128_f8f6f4 v[160:163], v[26:33], v[200:207], v[160:163]
	v_mfma_f32_16x16x128_f8f6f4 v[156:159], v[18:25], v[200:207], v[156:159]
	v_mfma_f32_16x16x128_f8f6f4 v[152:155], v[26:33], v[212:219], v[152:155]
	v_mfma_f32_16x16x128_f8f6f4 v[144:147], v[18:25], v[212:219], v[144:147]
	v_mfma_f32_16x16x128_f8f6f4 v[136:139], v[26:33], v[220:227], v[136:139]
	v_mfma_f32_16x16x128_f8f6f4 v[128:131], v[18:25], v[220:227], v[128:131]
	v_mfma_f32_16x16x128_f8f6f4 v[120:123], v[26:33], v[234:241], v[120:123]
	v_mfma_f32_16x16x128_f8f6f4 v[112:115], v[18:25], v[234:241], v[112:115]
	v_mfma_f32_16x16x128_f8f6f4 v[148:151], v[10:17], v[200:207], v[148:151]
	v_mfma_f32_16x16x128_f8f6f4 v[140:143], v[2:9], v[200:207], v[140:143]
	v_mfma_f32_16x16x128_f8f6f4 v[132:135], v[10:17], v[212:219], v[132:135]
	v_mfma_f32_16x16x128_f8f6f4 v[124:127], v[2:9], v[212:219], v[124:127]
	v_mfma_f32_16x16x128_f8f6f4 v[116:119], v[10:17], v[220:227], v[116:119]
	v_mfma_f32_16x16x128_f8f6f4 v[108:111], v[2:9], v[220:227], v[108:111]
	v_mfma_f32_16x16x128_f8f6f4 v[104:107], v[10:17], v[234:241], v[104:107]
	v_mfma_f32_16x16x128_f8f6f4 v[100:103], v[2:9], v[234:241], v[100:103]
	s_setprio 0
	s_barrier
	s_add_i32 s42, s64, s15
	v_lshl_add_u64 v[200:201], s[44:45], 0, v[34:35]
	s_mov_b32 m0, s42
	ds_read_b128 v[212:215], v211 offset:16384
	ds_read_b128 v[216:219], v211 offset:17408
	ds_read_b128 v[220:223], v211 offset:18432
	ds_read_b128 v[224:227], v211 offset:19456
	ds_read_b128 v[234:237], v211 offset:20480
	ds_read_b128 v[238:241], v211 offset:21504
	ds_read_b128 v[242:245], v211 offset:22528
	ds_read_b128 v[246:249], v211 offset:23552
	global_load_lds_dwordx4 v[200:201], off
	s_add_i32 m0, s42, 0x2000
	s_add_u32 s42, s44, 0xb0000
	v_lshl_add_u64 v[202:203], s[44:45], 0, v[190:191]
	s_addc_u32 s43, s45, 0
	s_add_i32 s64, s65, s15
	global_load_lds_dwordx4 v[202:203], off
	v_lshl_add_u64 v[204:205], s[42:43], 0, v[34:35]
	s_mov_b32 m0, s64
	v_lshl_add_u64 v[206:207], s[50:51], 0, v[188:189]
	global_load_lds_dwordx4 v[204:205], off
	v_lshl_add_u64 v[204:205], s[42:43], 0, v[190:191]
	s_add_i32 m0, s64, 0x2000
	s_nop 0
	global_load_lds_dwordx4 v[204:205], off
	v_lshl_add_u64 v[204:205], s[50:51], 0, v[186:187]
	s_mov_b32 m0, s21
	s_nop 0
	global_load_lds_dwordx4 v[204:205], off
	s_mov_b32 m0, s34
	s_nop 0
	global_load_lds_dwordx4 v[206:207], off
	s_waitcnt vmcnt(8)
	s_waitcnt lgkmcnt(0)
	s_barrier
	s_setprio 1
	v_mfma_f32_16x16x128_f8f6f4 v[96:99], v[26:33], v[212:219], v[96:99]
	v_mfma_f32_16x16x128_f8f6f4 v[92:95], v[18:25], v[212:219], v[92:95]
	v_mfma_f32_16x16x128_f8f6f4 v[88:91], v[26:33], v[220:227], v[88:91]
	v_mfma_f32_16x16x128_f8f6f4 v[80:83], v[18:25], v[220:227], v[80:83]
	v_mfma_f32_16x16x128_f8f6f4 v[72:75], v[26:33], v[234:241], v[72:75]
	v_mfma_f32_16x16x128_f8f6f4 v[64:67], v[18:25], v[234:241], v[64:67]
	v_mfma_f32_16x16x128_f8f6f4 v[56:59], v[26:33], v[242:249], v[56:59]
	v_mfma_f32_16x16x128_f8f6f4 v[48:51], v[18:25], v[242:249], v[48:51]
	v_mfma_f32_16x16x128_f8f6f4 v[84:87], v[10:17], v[212:219], v[84:87]
	v_mfma_f32_16x16x128_f8f6f4 v[76:79], v[2:9], v[212:219], v[76:79]
	v_mfma_f32_16x16x128_f8f6f4 v[68:71], v[10:17], v[220:227], v[68:71]
	v_mfma_f32_16x16x128_f8f6f4 v[60:63], v[2:9], v[220:227], v[60:63]
	v_mfma_f32_16x16x128_f8f6f4 v[52:55], v[10:17], v[234:241], v[52:55]
	v_mfma_f32_16x16x128_f8f6f4 v[44:47], v[2:9], v[234:241], v[44:47]
	v_mfma_f32_16x16x128_f8f6f4 v[40:43], v[10:17], v[242:249], v[40:43]
	v_mfma_f32_16x16x128_f8f6f4 v[36:39], v[2:9], v[242:249], v[36:39]
	s_setprio 0
	s_barrier
; #define PG8_STAGE(bufoff, gbase, voff) do { _Pragma("unroll") for (int _i = 0; _i < 2; ++_i) \
;         __builtin_amdgcn_global_load_lds((const unsigned*)((const char*)(gbase) + (voff)[_i]), (PG8_LAS unsigned*)(lds + (bufoff) + ldsw + _i * 8192), 16, 0, 0); } while (0)
; #define PG8_LDA(dst, b, h) do { _Pragma("unroll") for (int m = 0; m < 4; ++m) _Pragma("unroll") for (int k = 0; k < 2; ++k) dst[m][k] = *(const PG8_LAS bf16x8*)(lds + PG8_SA(b, h) + aoff + m * 2048 + k * 1024); } while (0)
; #define PG8_LDB(dst, b, h) do { _Pragma("unroll") for (int n = 0; n < 2; ++n) _Pragma("unroll") for (int k = 0; k < 2; ++k) dst[n][k] = *(const PG8_LAS bf16x8*)(lds + PG8_SB(b, h) + boff + n * 2048 + k * 1024); } while (0)
; #define PG8_WAIT_V(n) asm volatile("s_waitcnt vmcnt(" #n ")" ::: "memory")
; #define PG8_WAIT_L(n) asm volatile("s_waitcnt lgkmcnt(" #n ")" ::: "memory")
; #define PG8_BAR __builtin_amdgcn_s_barrier()
; #define PG8_SCHED __builtin_amdgcn_sched_barrier(0)
;     ...
;             PG8_LDB(B0, 1, 0); PG8_LDB(B1, 1, 1); PG8_SCHED; PG8_LDA(At, 1, 0); PG8_STAGE(PG8_SA(0, 1), a2 + hstepA, voffA);
;             PG8_WAIT_V(8); PG8_WAIT_L(0); PG8_BAR; PG8_MMA(0, 0, At, B0); PG8_MMA(0, 1, At, B1); PG8_BAR; PG8_SCHED;
;             PG8_LDA(At, 1, 1); PG8_STAGE(PG8_SB(1, 0), b3, voffB); PG8_STAGE(PG8_SB(1, 1), b3 + hstepB, voffB); PG8_STAGE(PG8_SA(1, 0), a3, voffA);
;             PG8_WAIT_V(8); PG8_WAIT_L(0); PG8_BAR; PG8_MMA(1, 0, At, B0); PG8_MMA(1, 1, At, B1); PG8_BAR; PG8_SCHED;
	s_add_i32 s64, 0, 0x18000
	s_add_i32 s65, 0, 0x1c000
	v_add_u32_e32 v14, s64, v209
	v_add_u32_e32 v30, s65, v209
	ds_read_b128 v[2:5], v14
	ds_read_b128 v[6:9], v14 offset:1024
	ds_read_b128 v[10:13], v14 offset:2048
	ds_read_b128 v[14:17], v14 offset:3072
	ds_read_b128 v[18:21], v30
	ds_read_b128 v[22:25], v30 offset:1024
	ds_read_b128 v[26:29], v30 offset:2048
	ds_read_b128 v[30:33], v30 offset:3072
	s_add_u32 s42, s50, 0xb0000
	s_addc_u32 s43, s51, 0
	s_mov_b32 m0, s35
	v_lshl_add_u64 v[250:251], s[42:43], 0, v[186:187]
	ds_read_b128 v[212:215], v211 offset:32768
	ds_read_b128 v[216:219], v211 offset:33792
	ds_read_b128 v[220:223], v211 offset:34816
	ds_read_b128 v[224:227], v211 offset:35840
	ds_read_b128 v[234:237], v211 offset:36864
	ds_read_b128 v[238:241], v211 offset:37888
	ds_read_b128 v[242:245], v211 offset:38912
	ds_read_b128 v[246:249], v211 offset:39936
	global_load_lds_dwordx4 v[250:251], off
	v_lshl_add_u64 v[250:251], s[42:43], 0, v[188:189]
	s_mov_b32 m0, s52
	s_nop 0
	global_load_lds_dwordx4 v[250:251], off
	s_waitcnt vmcnt(8)
	s_waitcnt lgkmcnt(0)
	s_barrier
	s_setprio 1
	v_mfma_f32_16x16x128_f8f6f4 v[160:163], v[2:9], v[212:219], v[160:163]
	v_mfma_f32_16x16x128_f8f6f4 v[156:159], v[10:17], v[212:219], v[156:159]
	v_mfma_f32_16x16x128_f8f6f4 v[152:155], v[2:9], v[220:227], v[152:155]
	v_mfma_f32_16x16x128_f8f6f4 v[144:147], v[10:17], v[220:227], v[144:147]
	v_mfma_f32_16x16x128_f8f6f4 v[136:139], v[2:9], v[234:241], v[136:139]
	v_mfma_f32_16x16x128_f8f6f4 v[128:131], v[10:17], v[234:241], v[128:131]
	v_mfma_f32_16x16x128_f8f6f4 v[120:123], v[2:9], v[242:249], v[120:123]
	v_mfma_f32_16x16x128_f8f6f4 v[112:115], v[10:17], v[242:249], v[112:115]
	v_mfma_f32_16x16x128_f8f6f4 v[148:151], v[18:25], v[212:219], v[148:151]
	v_mfma_f32_16x16x128_f8f6f4 v[140:143], v[26:33], v[212:219], v[140:143]
	v_mfma_f32_16x16x128_f8f6f4 v[132:135], v[18:25], v[220:227], v[132:135]
	v_mfma_f32_16x16x128_f8f6f4 v[124:127], v[26:33], v[220:227], v[124:127]
	v_mfma_f32_16x16x128_f8f6f4 v[116:119], v[18:25], v[234:241], v[116:119]
	v_mfma_f32_16x16x128_f8f6f4 v[108:111], v[26:33], v[234:241], v[108:111]
	v_mfma_f32_16x16x128_f8f6f4 v[104:107], v[18:25], v[242:249], v[104:107]
	v_mfma_f32_16x16x128_f8f6f4 v[100:103], v[26:33], v[242:249], v[100:103]
	s_setprio 0
	s_barrier
	s_add_i32 s42, s64, s15
	v_lshl_add_u64 v[200:201], v[200:201], 0, s[22:23]
	s_mov_b32 m0, s42
	ds_read_b128 v[212:215], v211 offset:49152
	ds_read_b128 v[216:219], v211 offset:50176
	ds_read_b128 v[220:223], v211 offset:51200
	ds_read_b128 v[224:227], v211 offset:52224
	ds_read_b128 v[234:237], v211 offset:53248
	ds_read_b128 v[238:241], v211 offset:54272
	ds_read_b128 v[242:245], v211 offset:55296
	ds_read_b128 v[246:249], v211 offset:56320
	global_load_lds_dwordx4 v[200:201], off
	s_add_i32 m0, s42, 0x2000
	s_add_u32 s42, s44, 0xb0080
	v_lshl_add_u64 v[200:201], v[202:203], 0, s[22:23]
	s_addc_u32 s43, s45, 0
	s_add_i32 s44, s65, s15
	global_load_lds_dwordx4 v[200:201], off
	v_lshl_add_u64 v[200:201], s[42:43], 0, v[34:35]
	s_mov_b32 m0, s44
	s_nop 0
	global_load_lds_dwordx4 v[200:201], off
	v_lshl_add_u64 v[200:201], s[42:43], 0, v[190:191]
	s_add_i32 m0, s44, 0x2000
	s_nop 0
	global_load_lds_dwordx4 v[200:201], off
	v_lshl_add_u64 v[200:201], v[204:205], 0, s[22:23]
	s_mov_b32 m0, s53
	s_nop 0
	global_load_lds_dwordx4 v[200:201], off
	v_lshl_add_u64 v[200:201], v[206:207], 0, s[22:23]
	s_mov_b32 m0, s54
	s_nop 0
	global_load_lds_dwordx4 v[200:201], off
	s_waitcnt vmcnt(8)
	s_waitcnt lgkmcnt(0)
	s_barrier
	s_setprio 1
	v_mfma_f32_16x16x128_f8f6f4 v[96:99], v[2:9], v[212:219], v[96:99]
	v_mfma_f32_16x16x128_f8f6f4 v[92:95], v[10:17], v[212:219], v[92:95]
	v_mfma_f32_16x16x128_f8f6f4 v[88:91], v[2:9], v[220:227], v[88:91]
	v_mfma_f32_16x16x128_f8f6f4 v[80:83], v[10:17], v[220:227], v[80:83]
	v_mfma_f32_16x16x128_f8f6f4 v[72:75], v[2:9], v[234:241], v[72:75]
	v_mfma_f32_16x16x128_f8f6f4 v[64:67], v[10:17], v[234:241], v[64:67]
	v_mfma_f32_16x16x128_f8f6f4 v[56:59], v[2:9], v[242:249], v[56:59]
	v_mfma_f32_16x16x128_f8f6f4 v[48:51], v[10:17], v[242:249], v[48:51]
	v_mfma_f32_16x16x128_f8f6f4 v[84:87], v[18:25], v[212:219], v[84:87]
	v_mfma_f32_16x16x128_f8f6f4 v[76:79], v[26:33], v[212:219], v[76:79]
	v_mfma_f32_16x16x128_f8f6f4 v[68:71], v[18:25], v[220:227], v[68:71]
	v_mfma_f32_16x16x128_f8f6f4 v[60:63], v[26:33], v[220:227], v[60:63]
	v_mfma_f32_16x16x128_f8f6f4 v[52:55], v[18:25], v[234:241], v[52:55]
	v_mfma_f32_16x16x128_f8f6f4 v[44:47], v[26:33], v[234:241], v[44:47]
	v_mfma_f32_16x16x128_f8f6f4 v[40:43], v[18:25], v[242:249], v[40:43]
	v_mfma_f32_16x16x128_f8f6f4 v[36:39], v[26:33], v[242:249], v[36:39]
	s_setprio 0
	s_barrier
	s_add_i32 s63, s63, 2
	s_add_u32 s61, s61, 0x100
	s_addc_u32 s62, s62, 0
	s_cmp_gt_u32 s63, 41
	s_mov_b64 s[42:43], s[40:41]
	s_cbranch_scc0 .LBB0_726
	s_and_b64 vcc, exec, s[28:29]
	s_cbranch_vccz .LBB0_729
	s_barrier

; #define PG8_STAGE(bufoff, gbase, voff) do { _Pragma("unroll") for (int _i = 0; _i < 2; ++_i) \
;         __builtin_amdgcn_global_load_lds((const unsigned*)((const char*)(gbase) + (voff)[_i]), (PG8_LAS unsigned*)(lds + (bufoff) + ldsw + _i * 8192), 16, 0, 0); } while (0)
; #define PG8_LDA(dst, b, h) do { _Pragma("unroll") for (int m = 0; m < 4; ++m) _Pragma("unroll") for (int k = 0; k < 2; ++k) dst[m][k] = *(const PG8_LAS bf16x8*)(lds + PG8_SA(b, h) + aoff + m * 2048 + k * 1024); } while (0)
; #define PG8_LDB(dst, b, h) do { _Pragma("unroll") for (int n = 0; n < 2; ++n) _Pragma("unroll") for (int k = 0; k < 2; ++k) dst[n][k] = *(const PG8_LAS bf16x8*)(lds + PG8_SB(b, h) + boff + n * 2048 + k * 1024); } while (0)
; #define PG8_WAIT_V(n) asm volatile("s_waitcnt vmcnt(" #n ")" ::: "memory")
; #define PG8_WAIT_L(n) asm volatile("s_waitcnt lgkmcnt(" #n ")" ::: "memory")
; #define PG8_BAR __builtin_amdgcn_s_barrier()
; #define PG8_SCHED __builtin_amdgcn_sched_barrier(0)
;     ...
;         for (int t = 0; t < nt; t += 2) {
;             const bool last = (t == nt - 2);
;             const char* a1 = cA + (size_t)(t + 1) * kstep;
;             const char* a2 = last ? nA : cA + (size_t)(t + 2) * kstep; const char* b2 = last ? nB : cB + (size_t)(t + 2) * kstep;
;             const char* a3 = a2 + kstep; const char* b3 = b2 + kstep;
;             if (last && has_next) S.a_ready(nxt);
;             if constexpr (SP2) {
;             PG8_LDB(B0, 0, 0); PG8_LDB(B1, 0, 1); PG8_SCHED; PG8_LDA(At, 0, 0); PG8_STAGE(PG8_SA(1, 1), a1 + hstepA, voffA);
;             PG8_WAIT_V(8); PG8_WAIT_L(0); PG8_BAR; PG8_MMA(0, 0, At, B0); PG8_MMA(0, 1, At, B1); PG8_BAR; PG8_SCHED;
;     ...
;         if (!Epi::SEGMENTED || cur.seg == 2)
; #pragma unroll
;         for (int a = 0; a < 2; ++a)
; #pragma unroll
;             for (int b = 0; b < 2; ++b)
; #pragma unroll
;                 for (int m = 0; m < 4; ++m)
; #pragma unroll
;                     for (int n = 0; n < 2; ++n) acc[a][b][m][n] = (f32x4){0.f, 0.f, 0.f, 0.f};
;         cur = nxt; cA = nA; cB = nB; ++ui;
.LBB0_922:
	s_ashr_i32 s47, s46, 31
	s_lshl_b64 s[34:35], s[46:47], 20
	s_add_u32 s48, s60, s34
	s_addc_u32 s49, s61, s35
	s_and_b64 s[34:35], s[38:39], exec
	s_cselect_b32 s6, s49, s53
	s_cselect_b32 s15, s48, s52
	s_ashr_i32 s37, s36, 31
	s_lshl_b64 s[34:35], s[36:37], 20
	s_add_u32 s50, s62, s34
	s_addc_u32 s51, s63, s35
	s_and_b64 s[34:35], s[38:39], exec
	s_cselect_b32 s34, s51, s57
	s_cselect_b32 s35, s50, s56
	s_add_u32 s52, s52, 0x80080
	s_addc_u32 s53, s53, 0
	s_add_u32 s37, s56, 0x100
	v_mov_b32_e32 v2, 0
	s_addc_u32 s41, s57, 0
	s_mov_b32 s47, -2
	v_mov_b32_e32 v3, v2
	v_mov_b64_e32 v[4:5], 0
	v_mov_b64_e32 v[6:7], 0
	v_mov_b64_e32 v[8:9], 0
	v_mov_b64_e32 v[10:11], 0
	v_mov_b64_e32 v[12:13], 0
	v_mov_b64_e32 v[14:15], 0
	v_mov_b64_e32 v[16:17], 0
	v_mov_b64_e32 v[18:19], 0
	v_mov_b64_e32 v[20:21], 0
	v_mov_b64_e32 v[22:23], 0
	v_mov_b64_e32 v[24:25], 0
	v_mov_b64_e32 v[26:27], 0
	v_mov_b64_e32 v[28:29], 0
	v_mov_b64_e32 v[30:31], 0
	v_mov_b64_e32 v[32:33], 0
	v_mov_b64_e32 v[36:37], 0
	v_mov_b64_e32 v[38:39], 0
	v_mov_b64_e32 v[40:41], 0
	v_mov_b64_e32 v[42:43], 0
	v_mov_b64_e32 v[44:45], 0
	v_mov_b64_e32 v[46:47], 0
	v_mov_b64_e32 v[48:49], 0
	v_mov_b64_e32 v[50:51], 0
	v_mov_b64_e32 v[52:53], 0
	v_mov_b64_e32 v[54:55], 0
	v_mov_b64_e32 v[56:57], 0
	v_mov_b64_e32 v[58:59], 0
	v_mov_b64_e32 v[60:61], 0
	v_mov_b64_e32 v[62:63], 0
	v_mov_b64_e32 v[64:65], 0
	v_mov_b64_e32 v[66:67], 0
	v_mov_b64_e32 v[68:69], 0
	v_mov_b64_e32 v[70:71], 0
	v_mov_b64_e32 v[72:73], 0
	v_mov_b64_e32 v[74:75], 0
	v_mov_b64_e32 v[76:77], 0
	v_mov_b64_e32 v[78:79], 0
	v_mov_b64_e32 v[80:81], 0
	v_mov_b64_e32 v[82:83], 0
	v_mov_b64_e32 v[84:85], 0
	v_mov_b64_e32 v[86:87], 0
	v_mov_b64_e32 v[88:89], 0
	v_mov_b64_e32 v[90:91], 0
	v_mov_b64_e32 v[92:93], 0
	v_mov_b64_e32 v[94:95], 0
	v_mov_b64_e32 v[96:97], 0
	v_mov_b64_e32 v[98:99], 0
	v_mov_b64_e32 v[100:101], 0
	v_mov_b64_e32 v[102:103], 0
	v_mov_b64_e32 v[104:105], 0
	v_mov_b64_e32 v[106:107], 0
	v_mov_b64_e32 v[108:109], 0
	v_mov_b64_e32 v[110:111], 0
	v_mov_b64_e32 v[112:113], 0
	v_mov_b64_e32 v[114:115], 0
	v_mov_b64_e32 v[116:117], 0
	v_mov_b64_e32 v[118:119], 0
	v_mov_b64_e32 v[120:121], 0
	v_mov_b64_e32 v[122:123], 0
	v_mov_b64_e32 v[124:125], 0
	v_mov_b64_e32 v[126:127], 0
	v_mov_b64_e32 v[128:129], 0
	v_mov_b64_e32 v[130:131], 0
.LBB0_923:
	s_add_u32 s56, s52, 0xfff80080
	s_addc_u32 s57, s53, -1
	s_add_i32 s68, 0, 0x10000
	s_cmp_eq_u32 s47, 28
	s_cselect_b32 s59, s6, s57
	s_cselect_b32 s58, s15, s56
	s_cselect_b32 s57, s34, s41
	s_cselect_b32 s56, s35, s37
	s_add_i32 s76, 0, 0x14000
	s_waitcnt vmcnt(0)
	v_add_u32_e32 v160, s68, v153
	v_add_u32_e32 v198, s76, v153
	ds_read_b128 v[132:135], v160
	ds_read_b128 v[136:139], v160 offset:1024
	ds_read_b128 v[156:159], v160 offset:2048
	ds_read_b128 v[160:163], v160 offset:3072
	ds_read_b128 v[186:189], v198
	ds_read_b128 v[190:193], v198 offset:1024
	ds_read_b128 v[194:197], v198 offset:2048
	ds_read_b128 v[198:201], v198 offset:3072
	v_lshl_add_u64 v[226:227], s[52:53], 0, v[148:149]
	s_add_i32 m0, s10, 0xc000
	ds_read_b128 v[202:205], v155
	ds_read_b128 v[206:209], v155 offset:1024
	ds_read_b128 v[210:213], v155 offset:2048
	ds_read_b128 v[214:217], v155 offset:3072
	ds_read_b128 v[218:221], v155 offset:4096
	ds_read_b128 v[222:225], v155 offset:5120
	ds_read_b128 v[234:237], v155 offset:6144
	ds_read_b128 v[238:241], v155 offset:7168
	global_load_lds_dwordx4 v[226:227], off
	v_lshl_add_u64 v[226:227], s[52:53], 0, v[150:151]
	s_add_i32 m0, s10, 0xe000
	s_nop 0
	global_load_lds_dwordx4 v[226:227], off
	s_waitcnt vmcnt(8)
	s_waitcnt lgkmcnt(0)
	s_barrier
	s_setprio 1
	v_mfma_f32_16x16x32_bf16 v[128:131], v[132:135], v[202:205], v[128:131]
	v_mfma_f32_16x16x32_bf16 v[124:127], v[156:159], v[202:205], v[124:127]
	v_mfma_f32_16x16x32_bf16 v[112:115], v[132:135], v[210:213], v[112:115]
	v_mfma_f32_16x16x32_bf16 v[108:111], v[156:159], v[210:213], v[108:111]
	v_mfma_f32_16x16x32_bf16 v[96:99], v[132:135], v[218:221], v[96:99]
	v_mfma_f32_16x16x32_bf16 v[92:95], v[156:159], v[218:221], v[92:95]
	v_mfma_f32_16x16x32_bf16 v[80:83], v[132:135], v[234:237], v[80:83]
	v_mfma_f32_16x16x32_bf16 v[76:79], v[156:159], v[234:237], v[76:79]
	v_mfma_f32_16x16x32_bf16 v[128:131], v[136:139], v[206:209], v[128:131]
	v_mfma_f32_16x16x32_bf16 v[124:127], v[160:163], v[206:209], v[124:127]
	v_mfma_f32_16x16x32_bf16 v[112:115], v[136:139], v[214:217], v[112:115]
	v_mfma_f32_16x16x32_bf16 v[108:111], v[160:163], v[214:217], v[108:111]
	v_mfma_f32_16x16x32_bf16 v[96:99], v[136:139], v[222:225], v[96:99]
	v_mfma_f32_16x16x32_bf16 v[92:95], v[160:163], v[222:225], v[92:95]
	v_mfma_f32_16x16x32_bf16 v[80:83], v[136:139], v[238:241], v[80:83]
	v_mfma_f32_16x16x32_bf16 v[76:79], v[160:163], v[238:241], v[76:79]
	v_mfma_f32_16x16x32_bf16 v[120:123], v[186:189], v[202:205], v[120:123]
	v_mfma_f32_16x16x32_bf16 v[116:119], v[194:197], v[202:205], v[116:119]
	v_mfma_f32_16x16x32_bf16 v[104:107], v[186:189], v[210:213], v[104:107]
	v_mfma_f32_16x16x32_bf16 v[100:103], v[194:197], v[210:213], v[100:103]
	v_mfma_f32_16x16x32_bf16 v[88:91], v[186:189], v[218:221], v[88:91]
	v_mfma_f32_16x16x32_bf16 v[84:87], v[194:197], v[218:221], v[84:87]
	v_mfma_f32_16x16x32_bf16 v[72:75], v[186:189], v[234:237], v[72:75]
	v_mfma_f32_16x16x32_bf16 v[68:71], v[194:197], v[234:237], v[68:71]
	v_mfma_f32_16x16x32_bf16 v[120:123], v[190:193], v[206:209], v[120:123]
	v_mfma_f32_16x16x32_bf16 v[116:119], v[198:201], v[206:209], v[116:119]
	v_mfma_f32_16x16x32_bf16 v[104:107], v[190:193], v[214:217], v[104:107]
	v_mfma_f32_16x16x32_bf16 v[100:103], v[198:201], v[214:217], v[100:103]
	v_mfma_f32_16x16x32_bf16 v[88:91], v[190:193], v[222:225], v[88:91]
	v_mfma_f32_16x16x32_bf16 v[84:87], v[198:201], v[222:225], v[84:87]
	v_mfma_f32_16x16x32_bf16 v[72:75], v[190:193], v[238:241], v[72:75]
	v_mfma_f32_16x16x32_bf16 v[68:71], v[198:201], v[238:241], v[68:71]
	s_setprio 0
	s_barrier
; #define PG8_STAGE(bufoff, gbase, voff) do { _Pragma("unroll") for (int _i = 0; _i < 2; ++_i) \
;         __builtin_amdgcn_global_load_lds((const unsigned*)((const char*)(gbase) + (voff)[_i]), (PG8_LAS unsigned*)(lds + (bufoff) + ldsw + _i * 8192), 16, 0, 0); } while (0)
; #define PG8_LDA(dst, b, h) do { _Pragma("unroll") for (int m = 0; m < 4; ++m) _Pragma("unroll") for (int k = 0; k < 2; ++k) dst[m][k] = *(const PG8_LAS bf16x8*)(lds + PG8_SA(b, h) + aoff + m * 2048 + k * 1024); } while (0)
; #define PG8_LDB(dst, b, h) do { _Pragma("unroll") for (int n = 0; n < 2; ++n) _Pragma("unroll") for (int k = 0; k < 2; ++k) dst[n][k] = *(const PG8_LAS bf16x8*)(lds + PG8_SB(b, h) + boff + n * 2048 + k * 1024); } while (0)
; #define PG8_WAIT_V(n) asm volatile("s_waitcnt vmcnt(" #n ")" ::: "memory")
; #define PG8_WAIT_L(n) asm volatile("s_waitcnt lgkmcnt(" #n ")" ::: "memory")
; #define PG8_BAR __builtin_amdgcn_s_barrier()
; #define PG8_SCHED __builtin_amdgcn_sched_barrier(0)
;     ...
;             PG8_LDA(At, 0, 1); PG8_STAGE(PG8_SB(0, 0), b2, voffB); PG8_STAGE(PG8_SB(0, 1), b2 + hstepB, voffB); PG8_STAGE(PG8_SA(0, 0), a2, voffA);
;             PG8_WAIT_V(8); PG8_WAIT_L(0); PG8_BAR; PG8_MMA(1, 0, At, B0); PG8_MMA(1, 1, At, B1); PG8_BAR; PG8_SCHED;
;             PG8_LDB(B0, 1, 0); PG8_LDB(B1, 1, 1); PG8_SCHED; PG8_LDA(At, 1, 0); PG8_STAGE(PG8_SA(0, 1), a2 + hstepA, voffA);
;             PG8_WAIT_V(8); PG8_WAIT_L(0); PG8_BAR; PG8_MMA(0, 0, At, B0); PG8_MMA(0, 1, At, B1); PG8_BAR; PG8_SCHED;
	s_add_i32 s68, s68, s9
	v_lshl_add_u64 v[226:227], s[56:57], 0, v[142:143]
	s_mov_b32 m0, s68
	ds_read_b128 v[202:205], v155 offset:16384
	ds_read_b128 v[206:209], v155 offset:17408
	ds_read_b128 v[210:213], v155 offset:18432
	ds_read_b128 v[214:217], v155 offset:19456
	ds_read_b128 v[218:221], v155 offset:20480
	ds_read_b128 v[222:225], v155 offset:21504
	ds_read_b128 v[234:237], v155 offset:22528
	ds_read_b128 v[238:241], v155 offset:23552
	global_load_lds_dwordx4 v[226:227], off
	s_add_i32 m0, s68, 0x2000
	s_add_u32 s70, s56, 0x80000
	v_lshl_add_u64 v[242:243], s[56:57], 0, v[146:147]
	s_addc_u32 s71, s57, 0
	s_add_i32 s68, s76, s9
	global_load_lds_dwordx4 v[242:243], off
	v_lshl_add_u64 v[244:245], s[70:71], 0, v[142:143]
	s_mov_b32 m0, s68
	v_lshl_add_u64 v[246:247], s[58:59], 0, v[144:145]
	global_load_lds_dwordx4 v[244:245], off
	v_lshl_add_u64 v[244:245], s[70:71], 0, v[146:147]
	s_add_i32 m0, s68, 0x2000
	s_nop 0
	global_load_lds_dwordx4 v[244:245], off
	v_lshl_add_u64 v[244:245], s[58:59], 0, v[140:141]
	s_mov_b32 m0, s10
	s_nop 0
	global_load_lds_dwordx4 v[244:245], off
	s_mov_b32 m0, s11
	s_nop 0
	global_load_lds_dwordx4 v[246:247], off
	s_waitcnt vmcnt(8)
	s_waitcnt lgkmcnt(0)
	s_barrier
	s_setprio 1
	v_mfma_f32_16x16x32_bf16 v[64:67], v[132:135], v[202:205], v[64:67]
	v_mfma_f32_16x16x32_bf16 v[60:63], v[156:159], v[202:205], v[60:63]
	v_mfma_f32_16x16x32_bf16 v[48:51], v[132:135], v[210:213], v[48:51]
	v_mfma_f32_16x16x32_bf16 v[44:47], v[156:159], v[210:213], v[44:47]
	v_mfma_f32_16x16x32_bf16 v[30:33], v[132:135], v[218:221], v[30:33]
	v_mfma_f32_16x16x32_bf16 v[26:29], v[156:159], v[218:221], v[26:29]
	v_mfma_f32_16x16x32_bf16 v[14:17], v[132:135], v[234:237], v[14:17]
	v_mfma_f32_16x16x32_bf16 v[10:13], v[156:159], v[234:237], v[10:13]
	v_mfma_f32_16x16x32_bf16 v[64:67], v[136:139], v[206:209], v[64:67]
	v_mfma_f32_16x16x32_bf16 v[60:63], v[160:163], v[206:209], v[60:63]
	v_mfma_f32_16x16x32_bf16 v[48:51], v[136:139], v[214:217], v[48:51]
	v_mfma_f32_16x16x32_bf16 v[44:47], v[160:163], v[214:217], v[44:47]
	v_mfma_f32_16x16x32_bf16 v[30:33], v[136:139], v[222:225], v[30:33]
	v_mfma_f32_16x16x32_bf16 v[26:29], v[160:163], v[222:225], v[26:29]
	v_mfma_f32_16x16x32_bf16 v[14:17], v[136:139], v[238:241], v[14:17]
	v_mfma_f32_16x16x32_bf16 v[10:13], v[160:163], v[238:241], v[10:13]
	v_mfma_f32_16x16x32_bf16 v[56:59], v[186:189], v[202:205], v[56:59]
	v_mfma_f32_16x16x32_bf16 v[52:55], v[194:197], v[202:205], v[52:55]
	v_mfma_f32_16x16x32_bf16 v[40:43], v[186:189], v[210:213], v[40:43]
	v_mfma_f32_16x16x32_bf16 v[36:39], v[194:197], v[210:213], v[36:39]
	v_mfma_f32_16x16x32_bf16 v[22:25], v[186:189], v[218:221], v[22:25]
	v_mfma_f32_16x16x32_bf16 v[18:21], v[194:197], v[218:221], v[18:21]
	v_mfma_f32_16x16x32_bf16 v[6:9], v[186:189], v[234:237], v[6:9]
	v_mfma_f32_16x16x32_bf16 v[2:5], v[194:197], v[234:237], v[2:5]
	v_mfma_f32_16x16x32_bf16 v[56:59], v[190:193], v[206:209], v[56:59]
	v_mfma_f32_16x16x32_bf16 v[52:55], v[198:201], v[206:209], v[52:55]
	v_mfma_f32_16x16x32_bf16 v[40:43], v[190:193], v[214:217], v[40:43]
	v_mfma_f32_16x16x32_bf16 v[36:39], v[198:201], v[214:217], v[36:39]
	v_mfma_f32_16x16x32_bf16 v[22:25], v[190:193], v[222:225], v[22:25]
	v_mfma_f32_16x16x32_bf16 v[18:21], v[198:201], v[222:225], v[18:21]
	v_mfma_f32_16x16x32_bf16 v[6:9], v[190:193], v[238:241], v[6:9]
	v_mfma_f32_16x16x32_bf16 v[2:5], v[198:201], v[238:241], v[2:5]
	s_setprio 0
	s_barrier
	s_add_i32 s68, 0, 0x18000
	s_add_i32 s70, 0, 0x1c000
	v_add_u32_e32 v160, s68, v153
	v_add_u32_e32 v198, s70, v153
	ds_read_b128 v[132:135], v160
	ds_read_b128 v[136:139], v160 offset:1024
	ds_read_b128 v[156:159], v160 offset:2048
	ds_read_b128 v[160:163], v160 offset:3072
	ds_read_b128 v[186:189], v198
	ds_read_b128 v[190:193], v198 offset:1024
	ds_read_b128 v[194:197], v198 offset:2048
	ds_read_b128 v[198:201], v198 offset:3072
	s_add_u32 s58, s58, 0x80000
	s_addc_u32 s59, s59, 0
	s_mov_b32 m0, s12
	v_lshl_add_u64 v[248:249], s[58:59], 0, v[140:141]
	ds_read_b128 v[202:205], v155 offset:32768
	ds_read_b128 v[206:209], v155 offset:33792
	ds_read_b128 v[210:213], v155 offset:34816
	ds_read_b128 v[214:217], v155 offset:35840
	ds_read_b128 v[218:221], v155 offset:36864
	ds_read_b128 v[222:225], v155 offset:37888
	ds_read_b128 v[234:237], v155 offset:38912
	ds_read_b128 v[238:241], v155 offset:39936
	global_load_lds_dwordx4 v[248:249], off
	v_lshl_add_u64 v[248:249], s[58:59], 0, v[144:145]
	s_mov_b32 m0, s13
	s_nop 0
	global_load_lds_dwordx4 v[248:249], off
	s_waitcnt vmcnt(8)
	s_waitcnt lgkmcnt(0)
	s_barrier
; #define PG8_STAGE(bufoff, gbase, voff) do { _Pragma("unroll") for (int _i = 0; _i < 2; ++_i) \
;         __builtin_amdgcn_global_load_lds((const unsigned*)((const char*)(gbase) + (voff)[_i]), (PG8_LAS unsigned*)(lds + (bufoff) + ldsw + _i * 8192), 16, 0, 0); } while (0)
; #define PG8_LDA(dst, b, h) do { _Pragma("unroll") for (int m = 0; m < 4; ++m) _Pragma("unroll") for (int k = 0; k < 2; ++k) dst[m][k] = *(const PG8_LAS bf16x8*)(lds + PG8_SA(b, h) + aoff + m * 2048 + k * 1024); } while (0)
; #define PG8_WAIT_V(n) asm volatile("s_waitcnt vmcnt(" #n ")" ::: "memory")
; #define PG8_WAIT_L(n) asm volatile("s_waitcnt lgkmcnt(" #n ")" ::: "memory")
; #define PG8_BAR __builtin_amdgcn_s_barrier()
; #define PG8_SCHED __builtin_amdgcn_sched_barrier(0)
;     ...
;             PG8_WAIT_V(8); PG8_WAIT_L(0); PG8_BAR; PG8_MMA(0, 0, At, B0); PG8_MMA(0, 1, At, B1); PG8_BAR; PG8_SCHED;
;             PG8_LDA(At, 1, 1); PG8_STAGE(PG8_SB(1, 0), b3, voffB); PG8_STAGE(PG8_SB(1, 1), b3 + hstepB, voffB); PG8_STAGE(PG8_SA(1, 0), a3, voffA);
;             PG8_WAIT_V(8); PG8_WAIT_L(0); PG8_BAR; PG8_MMA(1, 0, At, B0); PG8_MMA(1, 1, At, B1); PG8_BAR; PG8_SCHED;
;     ...
;         if constexpr (ALIGN_EPI) { if (wr == 0) PG8_BAR; }
;         if constexpr (Q8 == 1) asm volatile("s_nop 15\n\ts_nop 15" ::: "memory");
;         if constexpr (!Epi::AFTER_DRAIN) { E(acc, cur, wr, wc, fr, fq); S.done(cur); }
;         if (!has_next) break;
	s_setprio 1
	v_mfma_f32_16x16x32_bf16 v[128:131], v[132:135], v[202:205], v[128:131]
	v_mfma_f32_16x16x32_bf16 v[124:127], v[156:159], v[202:205], v[124:127]
	v_mfma_f32_16x16x32_bf16 v[112:115], v[132:135], v[210:213], v[112:115]
	v_mfma_f32_16x16x32_bf16 v[108:111], v[156:159], v[210:213], v[108:111]
	v_mfma_f32_16x16x32_bf16 v[96:99], v[132:135], v[218:221], v[96:99]
	v_mfma_f32_16x16x32_bf16 v[92:95], v[156:159], v[218:221], v[92:95]
	v_mfma_f32_16x16x32_bf16 v[80:83], v[132:135], v[234:237], v[80:83]
	v_mfma_f32_16x16x32_bf16 v[76:79], v[156:159], v[234:237], v[76:79]
	v_mfma_f32_16x16x32_bf16 v[128:131], v[136:139], v[206:209], v[128:131]
	v_mfma_f32_16x16x32_bf16 v[124:127], v[160:163], v[206:209], v[124:127]
	v_mfma_f32_16x16x32_bf16 v[112:115], v[136:139], v[214:217], v[112:115]
	v_mfma_f32_16x16x32_bf16 v[108:111], v[160:163], v[214:217], v[108:111]
	v_mfma_f32_16x16x32_bf16 v[96:99], v[136:139], v[222:225], v[96:99]
	v_mfma_f32_16x16x32_bf16 v[92:95], v[160:163], v[222:225], v[92:95]
	v_mfma_f32_16x16x32_bf16 v[80:83], v[136:139], v[238:241], v[80:83]
	v_mfma_f32_16x16x32_bf16 v[76:79], v[160:163], v[238:241], v[76:79]
	v_mfma_f32_16x16x32_bf16 v[120:123], v[186:189], v[202:205], v[120:123]
	v_mfma_f32_16x16x32_bf16 v[116:119], v[194:197], v[202:205], v[116:119]
	v_mfma_f32_16x16x32_bf16 v[104:107], v[186:189], v[210:213], v[104:107]
	v_mfma_f32_16x16x32_bf16 v[100:103], v[194:197], v[210:213], v[100:103]
	v_mfma_f32_16x16x32_bf16 v[88:91], v[186:189], v[218:221], v[88:91]
	v_mfma_f32_16x16x32_bf16 v[84:87], v[194:197], v[218:221], v[84:87]
	v_mfma_f32_16x16x32_bf16 v[72:75], v[186:189], v[234:237], v[72:75]
	v_mfma_f32_16x16x32_bf16 v[68:71], v[194:197], v[234:237], v[68:71]
	v_mfma_f32_16x16x32_bf16 v[120:123], v[190:193], v[206:209], v[120:123]
	v_mfma_f32_16x16x32_bf16 v[116:119], v[198:201], v[206:209], v[116:119]
	v_mfma_f32_16x16x32_bf16 v[104:107], v[190:193], v[214:217], v[104:107]
	v_mfma_f32_16x16x32_bf16 v[100:103], v[198:201], v[214:217], v[100:103]
	v_mfma_f32_16x16x32_bf16 v[88:91], v[190:193], v[222:225], v[88:91]
	v_mfma_f32_16x16x32_bf16 v[84:87], v[198:201], v[222:225], v[84:87]
	v_mfma_f32_16x16x32_bf16 v[72:75], v[190:193], v[238:241], v[72:75]
	v_mfma_f32_16x16x32_bf16 v[68:71], v[198:201], v[238:241], v[68:71]
	s_setprio 0
	s_barrier
	s_add_i32 s58, s68, s9
	v_lshl_add_u64 v[226:227], v[226:227], 0, s[22:23]
	s_mov_b32 m0, s58
	ds_read_b128 v[202:205], v155 offset:49152
	ds_read_b128 v[206:209], v155 offset:50176
	ds_read_b128 v[210:213], v155 offset:51200
	ds_read_b128 v[214:217], v155 offset:52224
	ds_read_b128 v[218:221], v155 offset:53248
	ds_read_b128 v[222:225], v155 offset:54272
	ds_read_b128 v[234:237], v155 offset:55296
	ds_read_b128 v[238:241], v155 offset:56320
	global_load_lds_dwordx4 v[226:227], off
	s_add_i32 m0, s58, 0x2000
	s_add_u32 s56, s56, 0x80080
	v_lshl_add_u64 v[226:227], v[242:243], 0, s[22:23]
	s_addc_u32 s57, s57, 0
	s_add_i32 s58, s70, s9
	global_load_lds_dwordx4 v[226:227], off
	v_lshl_add_u64 v[226:227], s[56:57], 0, v[142:143]
	s_mov_b32 m0, s58
	s_nop 0
	global_load_lds_dwordx4 v[226:227], off
	v_lshl_add_u64 v[226:227], s[56:57], 0, v[146:147]
	s_add_i32 m0, s58, 0x2000
	s_nop 0
	global_load_lds_dwordx4 v[226:227], off
	v_lshl_add_u64 v[226:227], v[244:245], 0, s[22:23]
	s_mov_b32 m0, s55
	s_nop 0
	global_load_lds_dwordx4 v[226:227], off
	v_lshl_add_u64 v[226:227], v[246:247], 0, s[22:23]
	s_mov_b32 m0, s66
	s_nop 0
	global_load_lds_dwordx4 v[226:227], off
	s_waitcnt vmcnt(8)
	s_waitcnt lgkmcnt(0)
	s_barrier
	s_setprio 1
	v_mfma_f32_16x16x32_bf16 v[64:67], v[132:135], v[202:205], v[64:67]
	v_mfma_f32_16x16x32_bf16 v[60:63], v[156:159], v[202:205], v[60:63]
	v_mfma_f32_16x16x32_bf16 v[48:51], v[132:135], v[210:213], v[48:51]
	v_mfma_f32_16x16x32_bf16 v[44:47], v[156:159], v[210:213], v[44:47]
	v_mfma_f32_16x16x32_bf16 v[30:33], v[132:135], v[218:221], v[30:33]
	v_mfma_f32_16x16x32_bf16 v[26:29], v[156:159], v[218:221], v[26:29]
	v_mfma_f32_16x16x32_bf16 v[14:17], v[132:135], v[234:237], v[14:17]
	v_mfma_f32_16x16x32_bf16 v[10:13], v[156:159], v[234:237], v[10:13]
	v_mfma_f32_16x16x32_bf16 v[64:67], v[136:139], v[206:209], v[64:67]
	v_mfma_f32_16x16x32_bf16 v[60:63], v[160:163], v[206:209], v[60:63]
	v_mfma_f32_16x16x32_bf16 v[48:51], v[136:139], v[214:217], v[48:51]
	v_mfma_f32_16x16x32_bf16 v[44:47], v[160:163], v[214:217], v[44:47]
	v_mfma_f32_16x16x32_bf16 v[30:33], v[136:139], v[222:225], v[30:33]
	v_mfma_f32_16x16x32_bf16 v[26:29], v[160:163], v[222:225], v[26:29]
	v_mfma_f32_16x16x32_bf16 v[14:17], v[136:139], v[238:241], v[14:17]
	v_mfma_f32_16x16x32_bf16 v[10:13], v[160:163], v[238:241], v[10:13]
	v_mfma_f32_16x16x32_bf16 v[56:59], v[186:189], v[202:205], v[56:59]
	v_mfma_f32_16x16x32_bf16 v[52:55], v[194:197], v[202:205], v[52:55]
	v_mfma_f32_16x16x32_bf16 v[40:43], v[186:189], v[210:213], v[40:43]
	v_mfma_f32_16x16x32_bf16 v[36:39], v[194:197], v[210:213], v[36:39]
	v_mfma_f32_16x16x32_bf16 v[22:25], v[186:189], v[218:221], v[22:25]
	v_mfma_f32_16x16x32_bf16 v[18:21], v[194:197], v[218:221], v[18:21]
	v_mfma_f32_16x16x32_bf16 v[6:9], v[186:189], v[234:237], v[6:9]
	v_mfma_f32_16x16x32_bf16 v[2:5], v[194:197], v[234:237], v[2:5]
	v_mfma_f32_16x16x32_bf16 v[56:59], v[190:193], v[206:209], v[56:59]
	v_mfma_f32_16x16x32_bf16 v[52:55], v[198:201], v[206:209], v[52:55]
	v_mfma_f32_16x16x32_bf16 v[40:43], v[190:193], v[214:217], v[40:43]
	v_mfma_f32_16x16x32_bf16 v[36:39], v[198:201], v[214:217], v[36:39]
	v_mfma_f32_16x16x32_bf16 v[22:25], v[190:193], v[222:225], v[22:25]
	v_mfma_f32_16x16x32_bf16 v[18:21], v[198:201], v[222:225], v[18:21]
	v_mfma_f32_16x16x32_bf16 v[6:9], v[190:193], v[238:241], v[6:9]
	v_mfma_f32_16x16x32_bf16 v[2:5], v[198:201], v[238:241], v[2:5]
	s_setprio 0
	s_barrier
	s_add_i32 s47, s47, 2
	s_add_u32 s52, s52, 0x100
	s_addc_u32 s53, s53, 0
	s_add_u32 s37, s37, 0x100
	s_addc_u32 s41, s41, 0
	s_cmp_gt_u32 s47, 29
	s_cbranch_scc0 .LBB0_923
	s_and_b64 vcc, exec, s[30:31]
	s_cbranch_vccz .LBB0_926
	s_barrier

; #define PG8_STAGE(bufoff, gbase, voff) do { _Pragma("unroll") for (int _i = 0; _i < 2; ++_i) \
;         __builtin_amdgcn_global_load_lds((const unsigned*)((const char*)(gbase) + (voff)[_i]), (PG8_LAS unsigned*)(lds + (bufoff) + ldsw + _i * 8192), 16, 0, 0); } while (0)
; #define PG8_LDA(dst, b, h) do { _Pragma("unroll") for (int m = 0; m < 4; ++m) _Pragma("unroll") for (int k = 0; k < 2; ++k) dst[m][k] = *(const PG8_LAS bf16x8*)(lds + PG8_SA(b, h) + aoff + m * 2048 + k * 1024); } while (0)
; #define PG8_LDB(dst, b, h) do { _Pragma("unroll") for (int n = 0; n < 2; ++n) _Pragma("unroll") for (int k = 0; k < 2; ++k) dst[n][k] = *(const PG8_LAS bf16x8*)(lds + PG8_SB(b, h) + boff + n * 2048 + k * 1024); } while (0)
; #define PG8_WAIT_V(n) asm volatile("s_waitcnt vmcnt(" #n ")" ::: "memory")
; #define PG8_WAIT_L(n) asm volatile("s_waitcnt lgkmcnt(" #n ")" ::: "memory")
; #define PG8_BAR __builtin_amdgcn_s_barrier()
; #define PG8_SCHED __builtin_amdgcn_sched_barrier(0)
;     ...
;             PG8_LDB(B0, 0, 0); PG8_LDB(B1, 0, 1); PG8_SCHED; PG8_LDA(At, 0, 0); PG8_STAGE(PG8_SA(1, 1), a1 + hstepA, voffA);
;             PG8_WAIT_V(8); PG8_WAIT_L(0); PG8_BAR; PG8_MMA(0, 0, At, B0); PG8_MMA(0, 1, At, B1); PG8_BAR; PG8_SCHED;
;             PG8_LDA(At, 0, 1); PG8_STAGE(PG8_SB(0, 0), b2, voffB); PG8_STAGE(PG8_SB(0, 1), b2 + hstepB, voffB); PG8_STAGE(PG8_SA(0, 0), a2, voffA);
;             PG8_WAIT_V(8); PG8_WAIT_L(0); PG8_BAR; PG8_MMA(1, 0, At, B0); PG8_MMA(1, 1, At, B1); PG8_BAR; PG8_SCHED;
.LBB0_1133:
	s_add_u32 s52, s50, 0xfffc0080
	s_addc_u32 s53, s51, -1
	s_add_i32 s75, 0, 0x10000
	s_cmp_eq_u32 s74, 12
	s_cselect_b32 s55, s37, s53
	s_cselect_b32 s54, s67, s52
	s_cselect_b32 s53, s31, s71
	s_cselect_b32 s52, s68, s70
	s_add_i32 s76, 0, 0x14000
	v_add_u32_e32 v2, s75, v208
	v_add_u32_e32 v6, s76, v208
	ds_read_b128 v[26:29], v2
	ds_read_b128 v[30:33], v2 offset:1024
	ds_read_b128 v[18:21], v2 offset:2048
	ds_read_b128 v[22:25], v2 offset:3072
	ds_read_b128 v[10:13], v6
	ds_read_b128 v[14:17], v6 offset:1024
	ds_read_b128 v[2:5], v6 offset:2048
	ds_read_b128 v[6:9], v6 offset:3072
	v_lshl_add_u64 v[226:227], s[50:51], 0, v[194:195]
	s_add_i32 m0, s57, 0xc000
	ds_read_b128 v[198:201], v209
	ds_read_b128 v[202:205], v209 offset:1024
	ds_read_b128 v[210:213], v209 offset:2048
	ds_read_b128 v[214:217], v209 offset:3072
	ds_read_b128 v[218:221], v209 offset:4096
	ds_read_b128 v[222:225], v209 offset:5120
	ds_read_b128 v[234:237], v209 offset:6144
	ds_read_b128 v[238:241], v209 offset:7168
	global_load_lds_dwordx4 v[226:227], off
	v_lshl_add_u64 v[226:227], s[50:51], 0, v[196:197]
	s_add_i32 m0, s57, 0xe000
	s_nop 0
	global_load_lds_dwordx4 v[226:227], off
	s_waitcnt vmcnt(8)
	s_waitcnt lgkmcnt(0)
	s_barrier
	s_setprio 1
	v_mfma_f32_16x16x128_f8f6f4 v[160:163], v[26:33], v[198:205], v[160:163]
	v_mfma_f32_16x16x128_f8f6f4 v[156:159], v[18:25], v[198:205], v[156:159]
	v_mfma_f32_16x16x128_f8f6f4 v[144:147], v[26:33], v[210:217], v[144:147]
	v_mfma_f32_16x16x128_f8f6f4 v[140:143], v[18:25], v[210:217], v[140:143]
	v_mfma_f32_16x16x128_f8f6f4 v[128:131], v[26:33], v[218:225], v[128:131]
	v_mfma_f32_16x16x128_f8f6f4 v[124:127], v[18:25], v[218:225], v[124:127]
	v_mfma_f32_16x16x128_f8f6f4 v[112:115], v[26:33], v[234:241], v[112:115]
	v_mfma_f32_16x16x128_f8f6f4 v[108:111], v[18:25], v[234:241], v[108:111]
	v_mfma_f32_16x16x128_f8f6f4 v[152:155], v[10:17], v[198:205], v[152:155]
	v_mfma_f32_16x16x128_f8f6f4 v[148:151], v[2:9], v[198:205], v[148:151]
	v_mfma_f32_16x16x128_f8f6f4 v[136:139], v[10:17], v[210:217], v[136:139]
	v_mfma_f32_16x16x128_f8f6f4 v[132:135], v[2:9], v[210:217], v[132:135]
	v_mfma_f32_16x16x128_f8f6f4 v[120:123], v[10:17], v[218:225], v[120:123]
	v_mfma_f32_16x16x128_f8f6f4 v[116:119], v[2:9], v[218:225], v[116:119]
	v_mfma_f32_16x16x128_f8f6f4 v[104:107], v[10:17], v[234:241], v[104:107]
	v_mfma_f32_16x16x128_f8f6f4 v[100:103], v[2:9], v[234:241], v[100:103]
	s_setprio 0
	s_barrier
	s_add_i32 s75, s75, s11
	v_lshl_add_u64 v[198:199], s[52:53], 0, v[34:35]
	s_mov_b32 m0, s75
	ds_read_b128 v[210:213], v209 offset:16384
	ds_read_b128 v[214:217], v209 offset:17408
	ds_read_b128 v[218:221], v209 offset:18432
	ds_read_b128 v[222:225], v209 offset:19456
	ds_read_b128 v[234:237], v209 offset:20480
	ds_read_b128 v[238:241], v209 offset:21504
	ds_read_b128 v[242:245], v209 offset:22528
	ds_read_b128 v[246:249], v209 offset:23552
	global_load_lds_dwordx4 v[198:199], off
	s_add_i32 m0, s75, 0x2000
	s_add_u32 s78, s52, 0x40000
	v_lshl_add_u64 v[200:201], s[52:53], 0, v[186:187]
	s_addc_u32 s79, s53, 0
	s_add_i32 s75, s76, s11
	global_load_lds_dwordx4 v[200:201], off
	v_lshl_add_u64 v[202:203], s[78:79], 0, v[34:35]
	s_mov_b32 m0, s75
	v_lshl_add_u64 v[204:205], s[54:55], 0, v[188:189]
	global_load_lds_dwordx4 v[202:203], off
	v_lshl_add_u64 v[202:203], s[78:79], 0, v[186:187]
	s_add_i32 m0, s75, 0x2000
	s_nop 0
	global_load_lds_dwordx4 v[202:203], off
	v_lshl_add_u64 v[202:203], s[54:55], 0, v[190:191]
	s_mov_b32 m0, s57
	s_nop 0
	global_load_lds_dwordx4 v[202:203], off
	s_mov_b32 m0, s6
	s_nop 0
	global_load_lds_dwordx4 v[204:205], off
	s_waitcnt vmcnt(8)
	s_waitcnt lgkmcnt(0)
	s_barrier
	s_setprio 1
	v_mfma_f32_16x16x128_f8f6f4 v[96:99], v[26:33], v[210:217], v[96:99]
	v_mfma_f32_16x16x128_f8f6f4 v[92:95], v[18:25], v[210:217], v[92:95]
	v_mfma_f32_16x16x128_f8f6f4 v[80:83], v[26:33], v[218:225], v[80:83]
	v_mfma_f32_16x16x128_f8f6f4 v[76:79], v[18:25], v[218:225], v[76:79]
	v_mfma_f32_16x16x128_f8f6f4 v[64:67], v[26:33], v[234:241], v[64:67]
	v_mfma_f32_16x16x128_f8f6f4 v[60:63], v[18:25], v[234:241], v[60:63]
	v_mfma_f32_16x16x128_f8f6f4 v[48:51], v[26:33], v[242:249], v[48:51]
	v_mfma_f32_16x16x128_f8f6f4 v[44:47], v[18:25], v[242:249], v[44:47]
	v_mfma_f32_16x16x128_f8f6f4 v[88:91], v[10:17], v[210:217], v[88:91]
	v_mfma_f32_16x16x128_f8f6f4 v[84:87], v[2:9], v[210:217], v[84:87]
	v_mfma_f32_16x16x128_f8f6f4 v[72:75], v[10:17], v[218:225], v[72:75]
	v_mfma_f32_16x16x128_f8f6f4 v[68:71], v[2:9], v[218:225], v[68:71]
	v_mfma_f32_16x16x128_f8f6f4 v[56:59], v[10:17], v[234:241], v[56:59]
	v_mfma_f32_16x16x128_f8f6f4 v[52:55], v[2:9], v[234:241], v[52:55]
	v_mfma_f32_16x16x128_f8f6f4 v[40:43], v[10:17], v[242:249], v[40:43]
	v_mfma_f32_16x16x128_f8f6f4 v[36:39], v[2:9], v[242:249], v[36:39]
	s_setprio 0
	s_barrier
; #define PG8_STAGE(bufoff, gbase, voff) do { _Pragma("unroll") for (int _i = 0; _i < 2; ++_i) \
;         __builtin_amdgcn_global_load_lds((const unsigned*)((const char*)(gbase) + (voff)[_i]), (PG8_LAS unsigned*)(lds + (bufoff) + ldsw + _i * 8192), 16, 0, 0); } while (0)
; #define PG8_LDA(dst, b, h) do { _Pragma("unroll") for (int m = 0; m < 4; ++m) _Pragma("unroll") for (int k = 0; k < 2; ++k) dst[m][k] = *(const PG8_LAS bf16x8*)(lds + PG8_SA(b, h) + aoff + m * 2048 + k * 1024); } while (0)
; #define PG8_LDB(dst, b, h) do { _Pragma("unroll") for (int n = 0; n < 2; ++n) _Pragma("unroll") for (int k = 0; k < 2; ++k) dst[n][k] = *(const PG8_LAS bf16x8*)(lds + PG8_SB(b, h) + boff + n * 2048 + k * 1024); } while (0)
; #define PG8_WAIT_V(n) asm volatile("s_waitcnt vmcnt(" #n ")" ::: "memory")
; #define PG8_WAIT_L(n) asm volatile("s_waitcnt lgkmcnt(" #n ")" ::: "memory")
; #define PG8_BAR __builtin_amdgcn_s_barrier()
; #define PG8_SCHED __builtin_amdgcn_sched_barrier(0)
;     ...
;             PG8_LDB(B0, 1, 0); PG8_LDB(B1, 1, 1); PG8_SCHED; PG8_LDA(At, 1, 0); PG8_STAGE(PG8_SA(0, 1), a2 + hstepA, voffA);
;             PG8_WAIT_V(8); PG8_WAIT_L(0); PG8_BAR; PG8_MMA(0, 0, At, B0); PG8_MMA(0, 1, At, B1); PG8_BAR; PG8_SCHED;
;             PG8_LDA(At, 1, 1); PG8_STAGE(PG8_SB(1, 0), b3, voffB); PG8_STAGE(PG8_SB(1, 1), b3 + hstepB, voffB); PG8_STAGE(PG8_SA(1, 0), a3, voffA);
;             PG8_WAIT_V(8); PG8_WAIT_L(0); PG8_BAR; PG8_MMA(1, 0, At, B0); PG8_MMA(1, 1, At, B1); PG8_BAR; PG8_SCHED;
	s_add_i32 s75, 0, 0x18000
	s_add_i32 s76, 0, 0x1c000
	v_add_u32_e32 v14, s75, v208
	v_add_u32_e32 v30, s76, v208
	ds_read_b128 v[2:5], v14
	ds_read_b128 v[6:9], v14 offset:1024
	ds_read_b128 v[10:13], v14 offset:2048
	ds_read_b128 v[14:17], v14 offset:3072
	ds_read_b128 v[18:21], v30
	ds_read_b128 v[22:25], v30 offset:1024
	ds_read_b128 v[26:29], v30 offset:2048
	ds_read_b128 v[30:33], v30 offset:3072
	s_add_u32 s54, s54, 0x40000
	s_addc_u32 s55, s55, 0
	s_mov_b32 m0, s15
	v_lshl_add_u64 v[226:227], s[54:55], 0, v[190:191]
	ds_read_b128 v[210:213], v209 offset:32768
	ds_read_b128 v[214:217], v209 offset:33792
	ds_read_b128 v[218:221], v209 offset:34816
	ds_read_b128 v[222:225], v209 offset:35840
	ds_read_b128 v[234:237], v209 offset:36864
	ds_read_b128 v[238:241], v209 offset:37888
	ds_read_b128 v[242:245], v209 offset:38912
	ds_read_b128 v[246:249], v209 offset:39936
	global_load_lds_dwordx4 v[226:227], off
	v_lshl_add_u64 v[226:227], s[54:55], 0, v[188:189]
	s_mov_b32 m0, s34
	s_nop 0
	global_load_lds_dwordx4 v[226:227], off
	s_waitcnt vmcnt(8)
	s_waitcnt lgkmcnt(0)
	s_barrier
	s_setprio 1
	v_mfma_f32_16x16x128_f8f6f4 v[160:163], v[2:9], v[210:217], v[160:163]
	v_mfma_f32_16x16x128_f8f6f4 v[156:159], v[10:17], v[210:217], v[156:159]
	v_mfma_f32_16x16x128_f8f6f4 v[144:147], v[2:9], v[218:225], v[144:147]
	v_mfma_f32_16x16x128_f8f6f4 v[140:143], v[10:17], v[218:225], v[140:143]
	v_mfma_f32_16x16x128_f8f6f4 v[128:131], v[2:9], v[234:241], v[128:131]
	v_mfma_f32_16x16x128_f8f6f4 v[124:127], v[10:17], v[234:241], v[124:127]
	v_mfma_f32_16x16x128_f8f6f4 v[112:115], v[2:9], v[242:249], v[112:115]
	v_mfma_f32_16x16x128_f8f6f4 v[108:111], v[10:17], v[242:249], v[108:111]
	v_mfma_f32_16x16x128_f8f6f4 v[152:155], v[18:25], v[210:217], v[152:155]
	v_mfma_f32_16x16x128_f8f6f4 v[148:151], v[26:33], v[210:217], v[148:151]
	v_mfma_f32_16x16x128_f8f6f4 v[136:139], v[18:25], v[218:225], v[136:139]
	v_mfma_f32_16x16x128_f8f6f4 v[132:135], v[26:33], v[218:225], v[132:135]
	v_mfma_f32_16x16x128_f8f6f4 v[120:123], v[18:25], v[234:241], v[120:123]
	v_mfma_f32_16x16x128_f8f6f4 v[116:119], v[26:33], v[234:241], v[116:119]
	v_mfma_f32_16x16x128_f8f6f4 v[104:107], v[18:25], v[242:249], v[104:107]
	v_mfma_f32_16x16x128_f8f6f4 v[100:103], v[26:33], v[242:249], v[100:103]
	s_setprio 0
	s_barrier
	s_add_i32 s54, s75, s11
	v_lshl_add_u64 v[198:199], v[198:199], 0, s[22:23]
	s_mov_b32 m0, s54
	ds_read_b128 v[210:213], v209 offset:49152
	ds_read_b128 v[214:217], v209 offset:50176
	ds_read_b128 v[218:221], v209 offset:51200
	ds_read_b128 v[222:225], v209 offset:52224
	ds_read_b128 v[234:237], v209 offset:53248
	ds_read_b128 v[238:241], v209 offset:54272
	ds_read_b128 v[242:245], v209 offset:55296
	ds_read_b128 v[246:249], v209 offset:56320
	global_load_lds_dwordx4 v[198:199], off
	s_add_i32 m0, s54, 0x2000
	s_add_u32 s52, s52, 0x40080
	v_lshl_add_u64 v[198:199], v[200:201], 0, s[22:23]
	s_addc_u32 s53, s53, 0
	s_add_i32 s54, s76, s11
	global_load_lds_dwordx4 v[198:199], off
	v_lshl_add_u64 v[198:199], s[52:53], 0, v[34:35]
	s_mov_b32 m0, s54
	s_nop 0
	global_load_lds_dwordx4 v[198:199], off
	v_lshl_add_u64 v[198:199], s[52:53], 0, v[186:187]
	s_add_i32 m0, s54, 0x2000
	s_nop 0
	global_load_lds_dwordx4 v[198:199], off
	v_lshl_add_u64 v[198:199], v[202:203], 0, s[22:23]
	s_mov_b32 m0, s35
	s_nop 0
	global_load_lds_dwordx4 v[198:199], off
	v_lshl_add_u64 v[198:199], v[204:205], 0, s[22:23]
	s_mov_b32 m0, s58
	s_nop 0
	global_load_lds_dwordx4 v[198:199], off
	s_waitcnt vmcnt(8)
	s_waitcnt lgkmcnt(0)
	s_barrier
	s_setprio 1
	v_mfma_f32_16x16x128_f8f6f4 v[96:99], v[2:9], v[210:217], v[96:99]
	v_mfma_f32_16x16x128_f8f6f4 v[92:95], v[10:17], v[210:217], v[92:95]
	v_mfma_f32_16x16x128_f8f6f4 v[80:83], v[2:9], v[218:225], v[80:83]
	v_mfma_f32_16x16x128_f8f6f4 v[76:79], v[10:17], v[218:225], v[76:79]
	v_mfma_f32_16x16x128_f8f6f4 v[64:67], v[2:9], v[234:241], v[64:67]
	v_mfma_f32_16x16x128_f8f6f4 v[60:63], v[10:17], v[234:241], v[60:63]
	v_mfma_f32_16x16x128_f8f6f4 v[48:51], v[2:9], v[242:249], v[48:51]
	v_mfma_f32_16x16x128_f8f6f4 v[44:47], v[10:17], v[242:249], v[44:47]
	v_mfma_f32_16x16x128_f8f6f4 v[88:91], v[18:25], v[210:217], v[88:91]
	v_mfma_f32_16x16x128_f8f6f4 v[84:87], v[26:33], v[210:217], v[84:87]
	v_mfma_f32_16x16x128_f8f6f4 v[72:75], v[18:25], v[218:225], v[72:75]
	v_mfma_f32_16x16x128_f8f6f4 v[68:71], v[26:33], v[218:225], v[68:71]
	v_mfma_f32_16x16x128_f8f6f4 v[56:59], v[18:25], v[234:241], v[56:59]
	v_mfma_f32_16x16x128_f8f6f4 v[52:55], v[26:33], v[234:241], v[52:55]
	v_mfma_f32_16x16x128_f8f6f4 v[40:43], v[18:25], v[242:249], v[40:43]
	v_mfma_f32_16x16x128_f8f6f4 v[36:39], v[26:33], v[242:249], v[36:39]
	s_setprio 0
	s_barrier
	s_add_i32 s74, s74, 2
	s_add_u32 s50, s50, 0x100
	s_addc_u32 s51, s51, 0
	s_add_u32 s70, s70, 0x100
	s_addc_u32 s71, s71, 0
	s_cmp_gt_u32 s74, 13
	s_cbranch_scc0 .LBB0_1133
	s_and_b64 vcc, exec, s[28:29]
	s_cbranch_vccz .LBB0_1136
	s_barrier

; #define PG8_STAGE(bufoff, gbase, voff) do { _Pragma("unroll") for (int _i = 0; _i < 2; ++_i) \
;         __builtin_amdgcn_global_load_lds((const unsigned*)((const char*)(gbase) + (voff)[_i]), (PG8_LAS unsigned*)(lds + (bufoff) + ldsw + _i * 8192), 16, 0, 0); } while (0)
; #define PG8_LDA(dst, b, h) do { _Pragma("unroll") for (int m = 0; m < 4; ++m) _Pragma("unroll") for (int k = 0; k < 2; ++k) dst[m][k] = *(const PG8_LAS bf16x8*)(lds + PG8_SA(b, h) + aoff + m * 2048 + k * 1024); } while (0)
; #define PG8_LDB(dst, b, h) do { _Pragma("unroll") for (int n = 0; n < 2; ++n) _Pragma("unroll") for (int k = 0; k < 2; ++k) dst[n][k] = *(const PG8_LAS bf16x8*)(lds + PG8_SB(b, h) + boff + n * 2048 + k * 1024); } while (0)
; #define PG8_WAIT_V(n) asm volatile("s_waitcnt vmcnt(" #n ")" ::: "memory")
; #define PG8_WAIT_L(n) asm volatile("s_waitcnt lgkmcnt(" #n ")" ::: "memory")
; #define PG8_BAR __builtin_amdgcn_s_barrier()
; #define PG8_SCHED __builtin_amdgcn_sched_barrier(0)
;     ...
;         for (int t = 0; t < nt; t += 2) {
;             const bool last = (t == nt - 2);
;             const char* a1 = cA + (size_t)(t + 1) * kstep;
;             const char* a2 = last ? nA : cA + (size_t)(t + 2) * kstep; const char* b2 = last ? nB : cB + (size_t)(t + 2) * kstep;
;             const char* a3 = a2 + kstep; const char* b3 = b2 + kstep;
;             if (last && has_next) S.a_ready(nxt);
;             if constexpr (SP2) {
;             PG8_LDB(B0, 0, 0); PG8_LDB(B1, 0, 1); PG8_SCHED; PG8_LDA(At, 0, 0); PG8_STAGE(PG8_SA(1, 1), a1 + hstepA, voffA);
;             PG8_WAIT_V(8); PG8_WAIT_L(0); PG8_BAR; PG8_MMA(0, 0, At, B0); PG8_MMA(0, 1, At, B1); PG8_BAR; PG8_SCHED;
;     ...
;         if (!Epi::SEGMENTED || cur.seg == 2)
; #pragma unroll
;         for (int a = 0; a < 2; ++a)
; #pragma unroll
;             for (int b = 0; b < 2; ++b)
; #pragma unroll
;                 for (int m = 0; m < 4; ++m)
; #pragma unroll
;                     for (int n = 0; n < 2; ++n) acc[a][b][m][n] = (f32x4){0.f, 0.f, 0.f, 0.f};
;         cur = nxt; cA = nA; cB = nB; ++ui;
.LBB0_1152:
	s_ashr_i32 s49, s48, 31
	s_lshl_b64 s[10:11], s[48:49], 20
	s_add_u32 s50, s60, s10
	s_addc_u32 s51, s61, s11
	s_and_b64 s[10:11], s[38:39], exec
	s_cselect_b32 s6, s51, s27
	s_cselect_b32 s10, s50, s26
	s_ashr_i32 s19, s18, 31
	s_lshl_b64 s[12:13], s[18:19], 20
	s_add_u32 s52, s62, s12
	s_addc_u32 s53, s63, s13
	s_and_b64 s[12:13], s[38:39], exec
	s_cselect_b32 s11, s53, s41
	s_cselect_b32 s12, s52, s40
	s_add_u32 s26, s26, 0x80080
	s_addc_u32 s27, s27, 0
	s_add_u32 s13, s40, 0x100
	v_mov_b32_e32 v2, 0
	s_addc_u32 s15, s41, 0
	s_mov_b32 s19, -2
	v_mov_b32_e32 v3, v2
	v_mov_b64_e32 v[4:5], 0
	v_mov_b64_e32 v[6:7], 0
	v_mov_b64_e32 v[8:9], 0
	v_mov_b64_e32 v[10:11], 0
	v_mov_b64_e32 v[12:13], 0
	v_mov_b64_e32 v[14:15], 0
	v_mov_b64_e32 v[16:17], 0
	v_mov_b64_e32 v[18:19], 0
	v_mov_b64_e32 v[20:21], 0
	v_mov_b64_e32 v[22:23], 0
	v_mov_b64_e32 v[24:25], 0
	v_mov_b64_e32 v[26:27], 0
	v_mov_b64_e32 v[28:29], 0
	v_mov_b64_e32 v[30:31], 0
	v_mov_b64_e32 v[32:33], 0
	v_mov_b64_e32 v[36:37], 0
	v_mov_b64_e32 v[38:39], 0
	v_mov_b64_e32 v[40:41], 0
	v_mov_b64_e32 v[42:43], 0
	v_mov_b64_e32 v[44:45], 0
	v_mov_b64_e32 v[46:47], 0
	v_mov_b64_e32 v[48:49], 0
	v_mov_b64_e32 v[50:51], 0
	v_mov_b64_e32 v[52:53], 0
	v_mov_b64_e32 v[54:55], 0
	v_mov_b64_e32 v[56:57], 0
	v_mov_b64_e32 v[58:59], 0
	v_mov_b64_e32 v[60:61], 0
	v_mov_b64_e32 v[62:63], 0
	v_mov_b64_e32 v[64:65], 0
	v_mov_b64_e32 v[66:67], 0
	v_mov_b64_e32 v[68:69], 0
	v_mov_b64_e32 v[70:71], 0
	v_mov_b64_e32 v[72:73], 0
	v_mov_b64_e32 v[74:75], 0
	v_mov_b64_e32 v[76:77], 0
	v_mov_b64_e32 v[78:79], 0
	v_mov_b64_e32 v[80:81], 0
	v_mov_b64_e32 v[82:83], 0
	v_mov_b64_e32 v[84:85], 0
	v_mov_b64_e32 v[86:87], 0
	v_mov_b64_e32 v[88:89], 0
	v_mov_b64_e32 v[90:91], 0
	v_mov_b64_e32 v[92:93], 0
	v_mov_b64_e32 v[94:95], 0
	v_mov_b64_e32 v[96:97], 0
	v_mov_b64_e32 v[98:99], 0
	v_mov_b64_e32 v[100:101], 0
	v_mov_b64_e32 v[102:103], 0
	v_mov_b64_e32 v[104:105], 0
	v_mov_b64_e32 v[106:107], 0
	v_mov_b64_e32 v[108:109], 0
	v_mov_b64_e32 v[110:111], 0
	v_mov_b64_e32 v[112:113], 0
	v_mov_b64_e32 v[114:115], 0
	v_mov_b64_e32 v[116:117], 0
	v_mov_b64_e32 v[118:119], 0
	v_mov_b64_e32 v[120:121], 0
	v_mov_b64_e32 v[122:123], 0
	v_mov_b64_e32 v[124:125], 0
	v_mov_b64_e32 v[126:127], 0
	v_mov_b64_e32 v[128:129], 0
	v_mov_b64_e32 v[130:131], 0
.LBB0_1153:
	s_add_u32 s34, s26, 0xfff80080
	s_addc_u32 s35, s27, -1
	s_add_i32 s37, 0, 0x10000
	s_cmp_eq_u32 s19, 28
	s_cselect_b32 s57, s6, s35
	s_cselect_b32 s56, s10, s34
	v_add_u32_e32 v34, s37, v155
	s_cselect_b32 s41, s11, s15
	s_cselect_b32 s40, s12, s13
	s_add_i32 s49, 0, 0x14000
	ds_read_b128 v[132:135], v34
	ds_read_b128 v[136:139], v34 offset:1024
	s_waitcnt vmcnt(0)
	ds_read_b128 v[158:161], v34 offset:2048
	ds_read_b128 v[186:189], v34 offset:3072
	v_add_u32_e32 v34, s49, v155
	ds_read_b128 v[190:193], v34
	ds_read_b128 v[194:197], v34 offset:1024
	ds_read_b128 v[198:201], v34 offset:2048
	ds_read_b128 v[202:205], v34 offset:3072
	v_lshl_add_u64 v[162:163], s[26:27], 0, v[150:151]
	s_add_i32 m0, s8, 0xc000
	ds_read_b128 v[206:209], v157
	ds_read_b128 v[210:213], v157 offset:1024
	ds_read_b128 v[214:217], v157 offset:2048
	ds_read_b128 v[218:221], v157 offset:3072
	ds_read_b128 v[222:225], v157 offset:4096
	ds_read_b128 v[234:237], v157 offset:5120
	ds_read_b128 v[238:241], v157 offset:6144
	ds_read_b128 v[242:245], v157 offset:7168
	global_load_lds_dwordx4 v[162:163], off
	v_lshl_add_u64 v[162:163], s[26:27], 0, v[152:153]
	s_add_i32 m0, s8, 0xe000
	s_nop 0
	global_load_lds_dwordx4 v[162:163], off
	s_waitcnt vmcnt(8)
	s_waitcnt lgkmcnt(0)
	s_barrier
	s_setprio 1
	v_mfma_f32_16x16x32_bf16 v[128:131], v[132:135], v[206:209], v[128:131]
	v_mfma_f32_16x16x32_bf16 v[124:127], v[158:161], v[206:209], v[124:127]
	v_mfma_f32_16x16x32_bf16 v[112:115], v[132:135], v[214:217], v[112:115]
	v_mfma_f32_16x16x32_bf16 v[108:111], v[158:161], v[214:217], v[108:111]
	v_mfma_f32_16x16x32_bf16 v[96:99], v[132:135], v[222:225], v[96:99]
	v_mfma_f32_16x16x32_bf16 v[92:95], v[158:161], v[222:225], v[92:95]
	v_mfma_f32_16x16x32_bf16 v[80:83], v[132:135], v[238:241], v[80:83]
	v_mfma_f32_16x16x32_bf16 v[76:79], v[158:161], v[238:241], v[76:79]
	v_mfma_f32_16x16x32_bf16 v[128:131], v[136:139], v[210:213], v[128:131]
	v_mfma_f32_16x16x32_bf16 v[124:127], v[186:189], v[210:213], v[124:127]
	v_mfma_f32_16x16x32_bf16 v[112:115], v[136:139], v[218:221], v[112:115]
	v_mfma_f32_16x16x32_bf16 v[108:111], v[186:189], v[218:221], v[108:111]
	v_mfma_f32_16x16x32_bf16 v[96:99], v[136:139], v[234:237], v[96:99]
	v_mfma_f32_16x16x32_bf16 v[92:95], v[186:189], v[234:237], v[92:95]
	v_mfma_f32_16x16x32_bf16 v[80:83], v[136:139], v[242:245], v[80:83]
	v_mfma_f32_16x16x32_bf16 v[76:79], v[186:189], v[242:245], v[76:79]
	v_mfma_f32_16x16x32_bf16 v[120:123], v[190:193], v[206:209], v[120:123]
	v_mfma_f32_16x16x32_bf16 v[116:119], v[198:201], v[206:209], v[116:119]
	v_mfma_f32_16x16x32_bf16 v[104:107], v[190:193], v[214:217], v[104:107]
	v_mfma_f32_16x16x32_bf16 v[100:103], v[198:201], v[214:217], v[100:103]
	v_mfma_f32_16x16x32_bf16 v[88:91], v[190:193], v[222:225], v[88:91]
	v_mfma_f32_16x16x32_bf16 v[84:87], v[198:201], v[222:225], v[84:87]
	v_mfma_f32_16x16x32_bf16 v[72:75], v[190:193], v[238:241], v[72:75]
	v_mfma_f32_16x16x32_bf16 v[68:71], v[198:201], v[238:241], v[68:71]
	v_mfma_f32_16x16x32_bf16 v[120:123], v[194:197], v[210:213], v[120:123]
	v_mfma_f32_16x16x32_bf16 v[116:119], v[202:205], v[210:213], v[116:119]
	v_mfma_f32_16x16x32_bf16 v[104:107], v[194:197], v[218:221], v[104:107]
	v_mfma_f32_16x16x32_bf16 v[100:103], v[202:205], v[218:221], v[100:103]
	v_mfma_f32_16x16x32_bf16 v[88:91], v[194:197], v[234:237], v[88:91]
	v_mfma_f32_16x16x32_bf16 v[84:87], v[202:205], v[234:237], v[84:87]
	v_mfma_f32_16x16x32_bf16 v[72:75], v[194:197], v[242:245], v[72:75]
	v_mfma_f32_16x16x32_bf16 v[68:71], v[202:205], v[242:245], v[68:71]
	s_setprio 0
	s_barrier
; #define PG8_STAGE(bufoff, gbase, voff) do { _Pragma("unroll") for (int _i = 0; _i < 2; ++_i) \
;         __builtin_amdgcn_global_load_lds((const unsigned*)((const char*)(gbase) + (voff)[_i]), (PG8_LAS unsigned*)(lds + (bufoff) + ldsw + _i * 8192), 16, 0, 0); } while (0)
; #define PG8_LDA(dst, b, h) do { _Pragma("unroll") for (int m = 0; m < 4; ++m) _Pragma("unroll") for (int k = 0; k < 2; ++k) dst[m][k] = *(const PG8_LAS bf16x8*)(lds + PG8_SA(b, h) + aoff + m * 2048 + k * 1024); } while (0)
; #define PG8_LDB(dst, b, h) do { _Pragma("unroll") for (int n = 0; n < 2; ++n) _Pragma("unroll") for (int k = 0; k < 2; ++k) dst[n][k] = *(const PG8_LAS bf16x8*)(lds + PG8_SB(b, h) + boff + n * 2048 + k * 1024); } while (0)
; #define PG8_WAIT_V(n) asm volatile("s_waitcnt vmcnt(" #n ")" ::: "memory")
; #define PG8_WAIT_L(n) asm volatile("s_waitcnt lgkmcnt(" #n ")" ::: "memory")
; #define PG8_BAR __builtin_amdgcn_s_barrier()
; #define PG8_SCHED __builtin_amdgcn_sched_barrier(0)
;     ...
;             PG8_LDA(At, 0, 1); PG8_STAGE(PG8_SB(0, 0), b2, voffB); PG8_STAGE(PG8_SB(0, 1), b2 + hstepB, voffB); PG8_STAGE(PG8_SA(0, 0), a2, voffA);
;             PG8_WAIT_V(8); PG8_WAIT_L(0); PG8_BAR; PG8_MMA(1, 0, At, B0); PG8_MMA(1, 1, At, B1); PG8_BAR; PG8_SCHED;
;             PG8_LDB(B0, 1, 0); PG8_LDB(B1, 1, 1); PG8_SCHED; PG8_LDA(At, 1, 0); PG8_STAGE(PG8_SA(0, 1), a2 + hstepA, voffA);
;             PG8_WAIT_V(8); PG8_WAIT_L(0); PG8_BAR; PG8_MMA(0, 0, At, B0); PG8_MMA(0, 1, At, B1); PG8_BAR; PG8_SCHED;
	s_add_i32 s34, s37, s7
	v_lshl_add_u64 v[162:163], s[40:41], 0, v[142:143]
	s_mov_b32 m0, s34
	ds_read_b128 v[206:209], v157 offset:16384
	ds_read_b128 v[210:213], v157 offset:17408
	ds_read_b128 v[214:217], v157 offset:18432
	ds_read_b128 v[218:221], v157 offset:19456
	ds_read_b128 v[222:225], v157 offset:20480
	ds_read_b128 v[234:237], v157 offset:21504
	ds_read_b128 v[238:241], v157 offset:22528
	ds_read_b128 v[242:245], v157 offset:23552
	global_load_lds_dwordx4 v[162:163], off
	s_add_i32 m0, s34, 0x2000
	s_add_u32 s34, s40, 0x80000
	v_lshl_add_u64 v[226:227], s[40:41], 0, v[146:147]
	s_addc_u32 s35, s41, 0
	s_add_i32 s37, s49, s7
	global_load_lds_dwordx4 v[226:227], off
	v_lshl_add_u64 v[246:247], s[34:35], 0, v[142:143]
	s_mov_b32 m0, s37
	v_lshl_add_u64 v[248:249], s[56:57], 0, v[144:145]
	global_load_lds_dwordx4 v[246:247], off
	v_lshl_add_u64 v[246:247], s[34:35], 0, v[146:147]
	s_add_i32 m0, s37, 0x2000
	s_nop 0
	global_load_lds_dwordx4 v[246:247], off
	v_lshl_add_u64 v[246:247], s[56:57], 0, v[140:141]
	s_mov_b32 m0, s8
	s_nop 0
	global_load_lds_dwordx4 v[246:247], off
	s_mov_b32 m0, s9
	s_nop 0
	global_load_lds_dwordx4 v[248:249], off
	s_waitcnt vmcnt(8)
	s_waitcnt lgkmcnt(0)
	s_barrier
	s_setprio 1
	v_mfma_f32_16x16x32_bf16 v[64:67], v[132:135], v[206:209], v[64:67]
	v_mfma_f32_16x16x32_bf16 v[60:63], v[158:161], v[206:209], v[60:63]
	v_mfma_f32_16x16x32_bf16 v[48:51], v[132:135], v[214:217], v[48:51]
	v_mfma_f32_16x16x32_bf16 v[44:47], v[158:161], v[214:217], v[44:47]
	v_mfma_f32_16x16x32_bf16 v[30:33], v[132:135], v[222:225], v[30:33]
	v_mfma_f32_16x16x32_bf16 v[26:29], v[158:161], v[222:225], v[26:29]
	v_mfma_f32_16x16x32_bf16 v[14:17], v[132:135], v[238:241], v[14:17]
	v_mfma_f32_16x16x32_bf16 v[10:13], v[158:161], v[238:241], v[10:13]
	v_mfma_f32_16x16x32_bf16 v[64:67], v[136:139], v[210:213], v[64:67]
	v_mfma_f32_16x16x32_bf16 v[60:63], v[186:189], v[210:213], v[60:63]
	v_mfma_f32_16x16x32_bf16 v[48:51], v[136:139], v[218:221], v[48:51]
	v_mfma_f32_16x16x32_bf16 v[44:47], v[186:189], v[218:221], v[44:47]
	v_mfma_f32_16x16x32_bf16 v[30:33], v[136:139], v[234:237], v[30:33]
	v_mfma_f32_16x16x32_bf16 v[26:29], v[186:189], v[234:237], v[26:29]
	v_mfma_f32_16x16x32_bf16 v[14:17], v[136:139], v[242:245], v[14:17]
	v_mfma_f32_16x16x32_bf16 v[10:13], v[186:189], v[242:245], v[10:13]
	v_mfma_f32_16x16x32_bf16 v[56:59], v[190:193], v[206:209], v[56:59]
	v_mfma_f32_16x16x32_bf16 v[52:55], v[198:201], v[206:209], v[52:55]
	v_mfma_f32_16x16x32_bf16 v[40:43], v[190:193], v[214:217], v[40:43]
	v_mfma_f32_16x16x32_bf16 v[36:39], v[198:201], v[214:217], v[36:39]
	v_mfma_f32_16x16x32_bf16 v[22:25], v[190:193], v[222:225], v[22:25]
	v_mfma_f32_16x16x32_bf16 v[18:21], v[198:201], v[222:225], v[18:21]
	v_mfma_f32_16x16x32_bf16 v[6:9], v[190:193], v[238:241], v[6:9]
	v_mfma_f32_16x16x32_bf16 v[2:5], v[198:201], v[238:241], v[2:5]
	v_mfma_f32_16x16x32_bf16 v[56:59], v[194:197], v[210:213], v[56:59]
	v_mfma_f32_16x16x32_bf16 v[52:55], v[202:205], v[210:213], v[52:55]
	v_mfma_f32_16x16x32_bf16 v[40:43], v[194:197], v[218:221], v[40:43]
	v_mfma_f32_16x16x32_bf16 v[36:39], v[202:205], v[218:221], v[36:39]
	v_mfma_f32_16x16x32_bf16 v[22:25], v[194:197], v[234:237], v[22:25]
	v_mfma_f32_16x16x32_bf16 v[18:21], v[202:205], v[234:237], v[18:21]
	v_mfma_f32_16x16x32_bf16 v[6:9], v[194:197], v[242:245], v[6:9]
	v_mfma_f32_16x16x32_bf16 v[2:5], v[202:205], v[242:245], v[2:5]
	s_setprio 0
	s_barrier
	s_add_i32 s37, 0, 0x18000
	v_add_u32_e32 v34, s37, v155
	s_add_i32 s49, 0, 0x1c000
	ds_read_b128 v[132:135], v34
	ds_read_b128 v[136:139], v34 offset:1024
	ds_read_b128 v[158:161], v34 offset:2048
	ds_read_b128 v[186:189], v34 offset:3072
	v_add_u32_e32 v34, s49, v155
	ds_read_b128 v[190:193], v34
	ds_read_b128 v[194:197], v34 offset:1024
	ds_read_b128 v[198:201], v34 offset:2048
	ds_read_b128 v[202:205], v34 offset:3072
	s_add_u32 s34, s56, 0x80000
	s_addc_u32 s35, s57, 0
	s_mov_b32 m0, s58
	v_lshl_add_u64 v[250:251], s[34:35], 0, v[140:141]
	ds_read_b128 v[206:209], v157 offset:32768
	ds_read_b128 v[210:213], v157 offset:33792
	ds_read_b128 v[214:217], v157 offset:34816
	ds_read_b128 v[218:221], v157 offset:35840
	ds_read_b128 v[222:225], v157 offset:36864
	ds_read_b128 v[234:237], v157 offset:37888
	ds_read_b128 v[238:241], v157 offset:38912
	ds_read_b128 v[242:245], v157 offset:39936
	global_load_lds_dwordx4 v[250:251], off
	v_lshl_add_u64 v[250:251], s[34:35], 0, v[144:145]
	s_mov_b32 m0, s59
	s_nop 0
	global_load_lds_dwordx4 v[250:251], off
	s_waitcnt vmcnt(8)
	s_waitcnt lgkmcnt(0)
	s_barrier
; #define PG8_STAGE(bufoff, gbase, voff) do { _Pragma("unroll") for (int _i = 0; _i < 2; ++_i) \
;         __builtin_amdgcn_global_load_lds((const unsigned*)((const char*)(gbase) + (voff)[_i]), (PG8_LAS unsigned*)(lds + (bufoff) + ldsw + _i * 8192), 16, 0, 0); } while (0)
; #define PG8_LDA(dst, b, h) do { _Pragma("unroll") for (int m = 0; m < 4; ++m) _Pragma("unroll") for (int k = 0; k < 2; ++k) dst[m][k] = *(const PG8_LAS bf16x8*)(lds + PG8_SA(b, h) + aoff + m * 2048 + k * 1024); } while (0)
; #define PG8_WAIT_V(n) asm volatile("s_waitcnt vmcnt(" #n ")" ::: "memory")
; #define PG8_WAIT_L(n) asm volatile("s_waitcnt lgkmcnt(" #n ")" ::: "memory")
; #define PG8_BAR __builtin_amdgcn_s_barrier()
; #define PG8_SCHED __builtin_amdgcn_sched_barrier(0)
;     ...
;             PG8_WAIT_V(8); PG8_WAIT_L(0); PG8_BAR; PG8_MMA(0, 0, At, B0); PG8_MMA(0, 1, At, B1); PG8_BAR; PG8_SCHED;
;             PG8_LDA(At, 1, 1); PG8_STAGE(PG8_SB(1, 0), b3, voffB); PG8_STAGE(PG8_SB(1, 1), b3 + hstepB, voffB); PG8_STAGE(PG8_SA(1, 0), a3, voffA);
;             PG8_WAIT_V(8); PG8_WAIT_L(0); PG8_BAR; PG8_MMA(1, 0, At, B0); PG8_MMA(1, 1, At, B1); PG8_BAR; PG8_SCHED;
;     ...
;         if constexpr (ALIGN_EPI) { if (wr == 0) PG8_BAR; }
;         if constexpr (Q8 == 1) asm volatile("s_nop 15\n\ts_nop 15" ::: "memory");
;         if constexpr (!Epi::AFTER_DRAIN) { E(acc, cur, wr, wc, fr, fq); S.done(cur); }
;         if (!has_next) break;
	s_setprio 1
	v_mfma_f32_16x16x32_bf16 v[128:131], v[132:135], v[206:209], v[128:131]
	v_mfma_f32_16x16x32_bf16 v[124:127], v[158:161], v[206:209], v[124:127]
	v_mfma_f32_16x16x32_bf16 v[112:115], v[132:135], v[214:217], v[112:115]
	v_mfma_f32_16x16x32_bf16 v[108:111], v[158:161], v[214:217], v[108:111]
	v_mfma_f32_16x16x32_bf16 v[96:99], v[132:135], v[222:225], v[96:99]
	v_mfma_f32_16x16x32_bf16 v[92:95], v[158:161], v[222:225], v[92:95]
	v_mfma_f32_16x16x32_bf16 v[80:83], v[132:135], v[238:241], v[80:83]
	v_mfma_f32_16x16x32_bf16 v[76:79], v[158:161], v[238:241], v[76:79]
	v_mfma_f32_16x16x32_bf16 v[128:131], v[136:139], v[210:213], v[128:131]
	v_mfma_f32_16x16x32_bf16 v[124:127], v[186:189], v[210:213], v[124:127]
	v_mfma_f32_16x16x32_bf16 v[112:115], v[136:139], v[218:221], v[112:115]
	v_mfma_f32_16x16x32_bf16 v[108:111], v[186:189], v[218:221], v[108:111]
	v_mfma_f32_16x16x32_bf16 v[96:99], v[136:139], v[234:237], v[96:99]
	v_mfma_f32_16x16x32_bf16 v[92:95], v[186:189], v[234:237], v[92:95]
	v_mfma_f32_16x16x32_bf16 v[80:83], v[136:139], v[242:245], v[80:83]
	v_mfma_f32_16x16x32_bf16 v[76:79], v[186:189], v[242:245], v[76:79]
	v_mfma_f32_16x16x32_bf16 v[120:123], v[190:193], v[206:209], v[120:123]
	v_mfma_f32_16x16x32_bf16 v[116:119], v[198:201], v[206:209], v[116:119]
	v_mfma_f32_16x16x32_bf16 v[104:107], v[190:193], v[214:217], v[104:107]
	v_mfma_f32_16x16x32_bf16 v[100:103], v[198:201], v[214:217], v[100:103]
	v_mfma_f32_16x16x32_bf16 v[88:91], v[190:193], v[222:225], v[88:91]
	v_mfma_f32_16x16x32_bf16 v[84:87], v[198:201], v[222:225], v[84:87]
	v_mfma_f32_16x16x32_bf16 v[72:75], v[190:193], v[238:241], v[72:75]
	v_mfma_f32_16x16x32_bf16 v[68:71], v[198:201], v[238:241], v[68:71]
	v_mfma_f32_16x16x32_bf16 v[120:123], v[194:197], v[210:213], v[120:123]
	v_mfma_f32_16x16x32_bf16 v[116:119], v[202:205], v[210:213], v[116:119]
	v_mfma_f32_16x16x32_bf16 v[104:107], v[194:197], v[218:221], v[104:107]
	v_mfma_f32_16x16x32_bf16 v[100:103], v[202:205], v[218:221], v[100:103]
	v_mfma_f32_16x16x32_bf16 v[88:91], v[194:197], v[234:237], v[88:91]
	v_mfma_f32_16x16x32_bf16 v[84:87], v[202:205], v[234:237], v[84:87]
	v_mfma_f32_16x16x32_bf16 v[72:75], v[194:197], v[242:245], v[72:75]
	v_mfma_f32_16x16x32_bf16 v[68:71], v[202:205], v[242:245], v[68:71]
	s_setprio 0
	s_barrier
	s_add_i32 s34, s37, s7
	v_lshl_add_u64 v[162:163], v[162:163], 0, s[22:23]
	s_mov_b32 m0, s34
	ds_read_b128 v[206:209], v157 offset:49152
	ds_read_b128 v[210:213], v157 offset:50176
	ds_read_b128 v[214:217], v157 offset:51200
	ds_read_b128 v[218:221], v157 offset:52224
	ds_read_b128 v[222:225], v157 offset:53248
	ds_read_b128 v[234:237], v157 offset:54272
	ds_read_b128 v[238:241], v157 offset:55296
	ds_read_b128 v[242:245], v157 offset:56320
	global_load_lds_dwordx4 v[162:163], off
	s_add_i32 m0, s34, 0x2000
	s_add_u32 s34, s40, 0x80080
	v_lshl_add_u64 v[162:163], v[226:227], 0, s[22:23]
	s_addc_u32 s35, s41, 0
	s_add_i32 s37, s49, s7
	global_load_lds_dwordx4 v[162:163], off
	v_lshl_add_u64 v[162:163], s[34:35], 0, v[142:143]
	s_mov_b32 m0, s37
	s_nop 0
	global_load_lds_dwordx4 v[162:163], off
	v_lshl_add_u64 v[162:163], s[34:35], 0, v[146:147]
	s_add_i32 m0, s37, 0x2000
	s_nop 0
	global_load_lds_dwordx4 v[162:163], off
	v_lshl_add_u64 v[162:163], v[246:247], 0, s[22:23]
	s_mov_b32 m0, s66
	s_nop 0
	global_load_lds_dwordx4 v[162:163], off
	v_lshl_add_u64 v[162:163], v[248:249], 0, s[22:23]
	s_mov_b32 m0, s67
	s_nop 0
	global_load_lds_dwordx4 v[162:163], off
	s_waitcnt vmcnt(8)
	s_waitcnt lgkmcnt(0)
	s_barrier
	s_setprio 1
	v_mfma_f32_16x16x32_bf16 v[64:67], v[132:135], v[206:209], v[64:67]
	v_mfma_f32_16x16x32_bf16 v[60:63], v[158:161], v[206:209], v[60:63]
	v_mfma_f32_16x16x32_bf16 v[48:51], v[132:135], v[214:217], v[48:51]
	v_mfma_f32_16x16x32_bf16 v[44:47], v[158:161], v[214:217], v[44:47]
	v_mfma_f32_16x16x32_bf16 v[30:33], v[132:135], v[222:225], v[30:33]
	v_mfma_f32_16x16x32_bf16 v[26:29], v[158:161], v[222:225], v[26:29]
	v_mfma_f32_16x16x32_bf16 v[14:17], v[132:135], v[238:241], v[14:17]
	v_mfma_f32_16x16x32_bf16 v[10:13], v[158:161], v[238:241], v[10:13]
	v_mfma_f32_16x16x32_bf16 v[64:67], v[136:139], v[210:213], v[64:67]
	v_mfma_f32_16x16x32_bf16 v[60:63], v[186:189], v[210:213], v[60:63]
	v_mfma_f32_16x16x32_bf16 v[48:51], v[136:139], v[218:221], v[48:51]
	v_mfma_f32_16x16x32_bf16 v[44:47], v[186:189], v[218:221], v[44:47]
	v_mfma_f32_16x16x32_bf16 v[30:33], v[136:139], v[234:237], v[30:33]
	v_mfma_f32_16x16x32_bf16 v[26:29], v[186:189], v[234:237], v[26:29]
	v_mfma_f32_16x16x32_bf16 v[14:17], v[136:139], v[242:245], v[14:17]
	v_mfma_f32_16x16x32_bf16 v[10:13], v[186:189], v[242:245], v[10:13]
	v_mfma_f32_16x16x32_bf16 v[56:59], v[190:193], v[206:209], v[56:59]
	v_mfma_f32_16x16x32_bf16 v[52:55], v[198:201], v[206:209], v[52:55]
	v_mfma_f32_16x16x32_bf16 v[40:43], v[190:193], v[214:217], v[40:43]
	v_mfma_f32_16x16x32_bf16 v[36:39], v[198:201], v[214:217], v[36:39]
	v_mfma_f32_16x16x32_bf16 v[22:25], v[190:193], v[222:225], v[22:25]
	v_mfma_f32_16x16x32_bf16 v[18:21], v[198:201], v[222:225], v[18:21]
	v_mfma_f32_16x16x32_bf16 v[6:9], v[190:193], v[238:241], v[6:9]
	v_mfma_f32_16x16x32_bf16 v[2:5], v[198:201], v[238:241], v[2:5]
	v_mfma_f32_16x16x32_bf16 v[56:59], v[194:197], v[210:213], v[56:59]
	v_mfma_f32_16x16x32_bf16 v[52:55], v[202:205], v[210:213], v[52:55]
	v_mfma_f32_16x16x32_bf16 v[40:43], v[194:197], v[218:221], v[40:43]
	v_mfma_f32_16x16x32_bf16 v[36:39], v[202:205], v[218:221], v[36:39]
	v_mfma_f32_16x16x32_bf16 v[22:25], v[194:197], v[234:237], v[22:25]
	v_mfma_f32_16x16x32_bf16 v[18:21], v[202:205], v[234:237], v[18:21]
	v_mfma_f32_16x16x32_bf16 v[6:9], v[194:197], v[242:245], v[6:9]
	v_mfma_f32_16x16x32_bf16 v[2:5], v[202:205], v[242:245], v[2:5]
	s_setprio 0
	s_barrier
	s_add_i32 s19, s19, 2
	s_add_u32 s26, s26, 0x100
	s_addc_u32 s27, s27, 0
	s_add_u32 s13, s13, 0x100
	s_addc_u32 s15, s15, 0
	s_cmp_gt_u32 s19, 29
	s_cbranch_scc0 .LBB0_1153
	s_and_b64 vcc, exec, s[46:47]
	s_cbranch_vccz .LBB0_1156
	s_barrier

;     __device__ __forceinline__ const char* pa(const Gemm& g, const Unit& u, size_t tstep) const { return (const char*)g.A + (size_t)u.pm * tstep; }
;     __device__ __forceinline__ const char* pb(const Gemm& g, const Unit& u, size_t tstep) const { return (const char*)g.Bt + (size_t)u.pn * tstep; }
;     __device__ __forceinline__ const char* pa(const Gemm& g, const Unit& u, size_t tstep) const { return (const char*)g.A + (size_t)(u.pn >> 1) * 512 + (size_t)u.pm * tstep; }
;     __device__ __forceinline__ bool next(int i, Unit& u) const { const int ti = i / 3, sg = i - 3 * ti; if (!StaticOrder::next(ti, u)) return false; u.seg = sg; return true; }
;     __device__ __forceinline__ const char* pa(const Gemm& g, const Unit& u, size_t tstep) const { return (const char*)g.A + (size_t)u.seg * astride + (size_t)u.pm * tstep; }
;     __device__ __forceinline__ const char* pb(const Gemm& g, const Unit& u, size_t tstep) const { return (const char*)g.Bt + (size_t)u.seg * bstride + (size_t)u.pn * tstep; }
;     ...
;         const bool has_next = S.next(ui + 1, nxt);
;         const char* nA = has_next ? S.pa(g, nxt, tstepA) : cA; const char* nB = has_next ? S.pb(g, nxt, tstepB) : cB;
;         for (int t = 0; t < nt; t += 2) {
;             const bool last = (t == nt - 2);
;             const char* a1 = cA + (size_t)(t + 1) * kstep;
;             const char* a2 = last ? nA : cA + (size_t)(t + 2) * kstep; const char* b2 = last ? nB : cB + (size_t)(t + 2) * kstep;
;     ...
;         if (!Epi::SEGMENTED || cur.seg == 2)
; #pragma unroll
;         for (int a = 0; a < 2; ++a)
; #pragma unroll
;             for (int b = 0; b < 2; ++b)
; #pragma unroll
;                 for (int m = 0; m < 4; ++m)
; #pragma unroll
;                     for (int n = 0; n < 2; ++n) acc[a][b][m][n] = (f32x4){0.f, 0.f, 0.f, 0.f};
;         cur = nxt; cA = nA; cB = nB; ++ui;
.LBB0_1501:
	s_ashr_i32 s54, s66, 1
	s_ashr_i32 s55, s54, 31
	s_lshl_b64 s[54:55], s[54:55], 9
	s_add_u32 s68, s18, s54
	s_addc_u32 s70, s19, s55
	s_ashr_i32 s51, s50, 31
	s_lshl_b64 s[54:55], s[50:51], 19
	s_add_u32 s54, s68, s54
	v_mov_b32_e32 v147, 0
	s_addc_u32 s55, s70, s55
	s_andn2_b64 vcc, exec, s[46:47]
	v_mov_b32_e32 v146, v147
	v_mov_b32_e32 v145, v147
	v_mov_b32_e32 v144, v147
	v_mov_b32_e32 v143, v147
	v_mov_b32_e32 v142, v147
	v_mov_b32_e32 v141, v147
	v_mov_b32_e32 v140, v147
	v_mov_b32_e32 v123, v147
	v_mov_b32_e32 v122, v147
	v_mov_b32_e32 v121, v147
	v_mov_b32_e32 v120, v147
	v_mov_b32_e32 v119, v147
	v_mov_b32_e32 v118, v147
	v_mov_b32_e32 v117, v147
	v_mov_b32_e32 v116, v147
	v_mov_b32_e32 v99, v147
	v_mov_b32_e32 v98, v147
	v_mov_b32_e32 v97, v147
	v_mov_b32_e32 v96, v147
	v_mov_b32_e32 v95, v147
	v_mov_b32_e32 v94, v147
	v_mov_b32_e32 v93, v147
	v_mov_b32_e32 v92, v147
	v_mov_b32_e32 v83, v147
	v_mov_b32_e32 v82, v147
	v_mov_b32_e32 v81, v147
	v_mov_b32_e32 v80, v147
	v_mov_b32_e32 v79, v147
	v_mov_b32_e32 v78, v147
	v_mov_b32_e32 v77, v147
	v_mov_b32_e32 v76, v147
	v_mov_b32_e32 v139, v147
	v_mov_b32_e32 v138, v147
	v_mov_b32_e32 v137, v147
	v_mov_b32_e32 v136, v147
	v_mov_b32_e32 v135, v147
	v_mov_b32_e32 v134, v147
	v_mov_b32_e32 v133, v147
	v_mov_b32_e32 v132, v147
	v_mov_b32_e32 v107, v147
	v_mov_b32_e32 v106, v147
	v_mov_b32_e32 v105, v147
	v_mov_b32_e32 v104, v147
	v_mov_b32_e32 v103, v147
	v_mov_b32_e32 v102, v147
	v_mov_b32_e32 v101, v147
	v_mov_b32_e32 v100, v147
	v_mov_b32_e32 v91, v147
	v_mov_b32_e32 v90, v147
	v_mov_b32_e32 v89, v147
	v_mov_b32_e32 v88, v147
	v_mov_b32_e32 v87, v147
	v_mov_b32_e32 v86, v147
	v_mov_b32_e32 v85, v147
	v_mov_b32_e32 v84, v147
	v_mov_b32_e32 v75, v147
	v_mov_b32_e32 v74, v147
	v_mov_b32_e32 v73, v147
	v_mov_b32_e32 v72, v147
	v_mov_b32_e32 v71, v147
	v_mov_b32_e32 v70, v147
	v_mov_b32_e32 v69, v147
	v_mov_b32_e32 v68, v147
	v_mov_b32_e32 v67, v147
	v_mov_b32_e32 v66, v147
	v_mov_b32_e32 v65, v147
	v_mov_b32_e32 v64, v147
	v_mov_b32_e32 v63, v147
	v_mov_b32_e32 v62, v147
	v_mov_b32_e32 v61, v147
	v_mov_b32_e32 v60, v147
	v_mov_b32_e32 v51, v147
	v_mov_b32_e32 v50, v147
	v_mov_b32_e32 v49, v147
	v_mov_b32_e32 v48, v147
	v_mov_b32_e32 v47, v147
	v_mov_b32_e32 v46, v147
	v_mov_b32_e32 v45, v147
	v_mov_b32_e32 v44, v147
	v_mov_b32_e32 v33, v147
	v_mov_b32_e32 v32, v147
	v_mov_b32_e32 v31, v147
	v_mov_b32_e32 v30, v147
	v_mov_b32_e32 v29, v147
	v_mov_b32_e32 v28, v147
	v_mov_b32_e32 v27, v147
	v_mov_b32_e32 v26, v147
	v_mov_b32_e32 v17, v147
	v_mov_b32_e32 v16, v147
	v_mov_b32_e32 v15, v147
	v_mov_b32_e32 v14, v147
	v_mov_b32_e32 v13, v147
	v_mov_b32_e32 v12, v147
	v_mov_b32_e32 v11, v147
	v_mov_b32_e32 v10, v147
	v_mov_b32_e32 v59, v147
	v_mov_b32_e32 v58, v147
	v_mov_b32_e32 v57, v147
	v_mov_b32_e32 v56, v147
	v_mov_b32_e32 v55, v147
	v_mov_b32_e32 v54, v147
	v_mov_b32_e32 v53, v147
	v_mov_b32_e32 v52, v147
	v_mov_b32_e32 v43, v147
	v_mov_b32_e32 v42, v147
	v_mov_b32_e32 v41, v147
	v_mov_b32_e32 v40, v147
	v_mov_b32_e32 v39, v147
	v_mov_b32_e32 v38, v147
	v_mov_b32_e32 v37, v147
	v_mov_b32_e32 v36, v147
	v_mov_b32_e32 v25, v147
	v_mov_b32_e32 v24, v147
	v_mov_b32_e32 v23, v147
	v_mov_b32_e32 v22, v147
	v_mov_b32_e32 v21, v147
	v_mov_b32_e32 v20, v147
	v_mov_b32_e32 v19, v147
	v_mov_b32_e32 v18, v147
	v_mov_b32_e32 v9, v147
	v_mov_b32_e32 v8, v147
	v_mov_b32_e32 v7, v147
	v_mov_b32_e32 v6, v147
	v_mov_b32_e32 v5, v147
	v_mov_b32_e32 v4, v147
	v_mov_b32_e32 v3, v147
	v_mov_b32_e32 v2, v147
	s_cbranch_vccnz .LBB0_1505
	s_and_b64 s[40:41], s[40:41], exec
	s_cselect_b32 s51, s55, s61
	s_cselect_b32 s68, s54, s60
	s_add_u32 s40, s60, 0x40080
	s_addc_u32 s41, s61, 0
	s_add_u32 s60, s58, 0x100
	v_mov_b32_e32 v2, 0
	s_addc_u32 s61, s59, 0
	s_mov_b32 s58, 0
	v_mov_b32_e32 v3, v2
	v_mov_b64_e32 v[4:5], 0
	v_mov_b64_e32 v[6:7], 0
	v_mov_b64_e32 v[8:9], 0
	v_mov_b64_e32 v[10:11], 0
	v_mov_b64_e32 v[12:13], 0
	v_mov_b64_e32 v[14:15], 0
	v_mov_b64_e32 v[16:17], 0
	v_mov_b64_e32 v[18:19], 0
	v_mov_b64_e32 v[20:21], 0
	v_mov_b64_e32 v[22:23], 0
	v_mov_b64_e32 v[24:25], 0
	v_mov_b64_e32 v[26:27], 0
	v_mov_b64_e32 v[28:29], 0
	v_mov_b64_e32 v[30:31], 0
	v_mov_b64_e32 v[32:33], 0
	v_mov_b64_e32 v[36:37], 0
	v_mov_b64_e32 v[38:39], 0
	v_mov_b64_e32 v[40:41], 0
	v_mov_b64_e32 v[42:43], 0
	v_mov_b64_e32 v[44:45], 0
	v_mov_b64_e32 v[46:47], 0
	v_mov_b64_e32 v[48:49], 0
	v_mov_b64_e32 v[50:51], 0
	v_mov_b64_e32 v[52:53], 0
	v_mov_b64_e32 v[54:55], 0
	v_mov_b64_e32 v[56:57], 0
	v_mov_b64_e32 v[58:59], 0
	v_mov_b64_e32 v[60:61], 0
	v_mov_b64_e32 v[62:63], 0
	v_mov_b64_e32 v[64:65], 0
	v_mov_b64_e32 v[66:67], 0
	v_mov_b64_e32 v[68:69], 0
	v_mov_b64_e32 v[70:71], 0
	v_mov_b64_e32 v[72:73], 0
	v_mov_b64_e32 v[74:75], 0
	v_mov_b64_e32 v[76:77], 0
	v_mov_b64_e32 v[78:79], 0
	v_mov_b64_e32 v[80:81], 0
	v_mov_b64_e32 v[82:83], 0
	v_mov_b64_e32 v[84:85], 0
	v_mov_b64_e32 v[86:87], 0
	v_mov_b64_e32 v[88:89], 0
	v_mov_b64_e32 v[90:91], 0
	v_mov_b64_e32 v[92:93], 0
	v_mov_b64_e32 v[94:95], 0
	v_mov_b64_e32 v[96:97], 0
	v_mov_b64_e32 v[98:99], 0
	v_mov_b64_e32 v[100:101], 0
	v_mov_b64_e32 v[102:103], 0
	v_mov_b64_e32 v[104:105], 0
	v_mov_b64_e32 v[106:107], 0
	v_mov_b64_e32 v[116:117], 0
	v_mov_b64_e32 v[118:119], 0
	v_mov_b64_e32 v[120:121], 0
	v_mov_b64_e32 v[122:123], 0
	v_mov_b64_e32 v[132:133], 0
	v_mov_b64_e32 v[134:135], 0
	v_mov_b64_e32 v[136:137], 0
	v_mov_b64_e32 v[138:139], 0
	v_mov_b64_e32 v[140:141], 0
	v_mov_b64_e32 v[142:143], 0
	v_mov_b64_e32 v[144:145], 0
	v_mov_b64_e32 v[146:147], 0
; #define PG8_STAGE(bufoff, gbase, voff) do { _Pragma("unroll") for (int _i = 0; _i < 2; ++_i) \
;         __builtin_amdgcn_global_load_lds((const unsigned*)((const char*)(gbase) + (voff)[_i]), (PG8_LAS unsigned*)(lds + (bufoff) + ldsw + _i * 8192), 16, 0, 0); } while (0)
; #define PG8_LDA(dst, b, h) do { _Pragma("unroll") for (int m = 0; m < 4; ++m) _Pragma("unroll") for (int k = 0; k < 2; ++k) dst[m][k] = *(const PG8_LAS bf16x8*)(lds + PG8_SA(b, h) + aoff + m * 2048 + k * 1024); } while (0)
; #define PG8_LDB(dst, b, h) do { _Pragma("unroll") for (int n = 0; n < 2; ++n) _Pragma("unroll") for (int k = 0; k < 2; ++k) dst[n][k] = *(const PG8_LAS bf16x8*)(lds + PG8_SB(b, h) + boff + n * 2048 + k * 1024); } while (0)
; #define PG8_WAIT_V(n) asm volatile("s_waitcnt vmcnt(" #n ")" ::: "memory")
; #define PG8_WAIT_L(n) asm volatile("s_waitcnt lgkmcnt(" #n ")" ::: "memory")
; #define PG8_BAR __builtin_amdgcn_s_barrier()
; #define PG8_SCHED __builtin_amdgcn_sched_barrier(0)
;     ...
;             PG8_LDB(B0, 0, 0); PG8_LDB(B1, 0, 1); PG8_SCHED; PG8_LDA(At, 0, 0); PG8_STAGE(PG8_SA(1, 1), a1 + hstepA, voffA);
;             PG8_WAIT_V(8); PG8_WAIT_L(0); PG8_BAR; PG8_MMA(0, 0, At, B0); PG8_MMA(0, 1, At, B1); PG8_BAR; PG8_SCHED;
;             PG8_LDA(At, 0, 1); PG8_STAGE(PG8_SB(0, 0), b2, voffB); PG8_STAGE(PG8_SB(0, 1), b2 + hstepB, voffB); PG8_STAGE(PG8_SA(0, 0), a2, voffA);
;             PG8_WAIT_V(8); PG8_WAIT_L(0); PG8_BAR; PG8_MMA(1, 0, At, B0); PG8_MMA(1, 1, At, B1); PG8_BAR; PG8_SCHED;
.LBB0_1503:
	s_add_i32 s70, s58, 2
	s_add_u32 s71, s40, 0xfffc0080
	s_addc_u32 s59, s41, -1
	s_add_i32 s76, 0, 0x10000
	s_cmp_eq_u32 s63, s58
	s_cselect_b32 s59, s51, s59
	s_cselect_b32 s58, s68, s71
	s_cselect_b32 s75, s53, s61
	s_cselect_b32 s74, s52, s60
	s_add_i32 s71, 0, 0x14000
	v_add_u32_e32 v128, s76, v187
	v_add_u32_e32 v189, s71, v187
	ds_read_b128 v[108:111], v128
	ds_read_b128 v[112:115], v128 offset:1024
	ds_read_b128 v[124:127], v128 offset:2048
	ds_read_b128 v[128:131], v128 offset:3072
	ds_read_b128 v[160:163], v189
	ds_read_b128 v[190:193], v189 offset:1024
	ds_read_b128 v[194:197], v189 offset:2048
	ds_read_b128 v[198:201], v189 offset:3072
	v_lshl_add_u64 v[226:227], s[40:41], 0, v[156:157]
	s_add_i32 m0, s13, 0xc000
	ds_read_b128 v[202:205], v188
	ds_read_b128 v[206:209], v188 offset:1024
	ds_read_b128 v[210:213], v188 offset:2048
	ds_read_b128 v[214:217], v188 offset:3072
	ds_read_b128 v[218:221], v188 offset:4096
	ds_read_b128 v[222:225], v188 offset:5120
	ds_read_b128 v[234:237], v188 offset:6144
	ds_read_b128 v[238:241], v188 offset:7168
	global_load_lds_dwordx4 v[226:227], off
	v_lshl_add_u64 v[226:227], s[40:41], 0, v[158:159]
	s_add_i32 m0, s13, 0xe000
	s_nop 0
	global_load_lds_dwordx4 v[226:227], off
	s_waitcnt vmcnt(8)
	s_waitcnt lgkmcnt(0)
	s_barrier
	s_setprio 1
	v_mfma_f32_16x16x32_bf16 v[144:147], v[108:111], v[202:205], v[144:147]
	v_mfma_f32_16x16x32_bf16 v[140:143], v[124:127], v[202:205], v[140:143]
	v_mfma_f32_16x16x32_bf16 v[120:123], v[108:111], v[210:213], v[120:123]
	v_mfma_f32_16x16x32_bf16 v[116:119], v[124:127], v[210:213], v[116:119]
	v_mfma_f32_16x16x32_bf16 v[96:99], v[108:111], v[218:221], v[96:99]
	v_mfma_f32_16x16x32_bf16 v[92:95], v[124:127], v[218:221], v[92:95]
	v_mfma_f32_16x16x32_bf16 v[80:83], v[108:111], v[234:237], v[80:83]
	v_mfma_f32_16x16x32_bf16 v[76:79], v[124:127], v[234:237], v[76:79]
	v_mfma_f32_16x16x32_bf16 v[144:147], v[112:115], v[206:209], v[144:147]
	v_mfma_f32_16x16x32_bf16 v[140:143], v[128:131], v[206:209], v[140:143]
	v_mfma_f32_16x16x32_bf16 v[120:123], v[112:115], v[214:217], v[120:123]
	v_mfma_f32_16x16x32_bf16 v[116:119], v[128:131], v[214:217], v[116:119]
	v_mfma_f32_16x16x32_bf16 v[96:99], v[112:115], v[222:225], v[96:99]
	v_mfma_f32_16x16x32_bf16 v[92:95], v[128:131], v[222:225], v[92:95]
	v_mfma_f32_16x16x32_bf16 v[80:83], v[112:115], v[238:241], v[80:83]
	v_mfma_f32_16x16x32_bf16 v[76:79], v[128:131], v[238:241], v[76:79]
	v_mfma_f32_16x16x32_bf16 v[136:139], v[160:163], v[202:205], v[136:139]
	v_mfma_f32_16x16x32_bf16 v[132:135], v[194:197], v[202:205], v[132:135]
	v_mfma_f32_16x16x32_bf16 v[104:107], v[160:163], v[210:213], v[104:107]
	v_mfma_f32_16x16x32_bf16 v[100:103], v[194:197], v[210:213], v[100:103]
	v_mfma_f32_16x16x32_bf16 v[88:91], v[160:163], v[218:221], v[88:91]
	v_mfma_f32_16x16x32_bf16 v[84:87], v[194:197], v[218:221], v[84:87]
	v_mfma_f32_16x16x32_bf16 v[72:75], v[160:163], v[234:237], v[72:75]
	v_mfma_f32_16x16x32_bf16 v[68:71], v[194:197], v[234:237], v[68:71]
	v_mfma_f32_16x16x32_bf16 v[136:139], v[190:193], v[206:209], v[136:139]
	v_mfma_f32_16x16x32_bf16 v[132:135], v[198:201], v[206:209], v[132:135]
	v_mfma_f32_16x16x32_bf16 v[104:107], v[190:193], v[214:217], v[104:107]
	v_mfma_f32_16x16x32_bf16 v[100:103], v[198:201], v[214:217], v[100:103]
	v_mfma_f32_16x16x32_bf16 v[88:91], v[190:193], v[222:225], v[88:91]
	v_mfma_f32_16x16x32_bf16 v[84:87], v[198:201], v[222:225], v[84:87]
	v_mfma_f32_16x16x32_bf16 v[72:75], v[190:193], v[238:241], v[72:75]
	v_mfma_f32_16x16x32_bf16 v[68:71], v[198:201], v[238:241], v[68:71]
	s_setprio 0
	s_barrier
	s_add_i32 s76, s76, s12
	v_lshl_add_u64 v[226:227], s[74:75], 0, v[34:35]
	s_mov_b32 m0, s76
	ds_read_b128 v[202:205], v188 offset:16384
	ds_read_b128 v[206:209], v188 offset:17408
	ds_read_b128 v[210:213], v188 offset:18432
	ds_read_b128 v[214:217], v188 offset:19456
	ds_read_b128 v[218:221], v188 offset:20480
	ds_read_b128 v[222:225], v188 offset:21504
	ds_read_b128 v[234:237], v188 offset:22528
	ds_read_b128 v[238:241], v188 offset:23552
	global_load_lds_dwordx4 v[226:227], off
	s_add_i32 m0, s76, 0x2000
	v_lshl_add_u64 v[242:243], s[74:75], 0, v[152:153]
	s_add_u32 s74, s74, s28
	s_addc_u32 s75, s75, s29
	s_add_i32 s71, s71, s12
	global_load_lds_dwordx4 v[242:243], off
	v_lshl_add_u64 v[244:245], s[74:75], 0, v[34:35]
	s_mov_b32 m0, s71
	v_lshl_add_u64 v[246:247], s[74:75], 0, v[152:153]
	global_load_lds_dwordx4 v[244:245], off
	s_add_i32 m0, s71, 0x2000
	v_lshl_add_u64 v[248:249], s[58:59], 0, v[148:149]
	global_load_lds_dwordx4 v[246:247], off
	s_mov_b32 m0, s13
	v_lshl_add_u64 v[250:251], s[58:59], 0, v[150:151]
	global_load_lds_dwordx4 v[248:249], off
	s_mov_b32 m0, s15
	s_nop 0
	global_load_lds_dwordx4 v[250:251], off
	s_waitcnt vmcnt(8)
	s_waitcnt lgkmcnt(0)
	s_barrier
; #define PG8_STAGE(bufoff, gbase, voff) do { _Pragma("unroll") for (int _i = 0; _i < 2; ++_i) \
;         __builtin_amdgcn_global_load_lds((const unsigned*)((const char*)(gbase) + (voff)[_i]), (PG8_LAS unsigned*)(lds + (bufoff) + ldsw + _i * 8192), 16, 0, 0); } while (0)
; #define PG8_LDA(dst, b, h) do { _Pragma("unroll") for (int m = 0; m < 4; ++m) _Pragma("unroll") for (int k = 0; k < 2; ++k) dst[m][k] = *(const PG8_LAS bf16x8*)(lds + PG8_SA(b, h) + aoff + m * 2048 + k * 1024); } while (0)
; #define PG8_LDB(dst, b, h) do { _Pragma("unroll") for (int n = 0; n < 2; ++n) _Pragma("unroll") for (int k = 0; k < 2; ++k) dst[n][k] = *(const PG8_LAS bf16x8*)(lds + PG8_SB(b, h) + boff + n * 2048 + k * 1024); } while (0)
; #define PG8_WAIT_V(n) asm volatile("s_waitcnt vmcnt(" #n ")" ::: "memory")
; #define PG8_WAIT_L(n) asm volatile("s_waitcnt lgkmcnt(" #n ")" ::: "memory")
; #define PG8_BAR __builtin_amdgcn_s_barrier()
; #define PG8_SCHED __builtin_amdgcn_sched_barrier(0)
;     ...
;             PG8_WAIT_V(8); PG8_WAIT_L(0); PG8_BAR; PG8_MMA(1, 0, At, B0); PG8_MMA(1, 1, At, B1); PG8_BAR; PG8_SCHED;
;             PG8_LDB(B0, 1, 0); PG8_LDB(B1, 1, 1); PG8_SCHED; PG8_LDA(At, 1, 0); PG8_STAGE(PG8_SA(0, 1), a2 + hstepA, voffA);
;             PG8_WAIT_V(8); PG8_WAIT_L(0); PG8_BAR; PG8_MMA(0, 0, At, B0); PG8_MMA(0, 1, At, B1); PG8_BAR; PG8_SCHED;
;             PG8_LDA(At, 1, 1); PG8_STAGE(PG8_SB(1, 0), b3, voffB); PG8_STAGE(PG8_SB(1, 1), b3 + hstepB, voffB); PG8_STAGE(PG8_SA(1, 0), a3, voffA);
	s_setprio 1
	v_mfma_f32_16x16x32_bf16 v[64:67], v[108:111], v[202:205], v[64:67]
	v_mfma_f32_16x16x32_bf16 v[60:63], v[124:127], v[202:205], v[60:63]
	v_mfma_f32_16x16x32_bf16 v[48:51], v[108:111], v[210:213], v[48:51]
	v_mfma_f32_16x16x32_bf16 v[44:47], v[124:127], v[210:213], v[44:47]
	v_mfma_f32_16x16x32_bf16 v[30:33], v[108:111], v[218:221], v[30:33]
	v_mfma_f32_16x16x32_bf16 v[26:29], v[124:127], v[218:221], v[26:29]
	v_mfma_f32_16x16x32_bf16 v[14:17], v[108:111], v[234:237], v[14:17]
	v_mfma_f32_16x16x32_bf16 v[10:13], v[124:127], v[234:237], v[10:13]
	v_mfma_f32_16x16x32_bf16 v[64:67], v[112:115], v[206:209], v[64:67]
	v_mfma_f32_16x16x32_bf16 v[60:63], v[128:131], v[206:209], v[60:63]
	v_mfma_f32_16x16x32_bf16 v[48:51], v[112:115], v[214:217], v[48:51]
	v_mfma_f32_16x16x32_bf16 v[44:47], v[128:131], v[214:217], v[44:47]
	v_mfma_f32_16x16x32_bf16 v[30:33], v[112:115], v[222:225], v[30:33]
	v_mfma_f32_16x16x32_bf16 v[26:29], v[128:131], v[222:225], v[26:29]
	v_mfma_f32_16x16x32_bf16 v[14:17], v[112:115], v[238:241], v[14:17]
	v_mfma_f32_16x16x32_bf16 v[10:13], v[128:131], v[238:241], v[10:13]
	v_mfma_f32_16x16x32_bf16 v[56:59], v[160:163], v[202:205], v[56:59]
	v_mfma_f32_16x16x32_bf16 v[52:55], v[194:197], v[202:205], v[52:55]
	v_mfma_f32_16x16x32_bf16 v[40:43], v[160:163], v[210:213], v[40:43]
	v_mfma_f32_16x16x32_bf16 v[36:39], v[194:197], v[210:213], v[36:39]
	v_mfma_f32_16x16x32_bf16 v[22:25], v[160:163], v[218:221], v[22:25]
	v_mfma_f32_16x16x32_bf16 v[18:21], v[194:197], v[218:221], v[18:21]
	v_mfma_f32_16x16x32_bf16 v[6:9], v[160:163], v[234:237], v[6:9]
	v_mfma_f32_16x16x32_bf16 v[2:5], v[194:197], v[234:237], v[2:5]
	v_mfma_f32_16x16x32_bf16 v[56:59], v[190:193], v[206:209], v[56:59]
	v_mfma_f32_16x16x32_bf16 v[52:55], v[198:201], v[206:209], v[52:55]
	v_mfma_f32_16x16x32_bf16 v[40:43], v[190:193], v[214:217], v[40:43]
	v_mfma_f32_16x16x32_bf16 v[36:39], v[198:201], v[214:217], v[36:39]
	v_mfma_f32_16x16x32_bf16 v[22:25], v[190:193], v[222:225], v[22:25]
	v_mfma_f32_16x16x32_bf16 v[18:21], v[198:201], v[222:225], v[18:21]
	v_mfma_f32_16x16x32_bf16 v[6:9], v[190:193], v[238:241], v[6:9]
	v_mfma_f32_16x16x32_bf16 v[2:5], v[198:201], v[238:241], v[2:5]
	s_setprio 0
	s_barrier
	s_add_i32 s71, 0, 0x18000
	s_add_i32 s74, 0, 0x1c000
	v_add_u32_e32 v128, s71, v187
	v_add_u32_e32 v189, s74, v187
	ds_read_b128 v[108:111], v128
	ds_read_b128 v[112:115], v128 offset:1024
	ds_read_b128 v[124:127], v128 offset:2048
	ds_read_b128 v[128:131], v128 offset:3072
	ds_read_b128 v[160:163], v189
	ds_read_b128 v[190:193], v189 offset:1024
	ds_read_b128 v[194:197], v189 offset:2048
	ds_read_b128 v[198:201], v189 offset:3072
	s_add_u32 s58, s58, 0x40000
	s_addc_u32 s59, s59, 0
	s_mov_b32 m0, s21
	v_lshl_add_u64 v[252:253], s[58:59], 0, v[148:149]
	ds_read_b128 v[202:205], v188 offset:32768
	ds_read_b128 v[206:209], v188 offset:33792
	ds_read_b128 v[210:213], v188 offset:34816
	ds_read_b128 v[214:217], v188 offset:35840
	ds_read_b128 v[218:221], v188 offset:36864
	ds_read_b128 v[222:225], v188 offset:37888
	ds_read_b128 v[234:237], v188 offset:38912
	ds_read_b128 v[238:241], v188 offset:39936
	global_load_lds_dwordx4 v[252:253], off
	v_lshl_add_u64 v[252:253], s[58:59], 0, v[150:151]
	s_mov_b32 m0, s34
	s_nop 0
	global_load_lds_dwordx4 v[252:253], off
	s_waitcnt vmcnt(8)
	s_waitcnt lgkmcnt(0)
	s_barrier
	s_setprio 1
	v_mfma_f32_16x16x32_bf16 v[144:147], v[108:111], v[202:205], v[144:147]
	v_mfma_f32_16x16x32_bf16 v[140:143], v[124:127], v[202:205], v[140:143]
	v_mfma_f32_16x16x32_bf16 v[120:123], v[108:111], v[210:213], v[120:123]
	v_mfma_f32_16x16x32_bf16 v[116:119], v[124:127], v[210:213], v[116:119]
	v_mfma_f32_16x16x32_bf16 v[96:99], v[108:111], v[218:221], v[96:99]
	v_mfma_f32_16x16x32_bf16 v[92:95], v[124:127], v[218:221], v[92:95]
	v_mfma_f32_16x16x32_bf16 v[80:83], v[108:111], v[234:237], v[80:83]
	v_mfma_f32_16x16x32_bf16 v[76:79], v[124:127], v[234:237], v[76:79]
	v_mfma_f32_16x16x32_bf16 v[144:147], v[112:115], v[206:209], v[144:147]
	v_mfma_f32_16x16x32_bf16 v[140:143], v[128:131], v[206:209], v[140:143]
	v_mfma_f32_16x16x32_bf16 v[120:123], v[112:115], v[214:217], v[120:123]
	v_mfma_f32_16x16x32_bf16 v[116:119], v[128:131], v[214:217], v[116:119]
	v_mfma_f32_16x16x32_bf16 v[96:99], v[112:115], v[222:225], v[96:99]
	v_mfma_f32_16x16x32_bf16 v[92:95], v[128:131], v[222:225], v[92:95]
	v_mfma_f32_16x16x32_bf16 v[80:83], v[112:115], v[238:241], v[80:83]
	v_mfma_f32_16x16x32_bf16 v[76:79], v[128:131], v[238:241], v[76:79]
	v_mfma_f32_16x16x32_bf16 v[136:139], v[160:163], v[202:205], v[136:139]
	v_mfma_f32_16x16x32_bf16 v[132:135], v[194:197], v[202:205], v[132:135]
	v_mfma_f32_16x16x32_bf16 v[104:107], v[160:163], v[210:213], v[104:107]
	v_mfma_f32_16x16x32_bf16 v[100:103], v[194:197], v[210:213], v[100:103]
	v_mfma_f32_16x16x32_bf16 v[88:91], v[160:163], v[218:221], v[88:91]
	v_mfma_f32_16x16x32_bf16 v[84:87], v[194:197], v[218:221], v[84:87]
	v_mfma_f32_16x16x32_bf16 v[72:75], v[160:163], v[234:237], v[72:75]
	v_mfma_f32_16x16x32_bf16 v[68:71], v[194:197], v[234:237], v[68:71]
	v_mfma_f32_16x16x32_bf16 v[136:139], v[190:193], v[206:209], v[136:139]
	v_mfma_f32_16x16x32_bf16 v[132:135], v[198:201], v[206:209], v[132:135]
	v_mfma_f32_16x16x32_bf16 v[104:107], v[190:193], v[214:217], v[104:107]
	v_mfma_f32_16x16x32_bf16 v[100:103], v[198:201], v[214:217], v[100:103]
	v_mfma_f32_16x16x32_bf16 v[88:91], v[190:193], v[222:225], v[88:91]
	v_mfma_f32_16x16x32_bf16 v[84:87], v[198:201], v[222:225], v[84:87]
	v_mfma_f32_16x16x32_bf16 v[72:75], v[190:193], v[238:241], v[72:75]
	v_mfma_f32_16x16x32_bf16 v[68:71], v[198:201], v[238:241], v[68:71]
	s_setprio 0
	s_barrier
; #define PG8_STAGE(bufoff, gbase, voff) do { _Pragma("unroll") for (int _i = 0; _i < 2; ++_i) \
;         __builtin_amdgcn_global_load_lds((const unsigned*)((const char*)(gbase) + (voff)[_i]), (PG8_LAS unsigned*)(lds + (bufoff) + ldsw + _i * 8192), 16, 0, 0); } while (0)
; #define PG8_LDA(dst, b, h) do { _Pragma("unroll") for (int m = 0; m < 4; ++m) _Pragma("unroll") for (int k = 0; k < 2; ++k) dst[m][k] = *(const PG8_LAS bf16x8*)(lds + PG8_SA(b, h) + aoff + m * 2048 + k * 1024); } while (0)
; #define PG8_WAIT_V(n) asm volatile("s_waitcnt vmcnt(" #n ")" ::: "memory")
; #define PG8_WAIT_L(n) asm volatile("s_waitcnt lgkmcnt(" #n ")" ::: "memory")
; #define PG8_BAR __builtin_amdgcn_s_barrier()
; #define PG8_SCHED __builtin_amdgcn_sched_barrier(0)
;     ...
;             PG8_LDA(At, 1, 1); PG8_STAGE(PG8_SB(1, 0), b3, voffB); PG8_STAGE(PG8_SB(1, 1), b3 + hstepB, voffB); PG8_STAGE(PG8_SA(1, 0), a3, voffA);
;             PG8_WAIT_V(8); PG8_WAIT_L(0); PG8_BAR; PG8_MMA(1, 0, At, B0); PG8_MMA(1, 1, At, B1); PG8_BAR; PG8_SCHED;
	s_add_i32 s58, s71, s12
	v_lshl_add_u64 v[226:227], v[226:227], 0, s[22:23]
	s_mov_b32 m0, s58
	ds_read_b128 v[202:205], v188 offset:49152
	ds_read_b128 v[206:209], v188 offset:50176
	ds_read_b128 v[210:213], v188 offset:51200
	ds_read_b128 v[214:217], v188 offset:52224
	ds_read_b128 v[218:221], v188 offset:53248
	ds_read_b128 v[222:225], v188 offset:54272
	ds_read_b128 v[234:237], v188 offset:55296
	ds_read_b128 v[238:241], v188 offset:56320
	global_load_lds_dwordx4 v[226:227], off
	v_lshl_add_u64 v[226:227], v[242:243], 0, s[22:23]
	s_add_i32 m0, s58, 0x2000
	s_add_i32 s58, s74, s12
	global_load_lds_dwordx4 v[226:227], off
	v_lshl_add_u64 v[226:227], v[244:245], 0, s[22:23]
	s_mov_b32 m0, s58
	s_nop 0
	global_load_lds_dwordx4 v[226:227], off
	v_lshl_add_u64 v[226:227], v[246:247], 0, s[22:23]
	s_add_i32 m0, s58, 0x2000
	s_nop 0
	global_load_lds_dwordx4 v[226:227], off
	v_lshl_add_u64 v[226:227], v[248:249], 0, s[22:23]
	s_mov_b32 m0, s57
	s_nop 0
	global_load_lds_dwordx4 v[226:227], off
	v_lshl_add_u64 v[226:227], v[250:251], 0, s[22:23]
	s_mov_b32 m0, s62
	s_nop 0
	global_load_lds_dwordx4 v[226:227], off
	s_waitcnt vmcnt(8)
	s_waitcnt lgkmcnt(0)
	s_barrier
	s_setprio 1
	v_mfma_f32_16x16x32_bf16 v[64:67], v[108:111], v[202:205], v[64:67]
	v_mfma_f32_16x16x32_bf16 v[60:63], v[124:127], v[202:205], v[60:63]
	v_mfma_f32_16x16x32_bf16 v[48:51], v[108:111], v[210:213], v[48:51]
	v_mfma_f32_16x16x32_bf16 v[44:47], v[124:127], v[210:213], v[44:47]
	v_mfma_f32_16x16x32_bf16 v[30:33], v[108:111], v[218:221], v[30:33]
	v_mfma_f32_16x16x32_bf16 v[26:29], v[124:127], v[218:221], v[26:29]
	v_mfma_f32_16x16x32_bf16 v[14:17], v[108:111], v[234:237], v[14:17]
	v_mfma_f32_16x16x32_bf16 v[10:13], v[124:127], v[234:237], v[10:13]
	v_mfma_f32_16x16x32_bf16 v[64:67], v[112:115], v[206:209], v[64:67]
	v_mfma_f32_16x16x32_bf16 v[60:63], v[128:131], v[206:209], v[60:63]
	v_mfma_f32_16x16x32_bf16 v[48:51], v[112:115], v[214:217], v[48:51]
	v_mfma_f32_16x16x32_bf16 v[44:47], v[128:131], v[214:217], v[44:47]
	v_mfma_f32_16x16x32_bf16 v[30:33], v[112:115], v[222:225], v[30:33]
	v_mfma_f32_16x16x32_bf16 v[26:29], v[128:131], v[222:225], v[26:29]
	v_mfma_f32_16x16x32_bf16 v[14:17], v[112:115], v[238:241], v[14:17]
	v_mfma_f32_16x16x32_bf16 v[10:13], v[128:131], v[238:241], v[10:13]
	v_mfma_f32_16x16x32_bf16 v[56:59], v[160:163], v[202:205], v[56:59]
	v_mfma_f32_16x16x32_bf16 v[52:55], v[194:197], v[202:205], v[52:55]
	v_mfma_f32_16x16x32_bf16 v[40:43], v[160:163], v[210:213], v[40:43]
	v_mfma_f32_16x16x32_bf16 v[36:39], v[194:197], v[210:213], v[36:39]
	v_mfma_f32_16x16x32_bf16 v[22:25], v[160:163], v[218:221], v[22:25]
	v_mfma_f32_16x16x32_bf16 v[18:21], v[194:197], v[218:221], v[18:21]
	v_mfma_f32_16x16x32_bf16 v[6:9], v[160:163], v[234:237], v[6:9]
	v_mfma_f32_16x16x32_bf16 v[2:5], v[194:197], v[234:237], v[2:5]
	v_mfma_f32_16x16x32_bf16 v[56:59], v[190:193], v[206:209], v[56:59]
	v_mfma_f32_16x16x32_bf16 v[52:55], v[198:201], v[206:209], v[52:55]
	v_mfma_f32_16x16x32_bf16 v[40:43], v[190:193], v[214:217], v[40:43]
	v_mfma_f32_16x16x32_bf16 v[36:39], v[198:201], v[214:217], v[36:39]
	v_mfma_f32_16x16x32_bf16 v[22:25], v[190:193], v[222:225], v[22:25]
	v_mfma_f32_16x16x32_bf16 v[18:21], v[198:201], v[222:225], v[18:21]
	v_mfma_f32_16x16x32_bf16 v[6:9], v[190:193], v[238:241], v[6:9]
	v_mfma_f32_16x16x32_bf16 v[2:5], v[198:201], v[238:241], v[2:5]
	s_setprio 0
	s_barrier
	s_add_u32 s40, s40, 0x100
	s_addc_u32 s41, s41, 0
	s_add_u32 s60, s60, 0x100
	s_addc_u32 s61, s61, 0
	s_cmp_ge_i32 s70, s35
	s_mov_b32 s58, s70
	s_cbranch_scc0 .LBB0_1503
	s_movk_i32 s71, 0x6ff

; #define PG8_STAGE(bufoff, gbase, voff) do { _Pragma("unroll") for (int _i = 0; _i < 2; ++_i) \
;         __builtin_amdgcn_global_load_lds((const unsigned*)((const char*)(gbase) + (voff)[_i]), (PG8_LAS unsigned*)(lds + (bufoff) + ldsw + _i * 8192), 16, 0, 0); } while (0)
; #define PG8_WAIT_V(n) asm volatile("s_waitcnt vmcnt(" #n ")" ::: "memory")
; #define PG8_BAR __builtin_amdgcn_s_barrier()
;     ...
;     f32x4 acc[2][2][4][2];
; #pragma unroll
;     for (int a = 0; a < 2; ++a)
; #pragma unroll
;         for (int b = 0; b < 2; ++b)
; #pragma unroll
;             for (int m = 0; m < 4; ++m)
; #pragma unroll
;                 for (int n = 0; n < 2; ++n) acc[a][b][m][n] = (f32x4){0.f, 0.f, 0.f, 0.f};
;     ...
;         PG8_STAGE(PG8_SB(0, 0), cB, voffB); PG8_STAGE(PG8_SB(0, 1), cB + hstepB, voffB); PG8_STAGE(PG8_SA(0, 0), cA, voffA); PG8_STAGE(PG8_SA(0, 1), cA + hstepA, voffA);
;         if (wr == 1) PG8_BAR;
;         PG8_WAIT_V(2); PG8_BAR;
;         PG8_STAGE(PG8_SB(1, 0), cB + kstep, voffB); PG8_STAGE(PG8_SA(1, 0), cA + kstep, voffA); PG8_STAGE(PG8_SB(1, 1), cB + hstepB + kstep, voffB);
;         PG8_WAIT_V(6); PG8_BAR;
.LBB0_2009:
	s_add_u32 s26, s28, 0x54c00000
	v_lshrrev_b32_e32 v18, 1, v10
	s_addc_u32 s27, s29, 0
	v_and_b32_e32 v18, 24, v18
	s_add_u32 s28, s28, 0x6d400000
	v_and_b32_e32 v17, 15, v10
	v_lshlrev_b32_e32 v19, 1, v18
	v_lshlrev_b32_e32 v10, 2, v10
	s_addc_u32 s29, s29, 0
	v_lshl_or_b32 v234, s15, 6, v17
	v_lshl_or_b32 v17, v17, 6, v19
	s_lshl_b32 s15, s15, 13
	v_and_b32_e32 v10, 32, v10
	v_bitop3_b32 v19, v17, s15, v10 bitop3:0xde
	s_lshl_b32 s15, s24, 5
	s_and_b32 s15, s15, 0x60
	s_add_i32 m0, s53, 0x18000
	v_lshl_add_u64 v[8:9], v[8:9], 0, s[22:23]
	s_lshl_b32 s24, s15, 7
	s_waitcnt vmcnt(2)
	s_barrier
	global_load_lds_dwordx4 v[8:9], off
	v_lshl_add_u64 v[6:7], v[6:7], 0, s[22:23]
	s_add_i32 m0, s53, 0x1a000
	s_add_i32 s61, s53, 0x8000
	s_add_i32 s62, s53, 0xa000
	global_load_lds_dwordx4 v[6:7], off
	v_lshl_add_u64 v[2:3], v[2:3], 0, s[22:23]
	s_mov_b32 m0, s61
	s_add_u32 s30, s56, 0x40080
	global_load_lds_dwordx4 v[2:3], off
	v_lshl_add_u64 v[2:3], v[4:5], 0, s[22:23]
	s_mov_b32 m0, s62
	s_addc_u32 s31, s57, 0
	global_load_lds_dwordx4 v[2:3], off
	s_add_i32 m0, s53, 0x1c000
	v_lshl_add_u64 v[2:3], s[30:31], 0, v[34:35]
	global_load_lds_dwordx4 v[2:3], off
	v_lshl_add_u64 v[2:3], s[30:31], 0, v[136:137]
	s_add_i32 m0, s53, 0x1e000
	s_cmpk_lt_u32 s6, 0x100
	global_load_lds_dwordx4 v[2:3], off
	v_lshlrev_b32_e32 v2, 14, v11
	v_and_b32_e32 v2, 0xffff8000, v2
	v_lshl_add_u32 v2, v12, 11, v2
	v_and_b32_e32 v3, 1, v11
	v_lshl_or_b32 v2, v3, 6, v2
	v_lshl_add_u32 v138, v13, 1, v2
	v_lshlrev_b32_e32 v2, 14, v14
	v_and_b32_e32 v2, 0xffff8000, v2
	v_lshl_add_u32 v2, v15, 11, v2
	v_and_b32_e32 v3, 1, v14
	s_waitcnt vmcnt(6)
	v_lshl_or_b32 v2, v3, 6, v2
	v_lshl_add_u32 v140, v16, 1, v2
	v_mov_b32_e32 v2, 0
	v_bitop3_b32 v235, v17, s24, v10 bitop3:0xde
	s_cselect_b64 s[30:31], -1, 0
	s_ashr_i32 s63, s8, 31
	v_or_b32_e32 v236, s15, v18
	v_mov_b32_e32 v139, v35
	v_mov_b32_e32 v141, v35
	s_mov_b32 s6, 0
	v_add_u32_e32 v237, 0, v19
	s_mov_b32 s64, 0
	v_mov_b32_e32 v3, v2
	v_mov_b64_e32 v[4:5], 0
	v_mov_b64_e32 v[6:7], 0
	v_mov_b64_e32 v[8:9], 0
	v_mov_b64_e32 v[10:11], 0
	v_mov_b64_e32 v[12:13], 0
	v_mov_b64_e32 v[14:15], 0
	v_mov_b64_e32 v[16:17], 0
	v_mov_b64_e32 v[18:19], 0
	v_mov_b64_e32 v[20:21], 0
	v_mov_b64_e32 v[22:23], 0
	v_mov_b64_e32 v[24:25], 0
	v_mov_b64_e32 v[26:27], 0
	v_mov_b64_e32 v[28:29], 0
	v_mov_b64_e32 v[30:31], 0
	v_mov_b64_e32 v[32:33], 0
	v_mov_b64_e32 v[36:37], 0
	v_mov_b64_e32 v[38:39], 0
	v_mov_b64_e32 v[40:41], 0
	v_mov_b64_e32 v[42:43], 0
	v_mov_b64_e32 v[44:45], 0
	v_mov_b64_e32 v[46:47], 0
	v_mov_b64_e32 v[48:49], 0
	v_mov_b64_e32 v[50:51], 0
	v_mov_b64_e32 v[52:53], 0
	v_mov_b64_e32 v[54:55], 0
	v_mov_b64_e32 v[56:57], 0
	v_mov_b64_e32 v[58:59], 0
	v_mov_b64_e32 v[60:61], 0
	v_mov_b64_e32 v[62:63], 0
	v_mov_b64_e32 v[64:65], 0
	v_mov_b64_e32 v[66:67], 0
	v_mov_b64_e32 v[68:69], 0
	v_mov_b64_e32 v[70:71], 0
	v_mov_b64_e32 v[72:73], 0
	v_mov_b64_e32 v[74:75], 0
	v_mov_b64_e32 v[76:77], 0
	v_mov_b64_e32 v[78:79], 0
	v_mov_b64_e32 v[80:81], 0
	v_mov_b64_e32 v[82:83], 0
	v_mov_b64_e32 v[84:85], 0
	v_mov_b64_e32 v[86:87], 0
	v_mov_b64_e32 v[88:89], 0
	v_mov_b64_e32 v[90:91], 0
	v_mov_b64_e32 v[92:93], 0
	v_mov_b64_e32 v[94:95], 0
	v_mov_b64_e32 v[96:97], 0
	v_mov_b64_e32 v[98:99], 0
	v_mov_b64_e32 v[100:101], 0
	v_mov_b64_e32 v[102:103], 0
	v_mov_b64_e32 v[104:105], 0
	v_mov_b64_e32 v[106:107], 0
	v_mov_b64_e32 v[108:109], 0
	v_mov_b64_e32 v[110:111], 0
	v_mov_b64_e32 v[112:113], 0
	v_mov_b64_e32 v[114:115], 0
	v_mov_b64_e32 v[116:117], 0
	v_mov_b64_e32 v[118:119], 0
	v_mov_b64_e32 v[120:121], 0
	v_mov_b64_e32 v[122:123], 0
	v_mov_b64_e32 v[124:125], 0
	v_mov_b64_e32 v[126:127], 0
	v_mov_b64_e32 v[128:129], 0
	v_mov_b64_e32 v[130:131], 0
	s_barrier
	s_branch .LBB0_2012

; #define PG8_STAGE(bufoff, gbase, voff) do { _Pragma("unroll") for (int _i = 0; _i < 2; ++_i) \
;         __builtin_amdgcn_global_load_lds((const unsigned*)((const char*)(gbase) + (voff)[_i]), (PG8_LAS unsigned*)(lds + (bufoff) + ldsw + _i * 8192), 16, 0, 0); } while (0)
; #define PG8_LDA(dst, b, h) do { _Pragma("unroll") for (int m = 0; m < 4; ++m) _Pragma("unroll") for (int k = 0; k < 2; ++k) dst[m][k] = *(const PG8_LAS bf16x8*)(lds + PG8_SA(b, h) + aoff + m * 2048 + k * 1024); } while (0)
; #define PG8_LDB(dst, b, h) do { _Pragma("unroll") for (int n = 0; n < 2; ++n) _Pragma("unroll") for (int k = 0; k < 2; ++k) dst[n][k] = *(const PG8_LAS bf16x8*)(lds + PG8_SB(b, h) + boff + n * 2048 + k * 1024); } while (0)
; #define PG8_WAIT_V(n) asm volatile("s_waitcnt vmcnt(" #n ")" ::: "memory")
; #define PG8_WAIT_L(n) asm volatile("s_waitcnt lgkmcnt(" #n ")" ::: "memory")
; #define PG8_BAR __builtin_amdgcn_s_barrier()
; #define PG8_SCHED __builtin_amdgcn_sched_barrier(0)
;     ...
;             PG8_LDB(B0, 0, 0); PG8_LDB(B1, 0, 1); PG8_SCHED; PG8_LDA(At, 0, 0); PG8_STAGE(PG8_SA(1, 1), a1 + hstepA, voffA);
;             PG8_WAIT_V(8); PG8_WAIT_L(0); PG8_BAR; PG8_MMA(0, 0, At, B0); PG8_MMA(0, 1, At, B1); PG8_BAR; PG8_SCHED;
;             PG8_LDA(At, 0, 1); PG8_STAGE(PG8_SB(0, 0), b2, voffB); PG8_STAGE(PG8_SB(0, 1), b2 + hstepB, voffB); PG8_STAGE(PG8_SA(0, 0), a2, voffA);
;             PG8_WAIT_V(8); PG8_WAIT_L(0); PG8_BAR; PG8_MMA(1, 0, At, B0); PG8_MMA(1, 1, At, B1); PG8_BAR; PG8_SCHED;
.LBB0_2023:
	s_add_u32 s35, s40, 0xfffc0080
	s_addc_u32 s37, s41, -1
	s_add_i32 s43, 0, 0x10000
	s_cmp_eq_u32 s34, 12
	s_cselect_b32 s57, s49, s37
	s_cselect_b32 s56, s48, s35
	s_cselect_b32 s55, s51, s24
	s_cselect_b32 s54, s50, s15
	s_add_i32 s35, 0, 0x14000
	v_add_u32_e32 v154, s43, v235
	v_add_u32_e32 v162, s35, v235
	ds_read_b128 v[142:145], v154
	ds_read_b128 v[146:149], v154 offset:1024
	ds_read_b128 v[150:153], v154 offset:2048
	ds_read_b128 v[154:157], v154 offset:3072
	ds_read_b128 v[158:161], v162
	ds_read_b128 v[186:189], v162 offset:1024
	ds_read_b128 v[190:193], v162 offset:2048
	ds_read_b128 v[194:197], v162 offset:3072
	v_lshl_add_u64 v[162:163], s[40:41], 0, v[138:139]
	s_add_i32 m0, s53, 0xc000
	ds_read_b128 v[198:201], v237
	ds_read_b128 v[202:205], v237 offset:1024
	ds_read_b128 v[206:209], v237 offset:2048
	ds_read_b128 v[210:213], v237 offset:3072
	ds_read_b128 v[214:217], v237 offset:4096
	ds_read_b128 v[218:221], v237 offset:5120
	ds_read_b128 v[222:225], v237 offset:6144
	ds_read_b128 v[238:241], v237 offset:7168
	global_load_lds_dwordx4 v[162:163], off
	v_lshl_add_u64 v[162:163], s[40:41], 0, v[140:141]
	s_add_i32 m0, s53, 0xe000
	s_nop 0
	global_load_lds_dwordx4 v[162:163], off
	s_waitcnt vmcnt(8)
	s_waitcnt lgkmcnt(0)
	s_barrier
	s_setprio 1
	v_mfma_f32_16x16x32_bf16 v[128:131], v[142:145], v[198:201], v[128:131]
	v_mfma_f32_16x16x32_bf16 v[124:127], v[150:153], v[198:201], v[124:127]
	v_mfma_f32_16x16x32_bf16 v[120:123], v[142:145], v[206:209], v[120:123]
	v_mfma_f32_16x16x32_bf16 v[116:119], v[150:153], v[206:209], v[116:119]
	v_mfma_f32_16x16x32_bf16 v[112:115], v[142:145], v[214:217], v[112:115]
	v_mfma_f32_16x16x32_bf16 v[108:111], v[150:153], v[214:217], v[108:111]
	v_mfma_f32_16x16x32_bf16 v[104:107], v[142:145], v[222:225], v[104:107]
	v_mfma_f32_16x16x32_bf16 v[100:103], v[150:153], v[222:225], v[100:103]
	v_mfma_f32_16x16x32_bf16 v[128:131], v[146:149], v[202:205], v[128:131]
	v_mfma_f32_16x16x32_bf16 v[124:127], v[154:157], v[202:205], v[124:127]
	v_mfma_f32_16x16x32_bf16 v[120:123], v[146:149], v[210:213], v[120:123]
	v_mfma_f32_16x16x32_bf16 v[116:119], v[154:157], v[210:213], v[116:119]
	v_mfma_f32_16x16x32_bf16 v[112:115], v[146:149], v[218:221], v[112:115]
	v_mfma_f32_16x16x32_bf16 v[108:111], v[154:157], v[218:221], v[108:111]
	v_mfma_f32_16x16x32_bf16 v[104:107], v[146:149], v[238:241], v[104:107]
	v_mfma_f32_16x16x32_bf16 v[100:103], v[154:157], v[238:241], v[100:103]
	v_mfma_f32_16x16x32_bf16 v[96:99], v[158:161], v[198:201], v[96:99]
	v_mfma_f32_16x16x32_bf16 v[92:95], v[190:193], v[198:201], v[92:95]
	v_mfma_f32_16x16x32_bf16 v[88:91], v[158:161], v[206:209], v[88:91]
	v_mfma_f32_16x16x32_bf16 v[84:87], v[190:193], v[206:209], v[84:87]
	v_mfma_f32_16x16x32_bf16 v[80:83], v[158:161], v[214:217], v[80:83]
	v_mfma_f32_16x16x32_bf16 v[76:79], v[190:193], v[214:217], v[76:79]
	v_mfma_f32_16x16x32_bf16 v[72:75], v[158:161], v[222:225], v[72:75]
	v_mfma_f32_16x16x32_bf16 v[68:71], v[190:193], v[222:225], v[68:71]
	v_mfma_f32_16x16x32_bf16 v[96:99], v[186:189], v[202:205], v[96:99]
	v_mfma_f32_16x16x32_bf16 v[92:95], v[194:197], v[202:205], v[92:95]
	v_mfma_f32_16x16x32_bf16 v[88:91], v[186:189], v[210:213], v[88:91]
	v_mfma_f32_16x16x32_bf16 v[84:87], v[194:197], v[210:213], v[84:87]
	v_mfma_f32_16x16x32_bf16 v[80:83], v[186:189], v[218:221], v[80:83]
	v_mfma_f32_16x16x32_bf16 v[76:79], v[194:197], v[218:221], v[76:79]
	v_mfma_f32_16x16x32_bf16 v[72:75], v[186:189], v[238:241], v[72:75]
	v_mfma_f32_16x16x32_bf16 v[68:71], v[194:197], v[238:241], v[68:71]
	s_setprio 0
	s_barrier
	s_add_i32 s37, s43, s21
	v_lshl_add_u64 v[162:163], s[54:55], 0, v[34:35]
	s_mov_b32 m0, s37
	ds_read_b128 v[198:201], v237 offset:16384
	ds_read_b128 v[202:205], v237 offset:17408
	ds_read_b128 v[206:209], v237 offset:18432
	ds_read_b128 v[210:213], v237 offset:19456
	ds_read_b128 v[214:217], v237 offset:20480
	ds_read_b128 v[218:221], v237 offset:21504
	ds_read_b128 v[222:225], v237 offset:22528
	ds_read_b128 v[238:241], v237 offset:23552
	global_load_lds_dwordx4 v[162:163], off
	s_add_i32 m0, s37, 0x2000
	s_add_u32 s66, s54, 0x40000
	v_lshl_add_u64 v[226:227], s[54:55], 0, v[136:137]
	s_addc_u32 s67, s55, 0
	s_add_i32 s35, s35, s21
	global_load_lds_dwordx4 v[226:227], off
	v_lshl_add_u64 v[242:243], s[66:67], 0, v[34:35]
	s_mov_b32 m0, s35
	v_lshl_add_u64 v[244:245], s[56:57], 0, v[134:135]
	global_load_lds_dwordx4 v[242:243], off
	v_lshl_add_u64 v[242:243], s[66:67], 0, v[136:137]
	s_add_i32 m0, s35, 0x2000
	s_nop 0
	global_load_lds_dwordx4 v[242:243], off
	v_lshl_add_u64 v[242:243], s[56:57], 0, v[132:133]
	s_mov_b32 m0, s53
	s_nop 0
	global_load_lds_dwordx4 v[242:243], off
	s_mov_b32 m0, s58
	s_nop 0
	global_load_lds_dwordx4 v[244:245], off
	s_waitcnt vmcnt(8)
	s_waitcnt lgkmcnt(0)
	s_barrier
; #define PG8_STAGE(bufoff, gbase, voff) do { _Pragma("unroll") for (int _i = 0; _i < 2; ++_i) \
;         __builtin_amdgcn_global_load_lds((const unsigned*)((const char*)(gbase) + (voff)[_i]), (PG8_LAS unsigned*)(lds + (bufoff) + ldsw + _i * 8192), 16, 0, 0); } while (0)
; #define PG8_LDA(dst, b, h) do { _Pragma("unroll") for (int m = 0; m < 4; ++m) _Pragma("unroll") for (int k = 0; k < 2; ++k) dst[m][k] = *(const PG8_LAS bf16x8*)(lds + PG8_SA(b, h) + aoff + m * 2048 + k * 1024); } while (0)
; #define PG8_LDB(dst, b, h) do { _Pragma("unroll") for (int n = 0; n < 2; ++n) _Pragma("unroll") for (int k = 0; k < 2; ++k) dst[n][k] = *(const PG8_LAS bf16x8*)(lds + PG8_SB(b, h) + boff + n * 2048 + k * 1024); } while (0)
; #define PG8_WAIT_V(n) asm volatile("s_waitcnt vmcnt(" #n ")" ::: "memory")
; #define PG8_WAIT_L(n) asm volatile("s_waitcnt lgkmcnt(" #n ")" ::: "memory")
; #define PG8_BAR __builtin_amdgcn_s_barrier()
; #define PG8_SCHED __builtin_amdgcn_sched_barrier(0)
;     ...
;             PG8_WAIT_V(8); PG8_WAIT_L(0); PG8_BAR; PG8_MMA(1, 0, At, B0); PG8_MMA(1, 1, At, B1); PG8_BAR; PG8_SCHED;
;             PG8_LDB(B0, 1, 0); PG8_LDB(B1, 1, 1); PG8_SCHED; PG8_LDA(At, 1, 0); PG8_STAGE(PG8_SA(0, 1), a2 + hstepA, voffA);
;             PG8_WAIT_V(8); PG8_WAIT_L(0); PG8_BAR; PG8_MMA(0, 0, At, B0); PG8_MMA(0, 1, At, B1); PG8_BAR; PG8_SCHED;
;             PG8_LDA(At, 1, 1); PG8_STAGE(PG8_SB(1, 0), b3, voffB); PG8_STAGE(PG8_SB(1, 1), b3 + hstepB, voffB); PG8_STAGE(PG8_SA(1, 0), a3, voffA);
	s_setprio 1
	v_mfma_f32_16x16x32_bf16 v[64:67], v[142:145], v[198:201], v[64:67]
	v_mfma_f32_16x16x32_bf16 v[60:63], v[150:153], v[198:201], v[60:63]
	v_mfma_f32_16x16x32_bf16 v[56:59], v[142:145], v[206:209], v[56:59]
	v_mfma_f32_16x16x32_bf16 v[52:55], v[150:153], v[206:209], v[52:55]
	v_mfma_f32_16x16x32_bf16 v[48:51], v[142:145], v[214:217], v[48:51]
	v_mfma_f32_16x16x32_bf16 v[44:47], v[150:153], v[214:217], v[44:47]
	v_mfma_f32_16x16x32_bf16 v[40:43], v[142:145], v[222:225], v[40:43]
	v_mfma_f32_16x16x32_bf16 v[36:39], v[150:153], v[222:225], v[36:39]
	v_mfma_f32_16x16x32_bf16 v[64:67], v[146:149], v[202:205], v[64:67]
	v_mfma_f32_16x16x32_bf16 v[60:63], v[154:157], v[202:205], v[60:63]
	v_mfma_f32_16x16x32_bf16 v[56:59], v[146:149], v[210:213], v[56:59]
	v_mfma_f32_16x16x32_bf16 v[52:55], v[154:157], v[210:213], v[52:55]
	v_mfma_f32_16x16x32_bf16 v[48:51], v[146:149], v[218:221], v[48:51]
	v_mfma_f32_16x16x32_bf16 v[44:47], v[154:157], v[218:221], v[44:47]
	v_mfma_f32_16x16x32_bf16 v[40:43], v[146:149], v[238:241], v[40:43]
	v_mfma_f32_16x16x32_bf16 v[36:39], v[154:157], v[238:241], v[36:39]
	v_mfma_f32_16x16x32_bf16 v[30:33], v[158:161], v[198:201], v[30:33]
	v_mfma_f32_16x16x32_bf16 v[26:29], v[190:193], v[198:201], v[26:29]
	v_mfma_f32_16x16x32_bf16 v[22:25], v[158:161], v[206:209], v[22:25]
	v_mfma_f32_16x16x32_bf16 v[18:21], v[190:193], v[206:209], v[18:21]
	v_mfma_f32_16x16x32_bf16 v[14:17], v[158:161], v[214:217], v[14:17]
	v_mfma_f32_16x16x32_bf16 v[10:13], v[190:193], v[214:217], v[10:13]
	v_mfma_f32_16x16x32_bf16 v[6:9], v[158:161], v[222:225], v[6:9]
	v_mfma_f32_16x16x32_bf16 v[2:5], v[190:193], v[222:225], v[2:5]
	v_mfma_f32_16x16x32_bf16 v[30:33], v[186:189], v[202:205], v[30:33]
	v_mfma_f32_16x16x32_bf16 v[26:29], v[194:197], v[202:205], v[26:29]
	v_mfma_f32_16x16x32_bf16 v[22:25], v[186:189], v[210:213], v[22:25]
	v_mfma_f32_16x16x32_bf16 v[18:21], v[194:197], v[210:213], v[18:21]
	v_mfma_f32_16x16x32_bf16 v[14:17], v[186:189], v[218:221], v[14:17]
	v_mfma_f32_16x16x32_bf16 v[10:13], v[194:197], v[218:221], v[10:13]
	v_mfma_f32_16x16x32_bf16 v[6:9], v[186:189], v[238:241], v[6:9]
	v_mfma_f32_16x16x32_bf16 v[2:5], v[194:197], v[238:241], v[2:5]
	s_setprio 0
	s_barrier
	s_add_i32 s35, 0, 0x18000
	s_add_i32 s37, 0, 0x1c000
	v_add_u32_e32 v154, s35, v235
	v_add_u32_e32 v194, s37, v235
	ds_read_b128 v[142:145], v154
	ds_read_b128 v[146:149], v154 offset:1024
	ds_read_b128 v[150:153], v154 offset:2048
	ds_read_b128 v[154:157], v154 offset:3072
	ds_read_b128 v[158:161], v194
	ds_read_b128 v[186:189], v194 offset:1024
	ds_read_b128 v[190:193], v194 offset:2048
	ds_read_b128 v[194:197], v194 offset:3072
	s_add_u32 s56, s56, 0x40000
	s_addc_u32 s57, s57, 0
	s_mov_b32 m0, s59
	v_lshl_add_u64 v[246:247], s[56:57], 0, v[132:133]
	ds_read_b128 v[198:201], v237 offset:32768
	ds_read_b128 v[202:205], v237 offset:33792
	ds_read_b128 v[206:209], v237 offset:34816
	ds_read_b128 v[210:213], v237 offset:35840
	ds_read_b128 v[214:217], v237 offset:36864
	ds_read_b128 v[218:221], v237 offset:37888
	ds_read_b128 v[222:225], v237 offset:38912
	ds_read_b128 v[238:241], v237 offset:39936
	global_load_lds_dwordx4 v[246:247], off
	v_lshl_add_u64 v[246:247], s[56:57], 0, v[134:135]
	s_mov_b32 m0, s60
	s_nop 0
	global_load_lds_dwordx4 v[246:247], off
	s_waitcnt vmcnt(8)
	s_waitcnt lgkmcnt(0)
	s_barrier
	s_setprio 1
	v_mfma_f32_16x16x32_bf16 v[128:131], v[142:145], v[198:201], v[128:131]
	v_mfma_f32_16x16x32_bf16 v[124:127], v[150:153], v[198:201], v[124:127]
	v_mfma_f32_16x16x32_bf16 v[120:123], v[142:145], v[206:209], v[120:123]
	v_mfma_f32_16x16x32_bf16 v[116:119], v[150:153], v[206:209], v[116:119]
	v_mfma_f32_16x16x32_bf16 v[112:115], v[142:145], v[214:217], v[112:115]
	v_mfma_f32_16x16x32_bf16 v[108:111], v[150:153], v[214:217], v[108:111]
	v_mfma_f32_16x16x32_bf16 v[104:107], v[142:145], v[222:225], v[104:107]
	v_mfma_f32_16x16x32_bf16 v[100:103], v[150:153], v[222:225], v[100:103]
	v_mfma_f32_16x16x32_bf16 v[128:131], v[146:149], v[202:205], v[128:131]
	v_mfma_f32_16x16x32_bf16 v[124:127], v[154:157], v[202:205], v[124:127]
	v_mfma_f32_16x16x32_bf16 v[120:123], v[146:149], v[210:213], v[120:123]
	v_mfma_f32_16x16x32_bf16 v[116:119], v[154:157], v[210:213], v[116:119]
	v_mfma_f32_16x16x32_bf16 v[112:115], v[146:149], v[218:221], v[112:115]
	v_mfma_f32_16x16x32_bf16 v[108:111], v[154:157], v[218:221], v[108:111]
	v_mfma_f32_16x16x32_bf16 v[104:107], v[146:149], v[238:241], v[104:107]
	v_mfma_f32_16x16x32_bf16 v[100:103], v[154:157], v[238:241], v[100:103]
	v_mfma_f32_16x16x32_bf16 v[96:99], v[158:161], v[198:201], v[96:99]
	v_mfma_f32_16x16x32_bf16 v[92:95], v[190:193], v[198:201], v[92:95]
	v_mfma_f32_16x16x32_bf16 v[88:91], v[158:161], v[206:209], v[88:91]
	v_mfma_f32_16x16x32_bf16 v[84:87], v[190:193], v[206:209], v[84:87]
	v_mfma_f32_16x16x32_bf16 v[80:83], v[158:161], v[214:217], v[80:83]
	v_mfma_f32_16x16x32_bf16 v[76:79], v[190:193], v[214:217], v[76:79]
	v_mfma_f32_16x16x32_bf16 v[72:75], v[158:161], v[222:225], v[72:75]
	v_mfma_f32_16x16x32_bf16 v[68:71], v[190:193], v[222:225], v[68:71]
	v_mfma_f32_16x16x32_bf16 v[96:99], v[186:189], v[202:205], v[96:99]
	v_mfma_f32_16x16x32_bf16 v[92:95], v[194:197], v[202:205], v[92:95]
	v_mfma_f32_16x16x32_bf16 v[88:91], v[186:189], v[210:213], v[88:91]
	v_mfma_f32_16x16x32_bf16 v[84:87], v[194:197], v[210:213], v[84:87]
	v_mfma_f32_16x16x32_bf16 v[80:83], v[186:189], v[218:221], v[80:83]
	v_mfma_f32_16x16x32_bf16 v[76:79], v[194:197], v[218:221], v[76:79]
	v_mfma_f32_16x16x32_bf16 v[72:75], v[186:189], v[238:241], v[72:75]
	v_mfma_f32_16x16x32_bf16 v[68:71], v[194:197], v[238:241], v[68:71]
	s_setprio 0
	s_barrier
; #define BR_LOAD(ai_) do { _Pragma("unroll") for (int m = 0; m < 4; ++m) _Pragma("unroll") for (int bj = 0; bj < 2; ++bj) { const size_t go = (size_t)((ai_) * HALF + m * 16) * 6144 + bj * HALF; \
;             gn[ai_][m][bj] = *(const u32x2*)(qn + go); gd[ai_][m][bj] = *(const u32x2*)(qd + go); } } while (0)
; #define PG8_STAGE(bufoff, gbase, voff) do { _Pragma("unroll") for (int _i = 0; _i < 2; ++_i) \
;         __builtin_amdgcn_global_load_lds((const unsigned*)((const char*)(gbase) + (voff)[_i]), (PG8_LAS unsigned*)(lds + (bufoff) + ldsw + _i * 8192), 16, 0, 0); } while (0)
; #define PG8_LDA(dst, b, h) do { _Pragma("unroll") for (int m = 0; m < 4; ++m) _Pragma("unroll") for (int k = 0; k < 2; ++k) dst[m][k] = *(const PG8_LAS bf16x8*)(lds + PG8_SA(b, h) + aoff + m * 2048 + k * 1024); } while (0)
; #define PG8_WAIT_V(n) asm volatile("s_waitcnt vmcnt(" #n ")" ::: "memory")
; #define PG8_WAIT_L(n) asm volatile("s_waitcnt lgkmcnt(" #n ")" ::: "memory")
; #define PG8_BAR __builtin_amdgcn_s_barrier()
; #define PG8_SCHED __builtin_amdgcn_sched_barrier(0)
;     __device__ __forceinline__ void operator()(f32x4 (&acc)[2][2][4][2], const Unit& u, int wr, int wc, int fr, int fq) const {
;         const int row0 = u.pm * BM + wr * 64 + fr, col0 = u.pn * BM + wc * 32 + 8 * fq; const int sg = u.seg; const bool fin = sg == 2;
;         const unsigned char* qn = Q + (size_t)row0 * 6144 + sg * 2048 + col0; const unsigned char* qd = fin ? qn : qn + 2048;
;         u32x2 gn[2][4][2], gd[2][4][2];
;     ...
;         BR_LOAD(0); BR_LOAD(1);
;     ...
;             PG8_LDA(At, 1, 1); PG8_STAGE(PG8_SB(1, 0), b3, voffB); PG8_STAGE(PG8_SB(1, 1), b3 + hstepB, voffB); PG8_STAGE(PG8_SA(1, 0), a3, voffA);
;             PG8_WAIT_V(8); PG8_WAIT_L(0); PG8_BAR; PG8_MMA(1, 0, At, B0); PG8_MMA(1, 1, At, B1); PG8_BAR; PG8_SCHED;
	s_add_i32 s35, s35, s21
	v_lshl_add_u64 v[162:163], v[162:163], 0, s[22:23]
	s_mov_b32 m0, s35
	ds_read_b128 v[198:201], v237 offset:49152
	ds_read_b128 v[202:205], v237 offset:50176
	ds_read_b128 v[206:209], v237 offset:51200
	ds_read_b128 v[210:213], v237 offset:52224
	ds_read_b128 v[214:217], v237 offset:53248
	ds_read_b128 v[218:221], v237 offset:54272
	ds_read_b128 v[222:225], v237 offset:55296
	ds_read_b128 v[238:241], v237 offset:56320
	global_load_lds_dwordx4 v[162:163], off
	s_add_i32 m0, s35, 0x2000
	s_add_u32 s54, s54, 0x40080
	v_lshl_add_u64 v[162:163], v[226:227], 0, s[22:23]
	s_addc_u32 s55, s55, 0
	s_add_i32 s35, s37, s21
	global_load_lds_dwordx4 v[162:163], off
	v_lshl_add_u64 v[162:163], s[54:55], 0, v[34:35]
	s_mov_b32 m0, s35
	s_nop 0
	global_load_lds_dwordx4 v[162:163], off
	v_lshl_add_u64 v[162:163], s[54:55], 0, v[136:137]
	s_add_i32 m0, s35, 0x2000
	s_nop 0
	global_load_lds_dwordx4 v[162:163], off
	v_lshl_add_u64 v[162:163], v[242:243], 0, s[22:23]
	s_mov_b32 m0, s61
	s_nop 0
	global_load_lds_dwordx4 v[162:163], off
	v_lshl_add_u64 v[162:163], v[244:245], 0, s[22:23]
	s_mov_b32 m0, s62
	s_nop 0
	global_load_lds_dwordx4 v[162:163], off
	s_waitcnt vmcnt(8)
	s_waitcnt lgkmcnt(0)
	s_barrier
	s_setprio 1
	v_mfma_f32_16x16x32_bf16 v[64:67], v[142:145], v[198:201], v[64:67]
	v_mfma_f32_16x16x32_bf16 v[60:63], v[150:153], v[198:201], v[60:63]
	v_mfma_f32_16x16x32_bf16 v[56:59], v[142:145], v[206:209], v[56:59]
	v_mfma_f32_16x16x32_bf16 v[52:55], v[150:153], v[206:209], v[52:55]
	v_mfma_f32_16x16x32_bf16 v[48:51], v[142:145], v[214:217], v[48:51]
	v_mfma_f32_16x16x32_bf16 v[44:47], v[150:153], v[214:217], v[44:47]
	v_mfma_f32_16x16x32_bf16 v[40:43], v[142:145], v[222:225], v[40:43]
	v_mfma_f32_16x16x32_bf16 v[36:39], v[150:153], v[222:225], v[36:39]
	v_mfma_f32_16x16x32_bf16 v[64:67], v[146:149], v[202:205], v[64:67]
	v_mfma_f32_16x16x32_bf16 v[60:63], v[154:157], v[202:205], v[60:63]
	v_mfma_f32_16x16x32_bf16 v[56:59], v[146:149], v[210:213], v[56:59]
	v_mfma_f32_16x16x32_bf16 v[52:55], v[154:157], v[210:213], v[52:55]
	v_mfma_f32_16x16x32_bf16 v[48:51], v[146:149], v[218:221], v[48:51]
	v_mfma_f32_16x16x32_bf16 v[44:47], v[154:157], v[218:221], v[44:47]
	v_mfma_f32_16x16x32_bf16 v[40:43], v[146:149], v[238:241], v[40:43]
	v_mfma_f32_16x16x32_bf16 v[36:39], v[154:157], v[238:241], v[36:39]
	v_mfma_f32_16x16x32_bf16 v[30:33], v[158:161], v[198:201], v[30:33]
	v_mfma_f32_16x16x32_bf16 v[26:29], v[190:193], v[198:201], v[26:29]
	v_mfma_f32_16x16x32_bf16 v[22:25], v[158:161], v[206:209], v[22:25]
	v_mfma_f32_16x16x32_bf16 v[18:21], v[190:193], v[206:209], v[18:21]
	v_mfma_f32_16x16x32_bf16 v[14:17], v[158:161], v[214:217], v[14:17]
	v_mfma_f32_16x16x32_bf16 v[10:13], v[190:193], v[214:217], v[10:13]
	v_mfma_f32_16x16x32_bf16 v[6:9], v[158:161], v[222:225], v[6:9]
	v_mfma_f32_16x16x32_bf16 v[2:5], v[190:193], v[222:225], v[2:5]
	v_mfma_f32_16x16x32_bf16 v[30:33], v[186:189], v[202:205], v[30:33]
	v_mfma_f32_16x16x32_bf16 v[26:29], v[194:197], v[202:205], v[26:29]
	v_mfma_f32_16x16x32_bf16 v[22:25], v[186:189], v[210:213], v[22:25]
	v_mfma_f32_16x16x32_bf16 v[18:21], v[194:197], v[210:213], v[18:21]
	v_mfma_f32_16x16x32_bf16 v[14:17], v[186:189], v[218:221], v[14:17]
	v_mfma_f32_16x16x32_bf16 v[10:13], v[194:197], v[218:221], v[10:13]
	v_mfma_f32_16x16x32_bf16 v[6:9], v[186:189], v[238:241], v[6:9]
	v_mfma_f32_16x16x32_bf16 v[2:5], v[194:197], v[238:241], v[2:5]
	s_setprio 0
	s_barrier
	s_add_i32 s34, s34, 2
	s_add_u32 s40, s40, 0x100
	s_addc_u32 s41, s41, 0
	s_add_u32 s15, s15, 0x100
	s_addc_u32 s24, s24, 0
	s_cmp_gt_u32 s34, 13
	s_cbranch_scc0 .LBB0_2023
	s_and_b64 vcc, exec, s[30:31]
	s_cbranch_vccz .LBB0_2026
	s_barrier
.LBB0_2026:
	s_lshl_b32 s34, s6, 11
	s_ashr_i32 s35, s34, 31
	v_lshl_add_u32 v144, s42, 8, v234
	s_cmp_eq_u32 s6, 2
	v_mov_b64_e32 v[146:147], s[26:27]
	v_lshl_or_b32 v142, s52, 8, v236
	s_cselect_b64 s[40:41], -1, 0
	v_mad_i64_i32 v[146:147], s[42:43], v144, s33, v[146:147]
	s_and_b64 s[42:43], s[40:41], exec
	v_lshl_add_u64 v[146:147], v[146:147], 0, s[34:35]
	v_ashrrev_i32_e32 v143, 31, v142
	s_cselect_b32 s24, 0, 0x800
	s_cmp_lg_u32 s6, 2
	v_lshl_add_u64 v[146:147], v[146:147], 0, v[142:143]
	s_mov_b32 s6, 0x18000
	v_add_co_u32_e32 v150, vcc, s6, v146
	v_lshl_add_u64 v[148:149], v[146:147], 0, s[24:25]
	s_nop 0
	v_addc_co_u32_e32 v151, vcc, 0, v147, vcc
	v_add_co_u32_e32 v152, vcc, s6, v148
	s_mov_b32 s6, 0x30000
	s_nop 0
	v_addc_co_u32_e32 v153, vcc, 0, v149, vcc
	global_load_dwordx2 v[238:239], v[146:147], off
	global_load_dwordx2 v[240:241], v[148:149], off
	global_load_dwordx2 v[226:227], v[146:147], off offset:128
	global_load_dwordx2 v[224:225], v[148:149], off offset:128
	global_load_dwordx2 v[220:221], v[150:151], off
	global_load_dwordx2 v[222:223], v[152:153], off
	global_load_dwordx2 v[218:219], v[150:151], off offset:128
	global_load_dwordx2 v[216:217], v[152:153], off offset:128
	v_add_co_u32_e32 v150, vcc, s6, v146
	v_ashrrev_i32_e32 v145, 31, v144
	s_nop 0
	v_addc_co_u32_e32 v151, vcc, 0, v147, vcc
	v_add_co_u32_e32 v152, vcc, s6, v148
	s_mov_b32 s6, 0x48000
	s_nop 0
	v_addc_co_u32_e32 v153, vcc, 0, v149, vcc
	global_load_dwordx2 v[212:213], v[150:151], off
	global_load_dwordx2 v[214:215], v[152:153], off
	global_load_dwordx2 v[210:211], v[150:151], off offset:128
	global_load_dwordx2 v[208:209], v[152:153], off offset:128
	v_add_co_u32_e32 v150, vcc, s6, v146
	s_waitcnt vmcnt(0)
; __device__ __forceinline__ unsigned cvt_pk_bf16(float lo, float hi) { f32x2c v = {lo, hi}; bf16x2c b = __builtin_convertvector(v, bf16x2c); return __builtin_bit_cast(unsigned, b); }
; __device__ __forceinline__ float ub0(unsigned w) { return (float)(w & 0xFFu); }
; __device__ __forceinline__ float ub1(unsigned w) { return (float)((w >> 8) & 0xFFu); }
; __device__ __forceinline__ float ub2(unsigned w) { return (float)((w >> 16) & 0xFFu); }
; __device__ __forceinline__ float ub3(unsigned w) { return (float)(w >> 24); }
; #define BR_LOAD(ai_) do { _Pragma("unroll") for (int m = 0; m < 4; ++m) _Pragma("unroll") for (int bj = 0; bj < 2; ++bj) { const size_t go = (size_t)((ai_) * HALF + m * 16) * 6144 + bj * HALF; \
;             gn[ai_][m][bj] = *(const u32x2*)(qn + go); gd[ai_][m][bj] = *(const u32x2*)(qd + go); } } while (0)
;     __device__ __forceinline__ void operator()(f32x4 (&acc)[2][2][4][2], const Unit& u, int wr, int wc, int fr, int fq) const {
;     ...
;         u32x2 gn[2][4][2], gd[2][4][2];
;     ...
;         BR_LOAD(0); BR_LOAD(1);
; #pragma unroll
;         for (int ai = 0; ai < 2; ++ai) {
; #pragma unroll
;             for (int m = 0; m < 4; ++m)
; #pragma unroll
;                 for (int bj = 0; bj < 2; ++bj) { const u32x2 a = gn[ai][m][bj], d = gd[ai][m][bj];
;                     const float an[8] = {ub0(a.x), ub1(a.x), ub2(a.x), ub3(a.x), ub0(a.y), ub1(a.y), ub2(a.y), ub3(a.y)};
;                     const float dn[8] = {ub0(d.x), ub1(d.x), ub2(d.x), ub3(d.x), ub0(d.y), ub1(d.y), ub2(d.y), ub3(d.y)};
;                     float f[8];
; #pragma unroll
;                     for (int k = 0; k < 8; ++k) { const float rd = __builtin_amdgcn_rcpf(dn[k]); f[k] = an[k] * (fin ? (1.0f / 255.0f) : rd); }
;                     f32x4 v0 = acc[ai][bj][m][0], v1 = acc[ai][bj][m][1];
;                     v0[0] *= f[0]; v0[1] *= f[1]; v0[2] *= f[2]; v0[3] *= f[3]; v1[0] *= f[4]; v1[1] *= f[5]; v1[2] *= f[6]; v1[3] *= f[7];
;                     acc[ai][bj][m][0] = v0; acc[ai][bj][m][1] = v1;
;                     if (fin) { u32x4 w; w.x = cvt_pk_bf16(v0[0], v0[1]); w.y = cvt_pk_bf16(v0[2], v0[3]); w.z = cvt_pk_bf16(v1[0], v1[1]); w.w = cvt_pk_bf16(v1[2], v1[3]);
;                         *(u32x4*)(MO + (size_t)(row0 + ai * HALF + m * 16) * ld + col0 + bj * HALF) = w; } }
	v_cvt_f32_ubyte2_e32 v244, v238
	v_addc_co_u32_e32 v151, vcc, 0, v147, vcc
	v_add_co_u32_e32 v152, vcc, s6, v148
	s_mov_b32 s6, 0xc0000
	s_nop 0
	v_addc_co_u32_e32 v153, vcc, 0, v149, vcc
	global_load_dwordx2 v[204:205], v[150:151], off
	global_load_dwordx2 v[206:207], v[152:153], off
	global_load_dwordx2 v[202:203], v[150:151], off offset:128
	global_load_dwordx2 v[200:201], v[152:153], off offset:128
	v_add_co_u32_e32 v150, vcc, s6, v146
	v_cvt_f32_ubyte0_e32 v248, v240
	s_nop 0
	v_addc_co_u32_e32 v151, vcc, 0, v147, vcc
	v_add_co_u32_e32 v152, vcc, s6, v148
	s_mov_b32 s6, 0xd8000
	s_nop 0
	v_addc_co_u32_e32 v153, vcc, 0, v149, vcc
	global_load_dwordx2 v[196:197], v[150:151], off
	global_load_dwordx2 v[198:199], v[152:153], off
	global_load_dwordx2 v[194:195], v[150:151], off offset:128
	global_load_dwordx2 v[192:193], v[152:153], off offset:128
	v_add_co_u32_e32 v150, vcc, s6, v146
	v_cvt_f32_ubyte1_e32 v249, v240
	s_nop 0
	v_addc_co_u32_e32 v151, vcc, 0, v147, vcc
	v_add_co_u32_e32 v152, vcc, s6, v148
	s_mov_b32 s6, 0xf0000
	s_nop 0
	v_addc_co_u32_e32 v153, vcc, 0, v149, vcc
	global_load_dwordx2 v[188:189], v[150:151], off
	global_load_dwordx2 v[190:191], v[152:153], off
	global_load_dwordx2 v[186:187], v[150:151], off offset:128
	global_load_dwordx2 v[162:163], v[152:153], off offset:128
	v_add_co_u32_e32 v150, vcc, s6, v146
	v_cvt_f32_ubyte2_e32 v250, v240
	s_nop 0
	v_addc_co_u32_e32 v151, vcc, 0, v147, vcc
	v_add_co_u32_e32 v152, vcc, s6, v148
	s_mov_b32 s6, 0x108000
	s_nop 0
	v_addc_co_u32_e32 v153, vcc, 0, v149, vcc
	v_add_co_u32_e32 v146, vcc, s6, v146
	global_load_dwordx2 v[158:159], v[150:151], off
	s_nop 0
	v_addc_co_u32_e32 v147, vcc, 0, v147, vcc
	v_add_co_u32_e32 v242, vcc, s6, v148
	global_load_dwordx2 v[160:161], v[152:153], off
	global_load_dwordx2 v[156:157], v[150:151], off offset:128
	global_load_dwordx2 v[154:155], v[152:153], off offset:128
	v_addc_co_u32_e32 v243, vcc, 0, v149, vcc
	global_load_dwordx2 v[150:151], v[146:147], off
	global_load_dwordx2 v[152:153], v[242:243], off
	global_load_dwordx2 v[148:149], v[146:147], off offset:128
	s_nop 0
	global_load_dwordx2 v[146:147], v[242:243], off offset:128
	v_cvt_f32_ubyte3_e32 v240, v240
	v_rcp_iflag_f32_e32 v240, v240
	v_cvt_f32_ubyte0_e32 v242, v238
	v_cvt_f32_ubyte1_e32 v243, v238
	v_cvt_f32_ubyte3_e32 v238, v238
	v_cvt_f32_ubyte0_e32 v251, v241
	v_cndmask_b32_e64 v240, v240, v233, s[40:41]
	v_rcp_iflag_f32_e32 v248, v248
	v_mul_f32_e32 v238, v240, v238
	v_rcp_iflag_f32_e32 v240, v251
	v_cvt_f32_ubyte0_e32 v245, v239
	v_cvt_f32_ubyte1_e32 v252, v241
	v_cndmask_b32_e64 v248, v248, v233, s[40:41]
	v_cndmask_b32_e64 v240, v240, v233, s[40:41]
	v_mul_f32_e32 v242, v248, v242
	v_rcp_iflag_f32_e32 v248, v249
	v_mul_f32_e32 v240, v240, v245
	v_rcp_iflag_f32_e32 v245, v252
	v_cvt_f32_ubyte1_e32 v246, v239
	v_cvt_f32_ubyte2_e32 v253, v241
	v_cvt_f32_ubyte3_e32 v241, v241
	v_cndmask_b32_e64 v248, v248, v233, s[40:41]
	v_cndmask_b32_e64 v245, v245, v233, s[40:41]
	v_mul_f32_e32 v243, v248, v243
	v_rcp_iflag_f32_e32 v248, v250
	v_mul_f32_e32 v245, v245, v246
	v_rcp_iflag_f32_e32 v246, v253
	v_rcp_iflag_f32_e32 v241, v241
	v_cvt_f32_ubyte2_e32 v247, v239
	v_cvt_f32_ubyte3_e32 v239, v239
	v_cndmask_b32_e64 v248, v248, v233, s[40:41]
	v_cndmask_b32_e64 v246, v246, v233, s[40:41]
	v_cndmask_b32_e64 v241, v241, v233, s[40:41]
	v_mul_f32_e32 v244, v248, v244
	v_mul_f32_e32 v246, v246, v247
	v_mul_f32_e32 v239, v241, v239
	v_mul_f32_e32 v128, v128, v242
	v_mul_f32_e32 v129, v129, v243
	v_mul_f32_e32 v130, v130, v244
	v_mul_f32_e32 v131, v131, v238
	v_mul_f32_e32 v124, v124, v240
	v_mul_f32_e32 v125, v125, v245
	v_mul_f32_e32 v126, v126, v246
	v_mul_f32_e32 v127, v127, v239
	s_cbranch_scc1 .LBB0_2028
	v_lshlrev_b64 v[242:243], 12, v[144:145]
	v_lshl_add_u64 v[242:243], s[28:29], 0, v[242:243]
	v_cvt_pk_bf16_f32 v238, v128, v129
	v_cvt_pk_bf16_f32 v239, v130, v131
	v_cvt_pk_bf16_f32 v240, v124, v125
	v_cvt_pk_bf16_f32 v241, v126, v127
	v_lshl_add_u64 v[242:243], v[142:143], 1, v[242:243]
	global_store_dwordx4 v[242:243], v[238:241], off sc0 sc1
.LBB0_2028:
	v_cvt_f32_ubyte0_e32 v244, v224
	v_rcp_iflag_f32_e32 v244, v244
	v_cvt_f32_ubyte0_e32 v238, v226
	v_cvt_f32_ubyte2_e32 v246, v224
	v_cvt_f32_ubyte1_e32 v245, v224
	v_cndmask_b32_e64 v244, v244, v233, s[40:41]
	v_mul_f32_e32 v238, v244, v238
	v_rcp_iflag_f32_e32 v244, v246
	v_cvt_f32_ubyte3_e32 v224, v224
	v_cvt_f32_ubyte2_e32 v240, v226
	v_cvt_f32_ubyte0_e32 v247, v225
	v_rcp_iflag_f32_e32 v224, v224
	v_cndmask_b32_e64 v244, v244, v233, s[40:41]
	v_mul_f32_e32 v240, v244, v240
	v_rcp_iflag_f32_e32 v244, v247
	v_cvt_f32_ubyte1_e32 v239, v226
	v_cvt_f32_ubyte3_e32 v226, v226
	v_cvt_f32_ubyte1_e32 v248, v225
	v_cndmask_b32_e64 v224, v224, v233, s[40:41]
	v_cvt_f32_ubyte0_e32 v241, v227
	v_cvt_f32_ubyte2_e32 v249, v225
	v_cvt_f32_ubyte3_e32 v225, v225
	v_mul_f32_e32 v224, v224, v226
	v_rcp_iflag_f32_e32 v226, v248
	v_cndmask_b32_e64 v244, v244, v233, s[40:41]
	v_rcp_iflag_f32_e32 v245, v245
	v_mul_f32_e32 v241, v244, v241
	v_rcp_iflag_f32_e32 v244, v249
	v_rcp_iflag_f32_e32 v225, v225
	v_cvt_f32_ubyte1_e32 v242, v227
	v_cndmask_b32_e64 v226, v226, v233, s[40:41]
	v_cvt_f32_ubyte2_e32 v243, v227
	v_cvt_f32_ubyte3_e32 v227, v227
	v_cndmask_b32_e64 v245, v245, v233, s[40:41]
	v_mul_f32_e32 v226, v226, v242
	v_cndmask_b32_e64 v242, v244, v233, s[40:41]
	v_cndmask_b32_e64 v225, v225, v233, s[40:41]
	v_mul_f32_e32 v239, v245, v239
	v_mul_f32_e32 v242, v242, v243
	v_mul_f32_e32 v225, v225, v227
	v_mul_f32_e32 v99, v99, v224
	v_cndmask_b32_e64 v224, 0, 1, s[40:41]
	v_mul_f32_e32 v96, v96, v238
	v_mul_f32_e32 v97, v97, v239
	v_mul_f32_e32 v98, v98, v240
	v_mul_f32_e32 v92, v92, v241
	v_mul_f32_e32 v93, v93, v226
	v_mul_f32_e32 v94, v94, v242
	v_cmp_ne_u32_e64 s[42:43], 1, v224
	s_andn2_b64 vcc, exec, s[40:41]
	v_mul_f32_e32 v95, v95, v225
	s_cbranch_vccnz .LBB0_2030
	v_lshlrev_b64 v[238:239], 12, v[144:145]
	v_lshl_add_u64 v[238:239], s[28:29], 0, v[238:239]
	v_cvt_pk_bf16_f32 v224, v96, v97
	v_cvt_pk_bf16_f32 v225, v98, v99
	v_cvt_pk_bf16_f32 v226, v92, v93
	v_cvt_pk_bf16_f32 v227, v94, v95
	v_lshl_add_u64 v[238:239], v[142:143], 1, v[238:239]
	global_store_dwordx4 v[238:239], v[224:227], off offset:256 sc0 sc1
; __device__ __forceinline__ unsigned cvt_pk_bf16(float lo, float hi) { f32x2c v = {lo, hi}; bf16x2c b = __builtin_convertvector(v, bf16x2c); return __builtin_bit_cast(unsigned, b); }
; __device__ __forceinline__ float ub0(unsigned w) { return (float)(w & 0xFFu); }
; __device__ __forceinline__ float ub1(unsigned w) { return (float)((w >> 8) & 0xFFu); }
; __device__ __forceinline__ float ub2(unsigned w) { return (float)((w >> 16) & 0xFFu); }
; __device__ __forceinline__ float ub3(unsigned w) { return (float)(w >> 24); }
;     __device__ __forceinline__ void operator()(f32x4 (&acc)[2][2][4][2], const Unit& u, int wr, int wc, int fr, int fq) const {
;     ...
;         for (int ai = 0; ai < 2; ++ai) {
; #pragma unroll
;             for (int m = 0; m < 4; ++m)
; #pragma unroll
;                 for (int bj = 0; bj < 2; ++bj) { const u32x2 a = gn[ai][m][bj], d = gd[ai][m][bj];
;                     const float an[8] = {ub0(a.x), ub1(a.x), ub2(a.x), ub3(a.x), ub0(a.y), ub1(a.y), ub2(a.y), ub3(a.y)};
;                     const float dn[8] = {ub0(d.x), ub1(d.x), ub2(d.x), ub3(d.x), ub0(d.y), ub1(d.y), ub2(d.y), ub3(d.y)};
;                     float f[8];
; #pragma unroll
;                     for (int k = 0; k < 8; ++k) { const float rd = __builtin_amdgcn_rcpf(dn[k]); f[k] = an[k] * (fin ? (1.0f / 255.0f) : rd); }
;                     f32x4 v0 = acc[ai][bj][m][0], v1 = acc[ai][bj][m][1];
;                     v0[0] *= f[0]; v0[1] *= f[1]; v0[2] *= f[2]; v0[3] *= f[3]; v1[0] *= f[4]; v1[1] *= f[5]; v1[2] *= f[6]; v1[3] *= f[7];
;                     acc[ai][bj][m][0] = v0; acc[ai][bj][m][1] = v1;
;                     if (fin) { u32x4 w; w.x = cvt_pk_bf16(v0[0], v0[1]); w.y = cvt_pk_bf16(v0[2], v0[3]); w.z = cvt_pk_bf16(v1[0], v1[1]); w.w = cvt_pk_bf16(v1[2], v1[3]);
;                         *(u32x4*)(MO + (size_t)(row0 + ai * HALF + m * 16) * ld + col0 + bj * HALF) = w; } }
.LBB0_2030:
	v_cvt_f32_ubyte0_e32 v241, v222
	v_rcp_iflag_f32_e32 v241, v241
	v_cvt_f32_ubyte0_e32 v145, v220
	v_cvt_f32_ubyte2_e32 v243, v222
	v_cvt_f32_ubyte1_e32 v242, v222
	v_cndmask_b32_e64 v241, v241, v233, s[40:41]
	v_mul_f32_e32 v145, v241, v145
	v_rcp_iflag_f32_e32 v241, v243
	v_cvt_f32_ubyte3_e32 v222, v222
	v_cvt_f32_ubyte2_e32 v227, v220
	v_cvt_f32_ubyte0_e32 v244, v223
	v_rcp_iflag_f32_e32 v222, v222
	v_cndmask_b32_e64 v241, v241, v233, s[40:41]
	v_mul_f32_e32 v227, v241, v227
	v_rcp_iflag_f32_e32 v241, v244
	v_cvt_f32_ubyte1_e32 v226, v220
	v_cvt_f32_ubyte3_e32 v220, v220
	v_cvt_f32_ubyte1_e32 v245, v223
	v_cndmask_b32_e64 v222, v222, v233, s[40:41]
	v_cvt_f32_ubyte0_e32 v238, v221
	v_cvt_f32_ubyte2_e32 v246, v223
	v_cvt_f32_ubyte3_e32 v223, v223
	v_mul_f32_e32 v220, v222, v220
	v_rcp_iflag_f32_e32 v222, v245
	v_cndmask_b32_e64 v241, v241, v233, s[40:41]
	v_rcp_iflag_f32_e32 v242, v242
	v_mul_f32_e32 v238, v241, v238
	v_rcp_iflag_f32_e32 v241, v246
	v_rcp_iflag_f32_e32 v223, v223
	v_cvt_f32_ubyte1_e32 v239, v221
	v_cndmask_b32_e64 v222, v222, v233, s[40:41]
	v_cvt_f32_ubyte2_e32 v240, v221
	v_cvt_f32_ubyte3_e32 v221, v221
	v_cndmask_b32_e64 v242, v242, v233, s[40:41]
	v_mul_f32_e32 v222, v222, v239
	v_cndmask_b32_e64 v239, v241, v233, s[40:41]
	v_cndmask_b32_e64 v223, v223, v233, s[40:41]
	v_or_b32_e32 v224, 16, v144
	v_mul_f32_e32 v226, v242, v226
	v_mul_f32_e32 v239, v239, v240
	v_mul_f32_e32 v221, v223, v221
	v_ashrrev_i32_e32 v225, 31, v224
	v_mul_f32_e32 v120, v120, v145
	v_mul_f32_e32 v121, v121, v226
	v_mul_f32_e32 v122, v122, v227
	v_mul_f32_e32 v123, v123, v220
	v_mul_f32_e32 v116, v116, v238
	v_mul_f32_e32 v117, v117, v222
	v_mul_f32_e32 v118, v118, v239
	s_and_b64 vcc, exec, s[42:43]
	v_mul_f32_e32 v119, v119, v221
	s_cbranch_vccnz .LBB0_2032
	v_lshlrev_b64 v[226:227], 12, v[224:225]
	v_lshl_add_u64 v[226:227], s[28:29], 0, v[226:227]
	v_cvt_pk_bf16_f32 v220, v120, v121
	v_cvt_pk_bf16_f32 v221, v122, v123
	v_cvt_pk_bf16_f32 v222, v116, v117
	v_cvt_pk_bf16_f32 v223, v118, v119
	v_lshl_add_u64 v[226:227], v[142:143], 1, v[226:227]
	global_store_dwordx4 v[226:227], v[220:223], off sc0 sc1
.LBB0_2032:
	v_cvt_f32_ubyte0_e32 v227, v216
	v_rcp_iflag_f32_e32 v227, v227
	v_cvt_f32_ubyte0_e32 v145, v218
	v_cvt_f32_ubyte2_e32 v239, v216
	v_cvt_f32_ubyte1_e32 v238, v216
	v_cndmask_b32_e64 v227, v227, v233, s[40:41]
	v_mul_f32_e32 v145, v227, v145
	v_rcp_iflag_f32_e32 v227, v239
	v_cvt_f32_ubyte3_e32 v216, v216
	v_cvt_f32_ubyte2_e32 v221, v218
	v_cvt_f32_ubyte0_e32 v240, v217
	v_rcp_iflag_f32_e32 v216, v216
	v_cndmask_b32_e64 v227, v227, v233, s[40:41]
	v_mul_f32_e32 v221, v227, v221
	v_rcp_iflag_f32_e32 v227, v240
	v_cvt_f32_ubyte1_e32 v220, v218
	v_cvt_f32_ubyte3_e32 v218, v218
	v_cvt_f32_ubyte1_e32 v241, v217
	v_cndmask_b32_e64 v216, v216, v233, s[40:41]
	v_cvt_f32_ubyte0_e32 v222, v219
	v_cvt_f32_ubyte2_e32 v242, v217
	v_cvt_f32_ubyte3_e32 v217, v217
	v_mul_f32_e32 v216, v216, v218
	v_rcp_iflag_f32_e32 v218, v241
	v_cndmask_b32_e64 v227, v227, v233, s[40:41]
	v_rcp_iflag_f32_e32 v238, v238
	v_mul_f32_e32 v222, v227, v222
	v_rcp_iflag_f32_e32 v227, v242
	v_rcp_iflag_f32_e32 v217, v217
	v_cvt_f32_ubyte1_e32 v223, v219
	v_cndmask_b32_e64 v218, v218, v233, s[40:41]
	v_cvt_f32_ubyte2_e32 v226, v219
	v_cvt_f32_ubyte3_e32 v219, v219
	v_cndmask_b32_e64 v238, v238, v233, s[40:41]
	v_mul_f32_e32 v218, v218, v223
	v_cndmask_b32_e64 v223, v227, v233, s[40:41]
	v_cndmask_b32_e64 v217, v217, v233, s[40:41]
	v_mul_f32_e32 v220, v238, v220
	v_mul_f32_e32 v223, v223, v226
	v_mul_f32_e32 v217, v217, v219
	v_mul_f32_e32 v88, v88, v145
	v_mul_f32_e32 v89, v89, v220
	v_mul_f32_e32 v90, v90, v221
	v_mul_f32_e32 v91, v91, v216
	v_mul_f32_e32 v84, v84, v222
	v_mul_f32_e32 v85, v85, v218
	v_mul_f32_e32 v86, v86, v223
	s_and_b64 vcc, exec, s[42:43]
	v_mul_f32_e32 v87, v87, v217
	s_cbranch_vccnz .LBB0_2034
	v_lshlrev_b64 v[220:221], 12, v[224:225]
	v_lshl_add_u64 v[220:221], s[28:29], 0, v[220:221]
	v_cvt_pk_bf16_f32 v216, v88, v89
	v_cvt_pk_bf16_f32 v217, v90, v91
	v_cvt_pk_bf16_f32 v218, v84, v85
	v_cvt_pk_bf16_f32 v219, v86, v87
	v_lshl_add_u64 v[220:221], v[142:143], 1, v[220:221]
	global_store_dwordx4 v[220:221], v[216:219], off offset:256 sc0 sc1
.LBB0_2034:
	v_cvt_f32_ubyte0_e32 v223, v214
	v_rcp_iflag_f32_e32 v223, v223
	v_cvt_f32_ubyte0_e32 v145, v212
	v_cvt_f32_ubyte2_e32 v225, v214
	v_cvt_f32_ubyte1_e32 v224, v214
	v_cndmask_b32_e64 v223, v223, v233, s[40:41]
	v_mul_f32_e32 v145, v223, v145
	v_rcp_iflag_f32_e32 v223, v225
	v_cvt_f32_ubyte3_e32 v214, v214
	v_cvt_f32_ubyte2_e32 v219, v212
	v_cvt_f32_ubyte0_e32 v226, v215
	v_rcp_iflag_f32_e32 v214, v214
	v_cndmask_b32_e64 v223, v223, v233, s[40:41]
	v_mul_f32_e32 v219, v223, v219
	v_rcp_iflag_f32_e32 v223, v226
	v_cvt_f32_ubyte1_e32 v218, v212
	v_cvt_f32_ubyte3_e32 v212, v212
	v_cvt_f32_ubyte1_e32 v227, v215
	v_cndmask_b32_e64 v214, v214, v233, s[40:41]
	v_cvt_f32_ubyte0_e32 v220, v213
	v_cvt_f32_ubyte2_e32 v238, v215
	v_cvt_f32_ubyte3_e32 v215, v215
	v_mul_f32_e32 v212, v214, v212
	v_rcp_iflag_f32_e32 v214, v227
	v_cndmask_b32_e64 v223, v223, v233, s[40:41]
	v_rcp_iflag_f32_e32 v224, v224
	v_mul_f32_e32 v220, v223, v220
	v_rcp_iflag_f32_e32 v223, v238
	v_rcp_iflag_f32_e32 v215, v215
	v_cvt_f32_ubyte1_e32 v221, v213
	v_cndmask_b32_e64 v214, v214, v233, s[40:41]
	v_cvt_f32_ubyte2_e32 v222, v213
	v_cvt_f32_ubyte3_e32 v213, v213
	v_cndmask_b32_e64 v224, v224, v233, s[40:41]
	v_mul_f32_e32 v214, v214, v221
	v_cndmask_b32_e64 v221, v223, v233, s[40:41]
	v_cndmask_b32_e64 v215, v215, v233, s[40:41]
	v_or_b32_e32 v216, 32, v144
	v_mul_f32_e32 v218, v224, v218
	v_mul_f32_e32 v221, v221, v222
	v_mul_f32_e32 v213, v215, v213
	v_ashrrev_i32_e32 v217, 31, v216
	v_mul_f32_e32 v112, v112, v145
	v_mul_f32_e32 v113, v113, v218
	v_mul_f32_e32 v114, v114, v219
	v_mul_f32_e32 v115, v115, v212
	v_mul_f32_e32 v108, v108, v220
	v_mul_f32_e32 v109, v109, v214
	v_mul_f32_e32 v110, v110, v221
	s_and_b64 vcc, exec, s[42:43]
	v_mul_f32_e32 v111, v111, v213
	s_cbranch_vccnz .LBB0_2036
	v_lshlrev_b64 v[218:219], 12, v[216:217]
	v_lshl_add_u64 v[218:219], s[28:29], 0, v[218:219]
	v_cvt_pk_bf16_f32 v212, v112, v113
	v_cvt_pk_bf16_f32 v213, v114, v115
	v_cvt_pk_bf16_f32 v214, v108, v109
	v_cvt_pk_bf16_f32 v215, v110, v111
	v_lshl_add_u64 v[218:219], v[142:143], 1, v[218:219]
	global_store_dwordx4 v[218:219], v[212:215], off sc0 sc1
; __device__ __forceinline__ unsigned cvt_pk_bf16(float lo, float hi) { f32x2c v = {lo, hi}; bf16x2c b = __builtin_convertvector(v, bf16x2c); return __builtin_bit_cast(unsigned, b); }
; __device__ __forceinline__ float ub0(unsigned w) { return (float)(w & 0xFFu); }
; __device__ __forceinline__ float ub1(unsigned w) { return (float)((w >> 8) & 0xFFu); }
; __device__ __forceinline__ float ub2(unsigned w) { return (float)((w >> 16) & 0xFFu); }
; __device__ __forceinline__ float ub3(unsigned w) { return (float)(w >> 24); }
;     __device__ __forceinline__ void operator()(f32x4 (&acc)[2][2][4][2], const Unit& u, int wr, int wc, int fr, int fq) const {
;     ...
;         for (int ai = 0; ai < 2; ++ai) {
; #pragma unroll
;             for (int m = 0; m < 4; ++m)
; #pragma unroll
;                 for (int bj = 0; bj < 2; ++bj) { const u32x2 a = gn[ai][m][bj], d = gd[ai][m][bj];
;                     const float an[8] = {ub0(a.x), ub1(a.x), ub2(a.x), ub3(a.x), ub0(a.y), ub1(a.y), ub2(a.y), ub3(a.y)};
;                     const float dn[8] = {ub0(d.x), ub1(d.x), ub2(d.x), ub3(d.x), ub0(d.y), ub1(d.y), ub2(d.y), ub3(d.y)};
;                     float f[8];
; #pragma unroll
;                     for (int k = 0; k < 8; ++k) { const float rd = __builtin_amdgcn_rcpf(dn[k]); f[k] = an[k] * (fin ? (1.0f / 255.0f) : rd); }
;                     f32x4 v0 = acc[ai][bj][m][0], v1 = acc[ai][bj][m][1];
;                     v0[0] *= f[0]; v0[1] *= f[1]; v0[2] *= f[2]; v0[3] *= f[3]; v1[0] *= f[4]; v1[1] *= f[5]; v1[2] *= f[6]; v1[3] *= f[7];
;                     acc[ai][bj][m][0] = v0; acc[ai][bj][m][1] = v1;
;                     if (fin) { u32x4 w; w.x = cvt_pk_bf16(v0[0], v0[1]); w.y = cvt_pk_bf16(v0[2], v0[3]); w.z = cvt_pk_bf16(v1[0], v1[1]); w.w = cvt_pk_bf16(v1[2], v1[3]);
;                         *(u32x4*)(MO + (size_t)(row0 + ai * HALF + m * 16) * ld + col0 + bj * HALF) = w; } }
.LBB0_2036:
	v_cvt_f32_ubyte0_e32 v219, v208
	v_rcp_iflag_f32_e32 v219, v219
	v_cvt_f32_ubyte0_e32 v145, v210
	v_cvt_f32_ubyte2_e32 v221, v208
	v_cvt_f32_ubyte1_e32 v220, v208
	v_cndmask_b32_e64 v219, v219, v233, s[40:41]
	v_mul_f32_e32 v145, v219, v145
	v_rcp_iflag_f32_e32 v219, v221
	v_cvt_f32_ubyte3_e32 v208, v208
	v_cvt_f32_ubyte2_e32 v213, v210
	v_cvt_f32_ubyte0_e32 v222, v209
	v_rcp_iflag_f32_e32 v208, v208
	v_cndmask_b32_e64 v219, v219, v233, s[40:41]
	v_mul_f32_e32 v213, v219, v213
	v_rcp_iflag_f32_e32 v219, v222
	v_cvt_f32_ubyte1_e32 v212, v210
	v_cvt_f32_ubyte3_e32 v210, v210
	v_cvt_f32_ubyte1_e32 v223, v209
	v_cndmask_b32_e64 v208, v208, v233, s[40:41]
	v_cvt_f32_ubyte0_e32 v214, v211
	v_cvt_f32_ubyte2_e32 v224, v209
	v_cvt_f32_ubyte3_e32 v209, v209
	v_mul_f32_e32 v208, v208, v210
	v_rcp_iflag_f32_e32 v210, v223
	v_cndmask_b32_e64 v219, v219, v233, s[40:41]
	v_rcp_iflag_f32_e32 v220, v220
	v_mul_f32_e32 v214, v219, v214
	v_rcp_iflag_f32_e32 v219, v224
	v_rcp_iflag_f32_e32 v209, v209
	v_cvt_f32_ubyte1_e32 v215, v211
	v_cndmask_b32_e64 v210, v210, v233, s[40:41]
	v_cvt_f32_ubyte2_e32 v218, v211
	v_cvt_f32_ubyte3_e32 v211, v211
	v_cndmask_b32_e64 v220, v220, v233, s[40:41]
	v_mul_f32_e32 v210, v210, v215
	v_cndmask_b32_e64 v215, v219, v233, s[40:41]
	v_cndmask_b32_e64 v209, v209, v233, s[40:41]
	v_mul_f32_e32 v212, v220, v212
	v_mul_f32_e32 v215, v215, v218
	v_mul_f32_e32 v209, v209, v211
	v_mul_f32_e32 v80, v80, v145
	v_mul_f32_e32 v81, v81, v212
	v_mul_f32_e32 v82, v82, v213
	v_mul_f32_e32 v83, v83, v208
	v_mul_f32_e32 v76, v76, v214
	v_mul_f32_e32 v77, v77, v210
	v_mul_f32_e32 v78, v78, v215
	s_and_b64 vcc, exec, s[42:43]
	v_mul_f32_e32 v79, v79, v209
	s_cbranch_vccnz .LBB0_2038
	v_lshlrev_b64 v[212:213], 12, v[216:217]
	v_lshl_add_u64 v[212:213], s[28:29], 0, v[212:213]
	v_cvt_pk_bf16_f32 v208, v80, v81
	v_cvt_pk_bf16_f32 v209, v82, v83
	v_cvt_pk_bf16_f32 v210, v76, v77
	v_cvt_pk_bf16_f32 v211, v78, v79
	v_lshl_add_u64 v[212:213], v[142:143], 1, v[212:213]
	global_store_dwordx4 v[212:213], v[208:211], off offset:256 sc0 sc1
.LBB0_2038:
	s_waitcnt vmcnt(18)
	v_cvt_f32_ubyte0_e32 v215, v206
	v_rcp_iflag_f32_e32 v215, v215
	v_cvt_f32_ubyte0_e32 v145, v204
	v_cvt_f32_ubyte2_e32 v217, v206
	v_cvt_f32_ubyte1_e32 v216, v206
	v_cndmask_b32_e64 v215, v215, v233, s[40:41]
	v_mul_f32_e32 v145, v215, v145
	v_rcp_iflag_f32_e32 v215, v217
	v_cvt_f32_ubyte3_e32 v206, v206
	v_cvt_f32_ubyte2_e32 v211, v204
	v_cvt_f32_ubyte0_e32 v218, v207
	v_rcp_iflag_f32_e32 v206, v206
	v_cndmask_b32_e64 v215, v215, v233, s[40:41]
	v_mul_f32_e32 v211, v215, v211
	v_rcp_iflag_f32_e32 v215, v218
	v_cvt_f32_ubyte1_e32 v210, v204
	v_cvt_f32_ubyte3_e32 v204, v204
	v_cvt_f32_ubyte1_e32 v219, v207
	v_cndmask_b32_e64 v206, v206, v233, s[40:41]
	v_cvt_f32_ubyte0_e32 v212, v205
	v_cvt_f32_ubyte2_e32 v220, v207
	v_cvt_f32_ubyte3_e32 v207, v207
	v_mul_f32_e32 v204, v206, v204
	v_rcp_iflag_f32_e32 v206, v219
	v_cndmask_b32_e64 v215, v215, v233, s[40:41]
	v_rcp_iflag_f32_e32 v216, v216
	v_mul_f32_e32 v212, v215, v212
	v_rcp_iflag_f32_e32 v215, v220
	v_rcp_iflag_f32_e32 v207, v207
	v_cvt_f32_ubyte1_e32 v213, v205
	v_cndmask_b32_e64 v206, v206, v233, s[40:41]
	v_cvt_f32_ubyte2_e32 v214, v205
	v_cvt_f32_ubyte3_e32 v205, v205
	v_cndmask_b32_e64 v216, v216, v233, s[40:41]
	v_mul_f32_e32 v206, v206, v213
	v_cndmask_b32_e64 v213, v215, v233, s[40:41]
	v_cndmask_b32_e64 v207, v207, v233, s[40:41]
	v_or_b32_e32 v208, 48, v144
	v_mul_f32_e32 v210, v216, v210
	v_mul_f32_e32 v213, v213, v214
	v_mul_f32_e32 v205, v207, v205
	v_ashrrev_i32_e32 v209, 31, v208
	v_mul_f32_e32 v104, v104, v145
	v_mul_f32_e32 v105, v105, v210
	v_mul_f32_e32 v106, v106, v211
	v_mul_f32_e32 v107, v107, v204
	v_mul_f32_e32 v100, v100, v212
	v_mul_f32_e32 v101, v101, v206
	v_mul_f32_e32 v102, v102, v213
	s_and_b64 vcc, exec, s[42:43]
	v_mul_f32_e32 v103, v103, v205
	s_cbranch_vccnz .LBB0_2040
	v_lshlrev_b64 v[210:211], 12, v[208:209]
	v_lshl_add_u64 v[210:211], s[28:29], 0, v[210:211]
	v_cvt_pk_bf16_f32 v204, v104, v105
	v_cvt_pk_bf16_f32 v205, v106, v107
	v_cvt_pk_bf16_f32 v206, v100, v101
	v_cvt_pk_bf16_f32 v207, v102, v103
	v_lshl_add_u64 v[210:211], v[142:143], 1, v[210:211]
	global_store_dwordx4 v[210:211], v[204:207], off sc0 sc1
.LBB0_2040:
	s_waitcnt vmcnt(16)
	v_cvt_f32_ubyte0_e32 v211, v200
	v_rcp_iflag_f32_e32 v211, v211
	v_cvt_f32_ubyte0_e32 v145, v202
	v_cvt_f32_ubyte2_e32 v213, v200
	v_cvt_f32_ubyte1_e32 v212, v200
	v_cndmask_b32_e64 v211, v211, v233, s[40:41]
	v_mul_f32_e32 v145, v211, v145
	v_rcp_iflag_f32_e32 v211, v213
	v_cvt_f32_ubyte3_e32 v200, v200
	v_cvt_f32_ubyte2_e32 v205, v202
	v_cvt_f32_ubyte0_e32 v214, v201
	v_rcp_iflag_f32_e32 v200, v200
	v_cndmask_b32_e64 v211, v211, v233, s[40:41]
	v_mul_f32_e32 v205, v211, v205
	v_rcp_iflag_f32_e32 v211, v214
	v_cvt_f32_ubyte1_e32 v204, v202
	v_cvt_f32_ubyte3_e32 v202, v202
	v_cvt_f32_ubyte1_e32 v215, v201
	v_cndmask_b32_e64 v200, v200, v233, s[40:41]
	v_cvt_f32_ubyte0_e32 v206, v203
	v_cvt_f32_ubyte2_e32 v216, v201
	v_cvt_f32_ubyte3_e32 v201, v201
	v_mul_f32_e32 v200, v200, v202
	v_rcp_iflag_f32_e32 v202, v215
	v_cndmask_b32_e64 v211, v211, v233, s[40:41]
	v_rcp_iflag_f32_e32 v212, v212
	v_mul_f32_e32 v206, v211, v206
	v_rcp_iflag_f32_e32 v211, v216
	v_rcp_iflag_f32_e32 v201, v201
	v_cvt_f32_ubyte1_e32 v207, v203
	v_cndmask_b32_e64 v202, v202, v233, s[40:41]
	v_cvt_f32_ubyte2_e32 v210, v203
	v_cvt_f32_ubyte3_e32 v203, v203
	v_cndmask_b32_e64 v212, v212, v233, s[40:41]
	v_mul_f32_e32 v202, v202, v207
	v_cndmask_b32_e64 v207, v211, v233, s[40:41]
	v_cndmask_b32_e64 v201, v201, v233, s[40:41]
	v_mul_f32_e32 v204, v212, v204
	v_mul_f32_e32 v207, v207, v210
	v_mul_f32_e32 v201, v201, v203
	v_mul_f32_e32 v72, v72, v145
	v_mul_f32_e32 v73, v73, v204
	v_mul_f32_e32 v74, v74, v205
	v_mul_f32_e32 v75, v75, v200
	v_mul_f32_e32 v68, v68, v206
	v_mul_f32_e32 v69, v69, v202
	v_mul_f32_e32 v70, v70, v207
	s_and_b64 vcc, exec, s[42:43]
	v_mul_f32_e32 v71, v71, v201
	s_cbranch_vccnz .LBB0_2042
	v_lshlrev_b64 v[204:205], 12, v[208:209]
	v_lshl_add_u64 v[204:205], s[28:29], 0, v[204:205]
	v_cvt_pk_bf16_f32 v200, v72, v73
	v_cvt_pk_bf16_f32 v201, v74, v75
	v_cvt_pk_bf16_f32 v202, v68, v69
	v_cvt_pk_bf16_f32 v203, v70, v71
	v_lshl_add_u64 v[204:205], v[142:143], 1, v[204:205]
	global_store_dwordx4 v[204:205], v[200:203], off offset:256 sc0 sc1
; __device__ __forceinline__ unsigned cvt_pk_bf16(float lo, float hi) { f32x2c v = {lo, hi}; bf16x2c b = __builtin_convertvector(v, bf16x2c); return __builtin_bit_cast(unsigned, b); }
; __device__ __forceinline__ float ub0(unsigned w) { return (float)(w & 0xFFu); }
; __device__ __forceinline__ float ub1(unsigned w) { return (float)((w >> 8) & 0xFFu); }
; __device__ __forceinline__ float ub2(unsigned w) { return (float)((w >> 16) & 0xFFu); }
; __device__ __forceinline__ float ub3(unsigned w) { return (float)(w >> 24); }
;     __device__ __forceinline__ void operator()(f32x4 (&acc)[2][2][4][2], const Unit& u, int wr, int wc, int fr, int fq) const {
;     ...
;         for (int ai = 0; ai < 2; ++ai) {
; #pragma unroll
;             for (int m = 0; m < 4; ++m)
; #pragma unroll
;                 for (int bj = 0; bj < 2; ++bj) { const u32x2 a = gn[ai][m][bj], d = gd[ai][m][bj];
;                     const float an[8] = {ub0(a.x), ub1(a.x), ub2(a.x), ub3(a.x), ub0(a.y), ub1(a.y), ub2(a.y), ub3(a.y)};
;                     const float dn[8] = {ub0(d.x), ub1(d.x), ub2(d.x), ub3(d.x), ub0(d.y), ub1(d.y), ub2(d.y), ub3(d.y)};
;                     float f[8];
; #pragma unroll
;                     for (int k = 0; k < 8; ++k) { const float rd = __builtin_amdgcn_rcpf(dn[k]); f[k] = an[k] * (fin ? (1.0f / 255.0f) : rd); }
;                     f32x4 v0 = acc[ai][bj][m][0], v1 = acc[ai][bj][m][1];
;                     v0[0] *= f[0]; v0[1] *= f[1]; v0[2] *= f[2]; v0[3] *= f[3]; v1[0] *= f[4]; v1[1] *= f[5]; v1[2] *= f[6]; v1[3] *= f[7];
;                     acc[ai][bj][m][0] = v0; acc[ai][bj][m][1] = v1;
;                     if (fin) { u32x4 w; w.x = cvt_pk_bf16(v0[0], v0[1]); w.y = cvt_pk_bf16(v0[2], v0[3]); w.z = cvt_pk_bf16(v1[0], v1[1]); w.w = cvt_pk_bf16(v1[2], v1[3]);
;                         *(u32x4*)(MO + (size_t)(row0 + ai * HALF + m * 16) * ld + col0 + bj * HALF) = w; } }
.LBB0_2042:
	s_waitcnt vmcnt(14)
	v_cvt_f32_ubyte0_e32 v207, v198
	v_rcp_iflag_f32_e32 v207, v207
	v_cvt_f32_ubyte0_e32 v145, v196
	v_cvt_f32_ubyte2_e32 v209, v198
	v_cvt_f32_ubyte1_e32 v208, v198
	v_cndmask_b32_e64 v207, v207, v233, s[40:41]
	v_mul_f32_e32 v145, v207, v145
	v_rcp_iflag_f32_e32 v207, v209
	v_cvt_f32_ubyte3_e32 v198, v198
	v_cvt_f32_ubyte2_e32 v203, v196
	v_cvt_f32_ubyte0_e32 v210, v199
	v_rcp_iflag_f32_e32 v198, v198
	v_cndmask_b32_e64 v207, v207, v233, s[40:41]
	v_mul_f32_e32 v203, v207, v203
	v_rcp_iflag_f32_e32 v207, v210
	v_cvt_f32_ubyte1_e32 v202, v196
	v_cvt_f32_ubyte3_e32 v196, v196
	v_cvt_f32_ubyte1_e32 v211, v199
	v_cndmask_b32_e64 v198, v198, v233, s[40:41]
	v_cvt_f32_ubyte0_e32 v204, v197
	v_cvt_f32_ubyte2_e32 v212, v199
	v_cvt_f32_ubyte3_e32 v199, v199
	v_mul_f32_e32 v196, v198, v196
	v_rcp_iflag_f32_e32 v198, v211
	v_cndmask_b32_e64 v207, v207, v233, s[40:41]
	v_rcp_iflag_f32_e32 v208, v208
	v_mul_f32_e32 v204, v207, v204
	v_rcp_iflag_f32_e32 v207, v212
	v_rcp_iflag_f32_e32 v199, v199
	v_cvt_f32_ubyte1_e32 v205, v197
	v_cndmask_b32_e64 v198, v198, v233, s[40:41]
	v_cvt_f32_ubyte2_e32 v206, v197
	v_cvt_f32_ubyte3_e32 v197, v197
	v_cndmask_b32_e64 v208, v208, v233, s[40:41]
	v_mul_f32_e32 v198, v198, v205
	v_cndmask_b32_e64 v205, v207, v233, s[40:41]
	v_cndmask_b32_e64 v199, v199, v233, s[40:41]
	v_add_u32_e32 v200, 0x80, v144
	v_mul_f32_e32 v202, v208, v202
	v_mul_f32_e32 v205, v205, v206
	v_mul_f32_e32 v197, v199, v197
	v_ashrrev_i32_e32 v201, 31, v200
	v_mul_f32_e32 v64, v64, v145
	v_mul_f32_e32 v65, v65, v202
	v_mul_f32_e32 v66, v66, v203
	v_mul_f32_e32 v67, v67, v196
	v_mul_f32_e32 v60, v60, v204
	v_mul_f32_e32 v61, v61, v198
	v_mul_f32_e32 v62, v62, v205
	s_and_b64 vcc, exec, s[42:43]
	v_mul_f32_e32 v63, v63, v197
	s_cbranch_vccnz .LBB0_2044
	v_lshlrev_b64 v[202:203], 12, v[200:201]
	v_lshl_add_u64 v[202:203], s[28:29], 0, v[202:203]
	v_cvt_pk_bf16_f32 v196, v64, v65
	v_cvt_pk_bf16_f32 v197, v66, v67
	v_cvt_pk_bf16_f32 v198, v60, v61
	v_cvt_pk_bf16_f32 v199, v62, v63
	v_lshl_add_u64 v[202:203], v[142:143], 1, v[202:203]
	global_store_dwordx4 v[202:203], v[196:199], off sc0 sc1
.LBB0_2044:
	s_waitcnt vmcnt(12)
	v_cvt_f32_ubyte0_e32 v203, v192
	v_rcp_iflag_f32_e32 v203, v203
	v_cvt_f32_ubyte0_e32 v145, v194
	v_cvt_f32_ubyte2_e32 v205, v192
	v_cvt_f32_ubyte1_e32 v204, v192
	v_cndmask_b32_e64 v203, v203, v233, s[40:41]
	v_mul_f32_e32 v145, v203, v145
	v_rcp_iflag_f32_e32 v203, v205
	v_cvt_f32_ubyte3_e32 v192, v192
	v_cvt_f32_ubyte2_e32 v197, v194
	v_cvt_f32_ubyte0_e32 v206, v193
	v_rcp_iflag_f32_e32 v192, v192
	v_cndmask_b32_e64 v203, v203, v233, s[40:41]
	v_mul_f32_e32 v197, v203, v197
	v_rcp_iflag_f32_e32 v203, v206
	v_cvt_f32_ubyte1_e32 v196, v194
	v_cvt_f32_ubyte3_e32 v194, v194
	v_cvt_f32_ubyte1_e32 v207, v193
	v_cndmask_b32_e64 v192, v192, v233, s[40:41]
	v_cvt_f32_ubyte0_e32 v198, v195
	v_cvt_f32_ubyte2_e32 v208, v193
	v_cvt_f32_ubyte3_e32 v193, v193
	v_mul_f32_e32 v192, v192, v194
	v_rcp_iflag_f32_e32 v194, v207
	v_cndmask_b32_e64 v203, v203, v233, s[40:41]
	v_rcp_iflag_f32_e32 v204, v204
	v_mul_f32_e32 v198, v203, v198
	v_rcp_iflag_f32_e32 v203, v208
	v_rcp_iflag_f32_e32 v193, v193
	v_cvt_f32_ubyte1_e32 v199, v195
	v_cndmask_b32_e64 v194, v194, v233, s[40:41]
	v_cvt_f32_ubyte2_e32 v202, v195
	v_cvt_f32_ubyte3_e32 v195, v195
	v_cndmask_b32_e64 v204, v204, v233, s[40:41]
	v_mul_f32_e32 v194, v194, v199
	v_cndmask_b32_e64 v199, v203, v233, s[40:41]
	v_cndmask_b32_e64 v193, v193, v233, s[40:41]
	v_mul_f32_e32 v196, v204, v196
	v_mul_f32_e32 v199, v199, v202
	v_mul_f32_e32 v193, v193, v195
	v_mul_f32_e32 v30, v30, v145
	v_mul_f32_e32 v31, v31, v196
	v_mul_f32_e32 v32, v32, v197
	v_mul_f32_e32 v33, v33, v192
	v_mul_f32_e32 v26, v26, v198
	v_mul_f32_e32 v27, v27, v194
	v_mul_f32_e32 v28, v28, v199
	s_and_b64 vcc, exec, s[42:43]
	v_mul_f32_e32 v29, v29, v193
	s_cbranch_vccnz .LBB0_2046
	v_lshlrev_b64 v[196:197], 12, v[200:201]
	v_lshl_add_u64 v[196:197], s[28:29], 0, v[196:197]
	v_cvt_pk_bf16_f32 v192, v30, v31
	v_cvt_pk_bf16_f32 v193, v32, v33
	v_cvt_pk_bf16_f32 v194, v26, v27
	v_cvt_pk_bf16_f32 v195, v28, v29
	v_lshl_add_u64 v[196:197], v[142:143], 1, v[196:197]
	global_store_dwordx4 v[196:197], v[192:195], off offset:256 sc0 sc1
.LBB0_2046:
	s_waitcnt vmcnt(10)
	v_cvt_f32_ubyte0_e32 v199, v190
	v_rcp_iflag_f32_e32 v199, v199
	v_cvt_f32_ubyte0_e32 v145, v188
	v_cvt_f32_ubyte2_e32 v201, v190
	v_cvt_f32_ubyte1_e32 v200, v190
	v_cndmask_b32_e64 v199, v199, v233, s[40:41]
	v_mul_f32_e32 v145, v199, v145
	v_rcp_iflag_f32_e32 v199, v201
	v_cvt_f32_ubyte3_e32 v190, v190
	v_cvt_f32_ubyte2_e32 v195, v188
	v_cvt_f32_ubyte0_e32 v202, v191
	v_rcp_iflag_f32_e32 v190, v190
	v_cndmask_b32_e64 v199, v199, v233, s[40:41]
	v_mul_f32_e32 v195, v199, v195
	v_rcp_iflag_f32_e32 v199, v202
	v_cvt_f32_ubyte1_e32 v194, v188
	v_cvt_f32_ubyte3_e32 v188, v188
	v_cvt_f32_ubyte1_e32 v203, v191
	v_cndmask_b32_e64 v190, v190, v233, s[40:41]
	v_cvt_f32_ubyte0_e32 v196, v189
	v_cvt_f32_ubyte2_e32 v204, v191
	v_cvt_f32_ubyte3_e32 v191, v191
	v_mul_f32_e32 v188, v190, v188
	v_rcp_iflag_f32_e32 v190, v203
	v_cndmask_b32_e64 v199, v199, v233, s[40:41]
	v_rcp_iflag_f32_e32 v200, v200
	v_mul_f32_e32 v196, v199, v196
	v_rcp_iflag_f32_e32 v199, v204
	v_rcp_iflag_f32_e32 v191, v191
	v_cvt_f32_ubyte1_e32 v197, v189
	v_cndmask_b32_e64 v190, v190, v233, s[40:41]
	v_cvt_f32_ubyte2_e32 v198, v189
	v_cvt_f32_ubyte3_e32 v189, v189
	v_cndmask_b32_e64 v200, v200, v233, s[40:41]
	v_mul_f32_e32 v190, v190, v197
	v_cndmask_b32_e64 v197, v199, v233, s[40:41]
	v_cndmask_b32_e64 v191, v191, v233, s[40:41]
	v_add_u32_e32 v192, 0x90, v144
	v_mul_f32_e32 v194, v200, v194
	v_mul_f32_e32 v197, v197, v198
	v_mul_f32_e32 v189, v191, v189
	v_ashrrev_i32_e32 v193, 31, v192
	v_mul_f32_e32 v56, v56, v145
	v_mul_f32_e32 v57, v57, v194
	v_mul_f32_e32 v58, v58, v195
	v_mul_f32_e32 v59, v59, v188
	v_mul_f32_e32 v52, v52, v196
	v_mul_f32_e32 v53, v53, v190
	v_mul_f32_e32 v54, v54, v197
	s_and_b64 vcc, exec, s[42:43]
	v_mul_f32_e32 v55, v55, v189
	s_cbranch_vccnz .LBB0_2048
	v_lshlrev_b64 v[194:195], 12, v[192:193]
	v_lshl_add_u64 v[194:195], s[28:29], 0, v[194:195]
	v_cvt_pk_bf16_f32 v188, v56, v57
	v_cvt_pk_bf16_f32 v189, v58, v59
	v_cvt_pk_bf16_f32 v190, v52, v53
	v_cvt_pk_bf16_f32 v191, v54, v55
	v_lshl_add_u64 v[194:195], v[142:143], 1, v[194:195]
	global_store_dwordx4 v[194:195], v[188:191], off sc0 sc1
; __device__ __forceinline__ unsigned cvt_pk_bf16(float lo, float hi) { f32x2c v = {lo, hi}; bf16x2c b = __builtin_convertvector(v, bf16x2c); return __builtin_bit_cast(unsigned, b); }
; __device__ __forceinline__ float ub0(unsigned w) { return (float)(w & 0xFFu); }
; __device__ __forceinline__ float ub1(unsigned w) { return (float)((w >> 8) & 0xFFu); }
; __device__ __forceinline__ float ub2(unsigned w) { return (float)((w >> 16) & 0xFFu); }
; __device__ __forceinline__ float ub3(unsigned w) { return (float)(w >> 24); }
;     __device__ __forceinline__ void operator()(f32x4 (&acc)[2][2][4][2], const Unit& u, int wr, int wc, int fr, int fq) const {
;     ...
;         for (int ai = 0; ai < 2; ++ai) {
; #pragma unroll
;             for (int m = 0; m < 4; ++m)
; #pragma unroll
;                 for (int bj = 0; bj < 2; ++bj) { const u32x2 a = gn[ai][m][bj], d = gd[ai][m][bj];
;                     const float an[8] = {ub0(a.x), ub1(a.x), ub2(a.x), ub3(a.x), ub0(a.y), ub1(a.y), ub2(a.y), ub3(a.y)};
;                     const float dn[8] = {ub0(d.x), ub1(d.x), ub2(d.x), ub3(d.x), ub0(d.y), ub1(d.y), ub2(d.y), ub3(d.y)};
;                     float f[8];
; #pragma unroll
;                     for (int k = 0; k < 8; ++k) { const float rd = __builtin_amdgcn_rcpf(dn[k]); f[k] = an[k] * (fin ? (1.0f / 255.0f) : rd); }
;                     f32x4 v0 = acc[ai][bj][m][0], v1 = acc[ai][bj][m][1];
;                     v0[0] *= f[0]; v0[1] *= f[1]; v0[2] *= f[2]; v0[3] *= f[3]; v1[0] *= f[4]; v1[1] *= f[5]; v1[2] *= f[6]; v1[3] *= f[7];
;                     acc[ai][bj][m][0] = v0; acc[ai][bj][m][1] = v1;
;                     if (fin) { u32x4 w; w.x = cvt_pk_bf16(v0[0], v0[1]); w.y = cvt_pk_bf16(v0[2], v0[3]); w.z = cvt_pk_bf16(v1[0], v1[1]); w.w = cvt_pk_bf16(v1[2], v1[3]);
;                         *(u32x4*)(MO + (size_t)(row0 + ai * HALF + m * 16) * ld + col0 + bj * HALF) = w; } }
.LBB0_2048:
	s_waitcnt vmcnt(8)
	v_cvt_f32_ubyte0_e32 v195, v162
	v_rcp_iflag_f32_e32 v195, v195
	v_cvt_f32_ubyte0_e32 v145, v186
	v_cvt_f32_ubyte2_e32 v197, v162
	v_cvt_f32_ubyte1_e32 v196, v162
	v_cndmask_b32_e64 v195, v195, v233, s[40:41]
	v_mul_f32_e32 v145, v195, v145
	v_rcp_iflag_f32_e32 v195, v197
	v_cvt_f32_ubyte3_e32 v162, v162
	v_cvt_f32_ubyte2_e32 v189, v186
	v_cvt_f32_ubyte0_e32 v198, v163
	v_rcp_iflag_f32_e32 v162, v162
	v_cndmask_b32_e64 v195, v195, v233, s[40:41]
	v_mul_f32_e32 v189, v195, v189
	v_rcp_iflag_f32_e32 v195, v198
	v_cvt_f32_ubyte1_e32 v188, v186
	v_cvt_f32_ubyte3_e32 v186, v186
	v_cvt_f32_ubyte1_e32 v199, v163
	v_cndmask_b32_e64 v162, v162, v233, s[40:41]
	v_cvt_f32_ubyte0_e32 v190, v187
	v_cvt_f32_ubyte2_e32 v200, v163
	v_cvt_f32_ubyte3_e32 v163, v163
	v_mul_f32_e32 v162, v162, v186
	v_rcp_iflag_f32_e32 v186, v199
	v_cndmask_b32_e64 v195, v195, v233, s[40:41]
	v_rcp_iflag_f32_e32 v196, v196
	v_mul_f32_e32 v190, v195, v190
	v_rcp_iflag_f32_e32 v195, v200
	v_rcp_iflag_f32_e32 v163, v163
	v_cvt_f32_ubyte1_e32 v191, v187
	v_cndmask_b32_e64 v186, v186, v233, s[40:41]
	v_cvt_f32_ubyte2_e32 v194, v187
	v_cvt_f32_ubyte3_e32 v187, v187
	v_cndmask_b32_e64 v196, v196, v233, s[40:41]
	v_mul_f32_e32 v186, v186, v191
	v_cndmask_b32_e64 v191, v195, v233, s[40:41]
	v_cndmask_b32_e64 v163, v163, v233, s[40:41]
	v_mul_f32_e32 v188, v196, v188
	v_mul_f32_e32 v191, v191, v194
	v_mul_f32_e32 v163, v163, v187
	v_mul_f32_e32 v22, v22, v145
	v_mul_f32_e32 v23, v23, v188
	v_mul_f32_e32 v24, v24, v189
	v_mul_f32_e32 v25, v25, v162
	v_mul_f32_e32 v18, v18, v190
	v_mul_f32_e32 v19, v19, v186
	v_mul_f32_e32 v20, v20, v191
	s_and_b64 vcc, exec, s[42:43]
	v_mul_f32_e32 v21, v21, v163
	s_cbranch_vccnz .LBB0_2050
	v_lshlrev_b64 v[162:163], 12, v[192:193]
	v_lshl_add_u64 v[162:163], s[28:29], 0, v[162:163]
	v_cvt_pk_bf16_f32 v186, v22, v23
	v_cvt_pk_bf16_f32 v187, v24, v25
	v_cvt_pk_bf16_f32 v188, v18, v19
	v_cvt_pk_bf16_f32 v189, v20, v21
	v_lshl_add_u64 v[162:163], v[142:143], 1, v[162:163]
	global_store_dwordx4 v[162:163], v[186:189], off offset:256 sc0 sc1
.LBB0_2050:
	s_waitcnt vmcnt(6)
	v_cvt_f32_ubyte0_e32 v191, v160
	v_rcp_iflag_f32_e32 v191, v191
	v_cvt_f32_ubyte0_e32 v145, v158
	v_cvt_f32_ubyte2_e32 v193, v160
	v_cvt_f32_ubyte1_e32 v192, v160
	v_cndmask_b32_e64 v191, v191, v233, s[40:41]
	v_mul_f32_e32 v145, v191, v145
	v_rcp_iflag_f32_e32 v191, v193
	v_cvt_f32_ubyte3_e32 v160, v160
	v_cvt_f32_ubyte2_e32 v187, v158
	v_cvt_f32_ubyte0_e32 v194, v161
	v_rcp_iflag_f32_e32 v160, v160
	v_cndmask_b32_e64 v191, v191, v233, s[40:41]
	v_mul_f32_e32 v187, v191, v187
	v_rcp_iflag_f32_e32 v191, v194
	v_cvt_f32_ubyte1_e32 v186, v158
	v_cvt_f32_ubyte3_e32 v158, v158
	v_cvt_f32_ubyte1_e32 v195, v161
	v_cndmask_b32_e64 v160, v160, v233, s[40:41]
	v_cvt_f32_ubyte0_e32 v188, v159
	v_cvt_f32_ubyte2_e32 v196, v161
	v_cvt_f32_ubyte3_e32 v161, v161
	v_mul_f32_e32 v158, v160, v158
	v_rcp_iflag_f32_e32 v160, v195
	v_cndmask_b32_e64 v191, v191, v233, s[40:41]
	v_rcp_iflag_f32_e32 v192, v192
	v_mul_f32_e32 v188, v191, v188
	v_rcp_iflag_f32_e32 v191, v196
	v_rcp_iflag_f32_e32 v161, v161
	v_cvt_f32_ubyte1_e32 v189, v159
	v_cndmask_b32_e64 v160, v160, v233, s[40:41]
	v_cvt_f32_ubyte2_e32 v190, v159
	v_cvt_f32_ubyte3_e32 v159, v159
	v_cndmask_b32_e64 v192, v192, v233, s[40:41]
	v_mul_f32_e32 v160, v160, v189
	v_cndmask_b32_e64 v189, v191, v233, s[40:41]
	v_cndmask_b32_e64 v161, v161, v233, s[40:41]
	v_add_u32_e32 v162, 0xa0, v144
	v_mul_f32_e32 v186, v192, v186
	v_mul_f32_e32 v189, v189, v190
	v_mul_f32_e32 v159, v161, v159
	v_ashrrev_i32_e32 v163, 31, v162
	v_mul_f32_e32 v48, v48, v145
	v_mul_f32_e32 v49, v49, v186
	v_mul_f32_e32 v50, v50, v187
	v_mul_f32_e32 v51, v51, v158
	v_mul_f32_e32 v44, v44, v188
	v_mul_f32_e32 v45, v45, v160
	v_mul_f32_e32 v46, v46, v189
	s_and_b64 vcc, exec, s[42:43]
	v_mul_f32_e32 v47, v47, v159
	s_cbranch_vccnz .LBB0_2052
	v_lshlrev_b64 v[186:187], 12, v[162:163]
	v_lshl_add_u64 v[186:187], s[28:29], 0, v[186:187]
	v_cvt_pk_bf16_f32 v158, v48, v49
	v_cvt_pk_bf16_f32 v159, v50, v51
	v_cvt_pk_bf16_f32 v160, v44, v45
	v_cvt_pk_bf16_f32 v161, v46, v47
	v_lshl_add_u64 v[186:187], v[142:143], 1, v[186:187]
	global_store_dwordx4 v[186:187], v[158:161], off sc0 sc1
.LBB0_2052:
	s_waitcnt vmcnt(4)
	v_cvt_f32_ubyte0_e32 v187, v154
	v_rcp_iflag_f32_e32 v187, v187
	v_cvt_f32_ubyte0_e32 v145, v156
	v_cvt_f32_ubyte2_e32 v189, v154
	v_cvt_f32_ubyte1_e32 v188, v154
	v_cndmask_b32_e64 v187, v187, v233, s[40:41]
	v_mul_f32_e32 v145, v187, v145
	v_rcp_iflag_f32_e32 v187, v189
	v_cvt_f32_ubyte3_e32 v154, v154
	v_cvt_f32_ubyte2_e32 v159, v156
	v_cvt_f32_ubyte0_e32 v190, v155
	v_rcp_iflag_f32_e32 v154, v154
	v_cndmask_b32_e64 v187, v187, v233, s[40:41]
	v_mul_f32_e32 v159, v187, v159
	v_rcp_iflag_f32_e32 v187, v190
	v_cvt_f32_ubyte1_e32 v158, v156
	v_cvt_f32_ubyte3_e32 v156, v156
	v_cvt_f32_ubyte1_e32 v191, v155
	v_cndmask_b32_e64 v154, v154, v233, s[40:41]
	v_cvt_f32_ubyte0_e32 v160, v157
	v_cvt_f32_ubyte2_e32 v192, v155
	v_cvt_f32_ubyte3_e32 v155, v155
	v_mul_f32_e32 v154, v154, v156
	v_rcp_iflag_f32_e32 v156, v191
	v_cndmask_b32_e64 v187, v187, v233, s[40:41]
	v_rcp_iflag_f32_e32 v188, v188
	v_mul_f32_e32 v160, v187, v160
	v_rcp_iflag_f32_e32 v187, v192
	v_rcp_iflag_f32_e32 v155, v155
	v_cvt_f32_ubyte1_e32 v161, v157
	v_cndmask_b32_e64 v156, v156, v233, s[40:41]
	v_cvt_f32_ubyte2_e32 v186, v157
	v_cvt_f32_ubyte3_e32 v157, v157
	v_cndmask_b32_e64 v188, v188, v233, s[40:41]
	v_mul_f32_e32 v156, v156, v161
	v_cndmask_b32_e64 v161, v187, v233, s[40:41]
	v_cndmask_b32_e64 v155, v155, v233, s[40:41]
	v_mul_f32_e32 v158, v188, v158
	v_mul_f32_e32 v161, v161, v186
	v_mul_f32_e32 v155, v155, v157
	v_mul_f32_e32 v14, v14, v145
	v_mul_f32_e32 v15, v15, v158
	v_mul_f32_e32 v16, v16, v159
	v_mul_f32_e32 v17, v17, v154
	v_mul_f32_e32 v10, v10, v160
	v_mul_f32_e32 v11, v11, v156
	v_mul_f32_e32 v12, v12, v161
	s_and_b64 vcc, exec, s[42:43]
	v_mul_f32_e32 v13, v13, v155
	s_cbranch_vccnz .LBB0_2054
	v_lshlrev_b64 v[158:159], 12, v[162:163]
	v_lshl_add_u64 v[158:159], s[28:29], 0, v[158:159]
	v_cvt_pk_bf16_f32 v154, v14, v15
	v_cvt_pk_bf16_f32 v155, v16, v17
	v_cvt_pk_bf16_f32 v156, v10, v11
	v_cvt_pk_bf16_f32 v157, v12, v13
	v_lshl_add_u64 v[158:159], v[142:143], 1, v[158:159]
	global_store_dwordx4 v[158:159], v[154:157], off offset:256 sc0 sc1
; __device__ __forceinline__ unsigned cvt_pk_bf16(float lo, float hi) { f32x2c v = {lo, hi}; bf16x2c b = __builtin_convertvector(v, bf16x2c); return __builtin_bit_cast(unsigned, b); }
; __device__ __forceinline__ float ub0(unsigned w) { return (float)(w & 0xFFu); }
; __device__ __forceinline__ float ub1(unsigned w) { return (float)((w >> 8) & 0xFFu); }
; __device__ __forceinline__ float ub2(unsigned w) { return (float)((w >> 16) & 0xFFu); }
; __device__ __forceinline__ float ub3(unsigned w) { return (float)(w >> 24); }
;     __device__ __forceinline__ void operator()(f32x4 (&acc)[2][2][4][2], const Unit& u, int wr, int wc, int fr, int fq) const {
;     ...
;                 for (int bj = 0; bj < 2; ++bj) { const u32x2 a = gn[ai][m][bj], d = gd[ai][m][bj];
;                     const float an[8] = {ub0(a.x), ub1(a.x), ub2(a.x), ub3(a.x), ub0(a.y), ub1(a.y), ub2(a.y), ub3(a.y)};
;                     const float dn[8] = {ub0(d.x), ub1(d.x), ub2(d.x), ub3(d.x), ub0(d.y), ub1(d.y), ub2(d.y), ub3(d.y)};
;                     float f[8];
; #pragma unroll
;                     for (int k = 0; k < 8; ++k) { const float rd = __builtin_amdgcn_rcpf(dn[k]); f[k] = an[k] * (fin ? (1.0f / 255.0f) : rd); }
;                     f32x4 v0 = acc[ai][bj][m][0], v1 = acc[ai][bj][m][1];
;                     v0[0] *= f[0]; v0[1] *= f[1]; v0[2] *= f[2]; v0[3] *= f[3]; v1[0] *= f[4]; v1[1] *= f[5]; v1[2] *= f[6]; v1[3] *= f[7];
;                     acc[ai][bj][m][0] = v0; acc[ai][bj][m][1] = v1;
;                     if (fin) { u32x4 w; w.x = cvt_pk_bf16(v0[0], v0[1]); w.y = cvt_pk_bf16(v0[2], v0[3]); w.z = cvt_pk_bf16(v1[0], v1[1]); w.w = cvt_pk_bf16(v1[2], v1[3]);
;                         *(u32x4*)(MO + (size_t)(row0 + ai * HALF + m * 16) * ld + col0 + bj * HALF) = w; } }
;     ...
;         if (!Epi::SEGMENTED || cur.seg == 2)
; #pragma unroll
;         for (int a = 0; a < 2; ++a)
; #pragma unroll
;             for (int b = 0; b < 2; ++b)
; #pragma unroll
;                 for (int m = 0; m < 4; ++m)
; #pragma unroll
;                     for (int n = 0; n < 2; ++n) acc[a][b][m][n] = (f32x4){0.f, 0.f, 0.f, 0.f};
.LBB0_2054:
	s_waitcnt vmcnt(2)
	v_cvt_f32_ubyte0_e32 v160, v152
	v_rcp_iflag_f32_e32 v160, v160
	v_cvt_f32_ubyte0_e32 v154, v150
	v_cvt_f32_ubyte2_e32 v162, v152
	v_cvt_f32_ubyte1_e32 v161, v152
	v_cndmask_b32_e64 v160, v160, v233, s[40:41]
	v_mul_f32_e32 v154, v160, v154
	v_rcp_iflag_f32_e32 v160, v162
	v_cvt_f32_ubyte3_e32 v152, v152
	v_cvt_f32_ubyte2_e32 v156, v150
	v_cvt_f32_ubyte0_e32 v163, v153
	v_rcp_iflag_f32_e32 v152, v152
	v_cndmask_b32_e64 v160, v160, v233, s[40:41]
	v_mul_f32_e32 v156, v160, v156
	v_rcp_iflag_f32_e32 v160, v163
	v_cvt_f32_ubyte1_e32 v155, v150
	v_cvt_f32_ubyte3_e32 v150, v150
	v_cvt_f32_ubyte1_e32 v186, v153
	v_cndmask_b32_e64 v152, v152, v233, s[40:41]
	v_cvt_f32_ubyte0_e32 v157, v151
	v_cvt_f32_ubyte2_e32 v187, v153
	v_cvt_f32_ubyte3_e32 v153, v153
	v_mul_f32_e32 v150, v152, v150
	v_rcp_iflag_f32_e32 v152, v186
	v_cndmask_b32_e64 v160, v160, v233, s[40:41]
	v_rcp_iflag_f32_e32 v161, v161
	v_mul_f32_e32 v157, v160, v157
	v_rcp_iflag_f32_e32 v160, v187
	v_rcp_iflag_f32_e32 v153, v153
	v_cvt_f32_ubyte1_e32 v158, v151
	v_cndmask_b32_e64 v152, v152, v233, s[40:41]
	v_cvt_f32_ubyte2_e32 v159, v151
	v_cvt_f32_ubyte3_e32 v151, v151
	v_cndmask_b32_e64 v161, v161, v233, s[40:41]
	v_mul_f32_e32 v152, v152, v158
	v_cndmask_b32_e64 v158, v160, v233, s[40:41]
	v_cndmask_b32_e64 v153, v153, v233, s[40:41]
	v_add_u32_e32 v144, 0xb0, v144
	v_mul_f32_e32 v155, v161, v155
	v_mul_f32_e32 v158, v158, v159
	v_mul_f32_e32 v151, v153, v151
	v_ashrrev_i32_e32 v145, 31, v144
	v_mul_f32_e32 v40, v40, v154
	v_mul_f32_e32 v41, v41, v155
	v_mul_f32_e32 v42, v42, v156
	v_mul_f32_e32 v43, v43, v150
	v_mul_f32_e32 v36, v36, v157
	v_mul_f32_e32 v37, v37, v152
	v_mul_f32_e32 v38, v38, v158
	s_and_b64 vcc, exec, s[42:43]
	v_mul_f32_e32 v39, v39, v151
	s_cbranch_vccnz .LBB0_2056
	v_lshlrev_b64 v[154:155], 12, v[144:145]
	v_lshl_add_u64 v[154:155], s[28:29], 0, v[154:155]
	v_cvt_pk_bf16_f32 v150, v40, v41
	v_cvt_pk_bf16_f32 v151, v42, v43
	v_cvt_pk_bf16_f32 v152, v36, v37
	v_cvt_pk_bf16_f32 v153, v38, v39
	v_lshl_add_u64 v[154:155], v[142:143], 1, v[154:155]
	global_store_dwordx4 v[154:155], v[150:153], off sc0 sc1
.LBB0_2056:
	s_waitcnt vmcnt(0)
	v_cvt_f32_ubyte0_e32 v156, v146
	v_rcp_iflag_f32_e32 v156, v156
	v_cvt_f32_ubyte0_e32 v150, v148
	v_cvt_f32_ubyte2_e32 v158, v146
	v_cvt_f32_ubyte1_e32 v157, v146
	v_cndmask_b32_e64 v156, v156, v233, s[40:41]
	v_mul_f32_e32 v150, v156, v150
	v_rcp_iflag_f32_e32 v156, v158
	v_cvt_f32_ubyte3_e32 v146, v146
	v_cvt_f32_ubyte2_e32 v152, v148
	v_cvt_f32_ubyte0_e32 v159, v147
	v_rcp_iflag_f32_e32 v146, v146
	v_cndmask_b32_e64 v156, v156, v233, s[40:41]
	v_mul_f32_e32 v152, v156, v152
	v_rcp_iflag_f32_e32 v156, v159
	v_cvt_f32_ubyte1_e32 v151, v148
	v_cvt_f32_ubyte3_e32 v148, v148
	v_cvt_f32_ubyte1_e32 v160, v147
	v_cndmask_b32_e64 v146, v146, v233, s[40:41]
	v_cvt_f32_ubyte0_e32 v153, v149
	v_cvt_f32_ubyte2_e32 v161, v147
	v_cvt_f32_ubyte3_e32 v147, v147
	v_mul_f32_e32 v146, v146, v148
	v_rcp_iflag_f32_e32 v148, v160
	v_cndmask_b32_e64 v156, v156, v233, s[40:41]
	v_rcp_iflag_f32_e32 v157, v157
	v_mul_f32_e32 v153, v156, v153
	v_rcp_iflag_f32_e32 v156, v161
	v_rcp_iflag_f32_e32 v147, v147
	v_cvt_f32_ubyte1_e32 v154, v149
	v_cndmask_b32_e64 v148, v148, v233, s[40:41]
	v_cvt_f32_ubyte2_e32 v155, v149
	v_cvt_f32_ubyte3_e32 v149, v149
	v_cndmask_b32_e64 v157, v157, v233, s[40:41]
	v_mul_f32_e32 v148, v148, v154
	v_cndmask_b32_e64 v154, v156, v233, s[40:41]
	v_cndmask_b32_e64 v147, v147, v233, s[40:41]
	v_mul_f32_e32 v151, v157, v151
	v_mul_f32_e32 v154, v154, v155
	v_mul_f32_e32 v147, v147, v149
	v_mul_f32_e32 v6, v6, v150
	v_mul_f32_e32 v7, v7, v151
	v_mul_f32_e32 v8, v8, v152
	v_mul_f32_e32 v9, v9, v146
	v_mul_f32_e32 v2, v2, v153
	v_mul_f32_e32 v3, v3, v148
	v_mul_f32_e32 v4, v4, v154
	s_and_b64 vcc, exec, s[42:43]
	v_mul_f32_e32 v5, v5, v147
	s_cbranch_vccnz .LBB0_2058
	v_lshlrev_b64 v[144:145], 12, v[144:145]
	v_lshl_add_u64 v[144:145], s[28:29], 0, v[144:145]
	v_cvt_pk_bf16_f32 v146, v6, v7
	v_cvt_pk_bf16_f32 v147, v8, v9
	v_cvt_pk_bf16_f32 v148, v2, v3
	v_cvt_pk_bf16_f32 v149, v4, v5
	v_lshl_add_u64 v[142:143], v[142:143], 1, v[144:145]
	global_store_dwordx4 v[142:143], v[146:149], off offset:256 sc0 sc1
.LBB0_2058:
	s_and_b64 vcc, exec, s[38:39]
	s_mov_b64 s[38:39], -1
	s_cbranch_vccnz .LBB0_2011
	s_and_b64 vcc, exec, s[42:43]
	s_cbranch_vccnz .LBB0_2061
	v_mov_b32_e32 v2, 0
	v_mov_b32_e32 v3, v2
	v_mov_b64_e32 v[4:5], 0
	v_mov_b64_e32 v[6:7], 0
	v_mov_b64_e32 v[8:9], 0
	v_mov_b64_e32 v[10:11], 0
	v_mov_b64_e32 v[12:13], 0
	v_mov_b64_e32 v[14:15], 0
	v_mov_b64_e32 v[16:17], 0
	v_mov_b64_e32 v[18:19], 0
	v_mov_b64_e32 v[20:21], 0
	v_mov_b64_e32 v[22:23], 0
	v_mov_b64_e32 v[24:25], 0
	v_mov_b64_e32 v[26:27], 0
	v_mov_b64_e32 v[28:29], 0
	v_mov_b64_e32 v[30:31], 0
	v_mov_b64_e32 v[32:33], 0
	v_mov_b64_e32 v[36:37], 0
	v_mov_b64_e32 v[38:39], 0
	v_mov_b64_e32 v[40:41], 0
	v_mov_b64_e32 v[42:43], 0
	v_mov_b64_e32 v[44:45], 0
	v_mov_b64_e32 v[46:47], 0
	v_mov_b64_e32 v[48:49], 0
	v_mov_b64_e32 v[50:51], 0
	v_mov_b64_e32 v[52:53], 0
	v_mov_b64_e32 v[54:55], 0
	v_mov_b64_e32 v[56:57], 0
	v_mov_b64_e32 v[58:59], 0
	v_mov_b64_e32 v[60:61], 0
	v_mov_b64_e32 v[62:63], 0
	v_mov_b64_e32 v[64:65], 0
	v_mov_b64_e32 v[66:67], 0
	v_mov_b64_e32 v[68:69], 0
	v_mov_b64_e32 v[70:71], 0
	v_mov_b64_e32 v[72:73], 0
	v_mov_b64_e32 v[74:75], 0
	v_mov_b64_e32 v[76:77], 0
	v_mov_b64_e32 v[78:79], 0
	v_mov_b64_e32 v[80:81], 0
	v_mov_b64_e32 v[82:83], 0
	v_mov_b64_e32 v[84:85], 0
	v_mov_b64_e32 v[86:87], 0
	v_mov_b64_e32 v[88:89], 0
	v_mov_b64_e32 v[90:91], 0
	v_mov_b64_e32 v[92:93], 0
	v_mov_b64_e32 v[94:95], 0
	v_mov_b64_e32 v[96:97], 0
	v_mov_b64_e32 v[98:99], 0
	v_mov_b64_e32 v[100:101], 0
	v_mov_b64_e32 v[102:103], 0
	v_mov_b64_e32 v[104:105], 0
	v_mov_b64_e32 v[106:107], 0
	v_mov_b64_e32 v[108:109], 0
	v_mov_b64_e32 v[110:111], 0
	v_mov_b64_e32 v[112:113], 0
	v_mov_b64_e32 v[114:115], 0
	v_mov_b64_e32 v[116:117], 0
	v_mov_b64_e32 v[118:119], 0
	v_mov_b64_e32 v[120:121], 0
	v_mov_b64_e32 v[122:123], 0
	v_mov_b64_e32 v[124:125], 0
	v_mov_b64_e32 v[126:127], 0
	v_mov_b64_e32 v[128:129], 0
	v_mov_b64_e32 v[130:131], 0

;     __device__ __forceinline__ const char* pa(const Gemm& g, const Unit& u, size_t tstep) const { return (const char*)g.A + (size_t)u.pm * tstep; }
;     __device__ __forceinline__ const char* pb(const Gemm& g, const Unit& u, size_t tstep) const { return (const char*)g.Bt + (size_t)u.pn * tstep; }
;     __device__ __forceinline__ const char* pa(const Gemm& g, const Unit& u, size_t tstep) const { return (const char*)g.A + (size_t)(u.pn >> 1) * 512 + (size_t)u.pm * tstep; }
;     __device__ __forceinline__ bool next(int i, Unit& u) const { const int ti = i / 3, sg = i - 3 * ti; if (!StaticOrder::next(ti, u)) return false; u.seg = sg; return true; }
;     __device__ __forceinline__ const char* pa(const Gemm& g, const Unit& u, size_t tstep) const { return (const char*)g.A + (size_t)u.seg * astride + (size_t)u.pm * tstep; }
;     __device__ __forceinline__ const char* pb(const Gemm& g, const Unit& u, size_t tstep) const { return (const char*)g.Bt + (size_t)u.seg * bstride + (size_t)u.pn * tstep; }
; #define PG8_STAGE(bufoff, gbase, voff) do { _Pragma("unroll") for (int _i = 0; _i < 2; ++_i) \
;         __builtin_amdgcn_global_load_lds((const unsigned*)((const char*)(gbase) + (voff)[_i]), (PG8_LAS unsigned*)(lds + (bufoff) + ldsw + _i * 8192), 16, 0, 0); } while (0)
; #define PG8_LDA(dst, b, h) do { _Pragma("unroll") for (int m = 0; m < 4; ++m) _Pragma("unroll") for (int k = 0; k < 2; ++k) dst[m][k] = *(const PG8_LAS bf16x8*)(lds + PG8_SA(b, h) + aoff + m * 2048 + k * 1024); } while (0)
;     ...
;         const bool has_next = S.next(ui + 1, nxt);
;         const char* nA = has_next ? S.pa(g, nxt, tstepA) : cA; const char* nB = has_next ? S.pb(g, nxt, tstepB) : cB;
;         for (int t = 0; t < nt; t += 2) {
;             const bool last = (t == nt - 2);
;             const char* a1 = cA + (size_t)(t + 1) * kstep;
;             const char* a2 = last ? nA : cA + (size_t)(t + 2) * kstep; const char* b2 = last ? nB : cB + (size_t)(t + 2) * kstep;
;             const char* a3 = a2 + kstep; const char* b3 = b2 + kstep;
;             if (last && has_next) S.a_ready(nxt);
;             if constexpr (SP2) {
;             PG8_LDB(B0, 0, 0); PG8_LDB(B1, 0, 1); PG8_SCHED; PG8_LDA(At, 0, 0); PG8_STAGE(PG8_SA(1, 1), a1 + hstepA, voffA);
;             PG8_WAIT_V(8); PG8_WAIT_L(0); PG8_BAR; PG8_MMA(0, 0, At, B0); PG8_MMA(0, 1, At, B1); PG8_BAR; PG8_SCHED;
.LBB0_2137:
	s_ashr_i32 s41, s40, 31
	s_lshl_b64 s[42:43], s[40:41], 20
	s_add_u32 s42, s10, s42
	s_addc_u32 s43, s11, s43
	s_and_b64 s[44:45], s[38:39], exec
	s_cselect_b32 s41, s43, s47
	s_cselect_b32 s56, s42, s46
	s_ashr_i32 s37, s36, 31
	s_lshl_b64 s[44:45], s[36:37], 20
	s_add_u32 s44, s12, s44
	s_addc_u32 s45, s13, s45
	s_and_b64 s[50:51], s[38:39], exec
	s_cselect_b32 s37, s45, s49
	s_cselect_b32 s57, s44, s48
	s_add_u32 s46, s46, 0x80080
	s_addc_u32 s47, s47, 0
	s_add_u32 s58, s48, 0x100
	v_mov_b32_e32 v2, 0
	s_addc_u32 s59, s49, 0
	s_mov_b32 s60, -2
	v_mov_b32_e32 v3, v2
	v_mov_b64_e32 v[4:5], 0
	v_mov_b64_e32 v[6:7], 0
	v_mov_b64_e32 v[8:9], 0
	v_mov_b64_e32 v[10:11], 0
	v_mov_b64_e32 v[12:13], 0
	v_mov_b64_e32 v[14:15], 0
	v_mov_b64_e32 v[16:17], 0
	v_mov_b64_e32 v[18:19], 0
	v_mov_b64_e32 v[20:21], 0
	v_mov_b64_e32 v[22:23], 0
	v_mov_b64_e32 v[24:25], 0
	v_mov_b64_e32 v[26:27], 0
	v_mov_b64_e32 v[28:29], 0
	v_mov_b64_e32 v[30:31], 0
	v_mov_b64_e32 v[32:33], 0
	v_mov_b64_e32 v[36:37], 0
	v_mov_b64_e32 v[38:39], 0
	v_mov_b64_e32 v[40:41], 0
	v_mov_b64_e32 v[42:43], 0
	v_mov_b64_e32 v[44:45], 0
	v_mov_b64_e32 v[46:47], 0
	v_mov_b64_e32 v[48:49], 0
	v_mov_b64_e32 v[50:51], 0
	v_mov_b64_e32 v[52:53], 0
	v_mov_b64_e32 v[54:55], 0
	v_mov_b64_e32 v[56:57], 0
	v_mov_b64_e32 v[58:59], 0
	v_mov_b64_e32 v[60:61], 0
	v_mov_b64_e32 v[62:63], 0
	v_mov_b64_e32 v[64:65], 0
	v_mov_b64_e32 v[66:67], 0
	v_mov_b64_e32 v[68:69], 0
	v_mov_b64_e32 v[70:71], 0
	v_mov_b64_e32 v[72:73], 0
	v_mov_b64_e32 v[74:75], 0
	v_mov_b64_e32 v[76:77], 0
	v_mov_b64_e32 v[78:79], 0
	v_mov_b64_e32 v[80:81], 0
	v_mov_b64_e32 v[82:83], 0
	v_mov_b64_e32 v[84:85], 0
	v_mov_b64_e32 v[86:87], 0
	v_mov_b64_e32 v[88:89], 0
	v_mov_b64_e32 v[90:91], 0
	v_mov_b64_e32 v[92:93], 0
	v_mov_b64_e32 v[94:95], 0
	v_mov_b64_e32 v[96:97], 0
	v_mov_b64_e32 v[98:99], 0
	v_mov_b64_e32 v[100:101], 0
	v_mov_b64_e32 v[102:103], 0
	v_mov_b64_e32 v[104:105], 0
	v_mov_b64_e32 v[106:107], 0
	v_mov_b64_e32 v[108:109], 0
	v_mov_b64_e32 v[110:111], 0
	v_mov_b64_e32 v[112:113], 0
	v_mov_b64_e32 v[114:115], 0
	v_mov_b64_e32 v[116:117], 0
	v_mov_b64_e32 v[118:119], 0
	v_mov_b64_e32 v[120:121], 0
	v_mov_b64_e32 v[122:123], 0
	v_mov_b64_e32 v[124:125], 0
	v_mov_b64_e32 v[126:127], 0
	v_mov_b64_e32 v[128:129], 0
	v_mov_b64_e32 v[130:131], 0
.LBB0_2138:
	s_add_u32 s48, s46, 0xfff80080
	s_addc_u32 s49, s47, -1
	s_add_i32 s61, 0, 0x10000
	s_cmp_eq_u32 s60, 28
	s_cselect_b32 s51, s41, s49
	s_cselect_b32 s50, s56, s48
	s_cselect_b32 s49, s37, s59
	s_cselect_b32 s48, s57, s58
	s_add_i32 s64, 0, 0x14000
	v_add_u32_e32 v158, s61, v143
	v_add_u32_e32 v162, s64, v143
	ds_read_b128 v[146:149], v158
	ds_read_b128 v[150:153], v158 offset:1024
	ds_read_b128 v[154:157], v158 offset:2048
	ds_read_b128 v[158:161], v158 offset:3072
	ds_read_b128 v[186:189], v162
	ds_read_b128 v[190:193], v162 offset:1024
	ds_read_b128 v[194:197], v162 offset:2048
	ds_read_b128 v[198:201], v162 offset:3072
	v_lshl_add_u64 v[162:163], s[46:47], 0, v[138:139]
	s_add_i32 m0, s21, 0xc000
	ds_read_b128 v[202:205], v145
	ds_read_b128 v[206:209], v145 offset:1024
	ds_read_b128 v[210:213], v145 offset:2048
	ds_read_b128 v[214:217], v145 offset:3072
	ds_read_b128 v[218:221], v145 offset:4096
	ds_read_b128 v[222:225], v145 offset:5120
	ds_read_b128 v[234:237], v145 offset:6144
	ds_read_b128 v[238:241], v145 offset:7168
	global_load_lds_dwordx4 v[162:163], off
	v_lshl_add_u64 v[162:163], s[46:47], 0, v[140:141]
	s_add_i32 m0, s21, 0xe000
	s_nop 0
	global_load_lds_dwordx4 v[162:163], off
	s_waitcnt vmcnt(8)
	s_waitcnt lgkmcnt(0)
	s_barrier
	s_setprio 1
	v_mfma_f32_16x16x32_bf16 v[128:131], v[146:149], v[202:205], v[128:131]
	v_mfma_f32_16x16x32_bf16 v[124:127], v[154:157], v[202:205], v[124:127]
	v_mfma_f32_16x16x32_bf16 v[120:123], v[146:149], v[210:213], v[120:123]
	v_mfma_f32_16x16x32_bf16 v[116:119], v[154:157], v[210:213], v[116:119]
	v_mfma_f32_16x16x32_bf16 v[104:107], v[146:149], v[218:221], v[104:107]
	v_mfma_f32_16x16x32_bf16 v[100:103], v[154:157], v[218:221], v[100:103]
	v_mfma_f32_16x16x32_bf16 v[88:91], v[146:149], v[234:237], v[88:91]
	v_mfma_f32_16x16x32_bf16 v[84:87], v[154:157], v[234:237], v[84:87]
	v_mfma_f32_16x16x32_bf16 v[128:131], v[150:153], v[206:209], v[128:131]
	v_mfma_f32_16x16x32_bf16 v[124:127], v[158:161], v[206:209], v[124:127]
	v_mfma_f32_16x16x32_bf16 v[120:123], v[150:153], v[214:217], v[120:123]
	v_mfma_f32_16x16x32_bf16 v[116:119], v[158:161], v[214:217], v[116:119]
	v_mfma_f32_16x16x32_bf16 v[104:107], v[150:153], v[222:225], v[104:107]
	v_mfma_f32_16x16x32_bf16 v[100:103], v[158:161], v[222:225], v[100:103]
	v_mfma_f32_16x16x32_bf16 v[88:91], v[150:153], v[238:241], v[88:91]
	v_mfma_f32_16x16x32_bf16 v[84:87], v[158:161], v[238:241], v[84:87]
	v_mfma_f32_16x16x32_bf16 v[112:115], v[186:189], v[202:205], v[112:115]
	v_mfma_f32_16x16x32_bf16 v[108:111], v[194:197], v[202:205], v[108:111]
	v_mfma_f32_16x16x32_bf16 v[96:99], v[186:189], v[210:213], v[96:99]
	v_mfma_f32_16x16x32_bf16 v[92:95], v[194:197], v[210:213], v[92:95]
	v_mfma_f32_16x16x32_bf16 v[80:83], v[186:189], v[218:221], v[80:83]
	v_mfma_f32_16x16x32_bf16 v[76:79], v[194:197], v[218:221], v[76:79]
	v_mfma_f32_16x16x32_bf16 v[72:75], v[186:189], v[234:237], v[72:75]
	v_mfma_f32_16x16x32_bf16 v[68:71], v[194:197], v[234:237], v[68:71]
	v_mfma_f32_16x16x32_bf16 v[112:115], v[190:193], v[206:209], v[112:115]
	v_mfma_f32_16x16x32_bf16 v[108:111], v[198:201], v[206:209], v[108:111]
	v_mfma_f32_16x16x32_bf16 v[96:99], v[190:193], v[214:217], v[96:99]
	v_mfma_f32_16x16x32_bf16 v[92:95], v[198:201], v[214:217], v[92:95]
	v_mfma_f32_16x16x32_bf16 v[80:83], v[190:193], v[222:225], v[80:83]
	v_mfma_f32_16x16x32_bf16 v[76:79], v[198:201], v[222:225], v[76:79]
	v_mfma_f32_16x16x32_bf16 v[72:75], v[190:193], v[238:241], v[72:75]
	v_mfma_f32_16x16x32_bf16 v[68:71], v[198:201], v[238:241], v[68:71]
	s_setprio 0
	s_barrier
; #define PG8_STAGE(bufoff, gbase, voff) do { _Pragma("unroll") for (int _i = 0; _i < 2; ++_i) \
;         __builtin_amdgcn_global_load_lds((const unsigned*)((const char*)(gbase) + (voff)[_i]), (PG8_LAS unsigned*)(lds + (bufoff) + ldsw + _i * 8192), 16, 0, 0); } while (0)
; #define PG8_LDA(dst, b, h) do { _Pragma("unroll") for (int m = 0; m < 4; ++m) _Pragma("unroll") for (int k = 0; k < 2; ++k) dst[m][k] = *(const PG8_LAS bf16x8*)(lds + PG8_SA(b, h) + aoff + m * 2048 + k * 1024); } while (0)
; #define PG8_LDB(dst, b, h) do { _Pragma("unroll") for (int n = 0; n < 2; ++n) _Pragma("unroll") for (int k = 0; k < 2; ++k) dst[n][k] = *(const PG8_LAS bf16x8*)(lds + PG8_SB(b, h) + boff + n * 2048 + k * 1024); } while (0)
; #define PG8_WAIT_V(n) asm volatile("s_waitcnt vmcnt(" #n ")" ::: "memory")
; #define PG8_WAIT_L(n) asm volatile("s_waitcnt lgkmcnt(" #n ")" ::: "memory")
; #define PG8_BAR __builtin_amdgcn_s_barrier()
; #define PG8_SCHED __builtin_amdgcn_sched_barrier(0)
;     ...
;             PG8_LDA(At, 0, 1); PG8_STAGE(PG8_SB(0, 0), b2, voffB); PG8_STAGE(PG8_SB(0, 1), b2 + hstepB, voffB); PG8_STAGE(PG8_SA(0, 0), a2, voffA);
;             PG8_WAIT_V(8); PG8_WAIT_L(0); PG8_BAR; PG8_MMA(1, 0, At, B0); PG8_MMA(1, 1, At, B1); PG8_BAR; PG8_SCHED;
;             PG8_LDB(B0, 1, 0); PG8_LDB(B1, 1, 1); PG8_SCHED; PG8_LDA(At, 1, 0); PG8_STAGE(PG8_SA(0, 1), a2 + hstepA, voffA);
	s_add_i32 s61, s61, s15
	v_lshl_add_u64 v[162:163], s[48:49], 0, v[34:35]
	s_mov_b32 m0, s61
	ds_read_b128 v[202:205], v145 offset:16384
	ds_read_b128 v[206:209], v145 offset:17408
	ds_read_b128 v[210:213], v145 offset:18432
	ds_read_b128 v[214:217], v145 offset:19456
	ds_read_b128 v[218:221], v145 offset:20480
	ds_read_b128 v[222:225], v145 offset:21504
	ds_read_b128 v[234:237], v145 offset:22528
	ds_read_b128 v[238:241], v145 offset:23552
	global_load_lds_dwordx4 v[162:163], off
	s_add_i32 m0, s61, 0x2000
	s_add_u32 s62, s48, 0x80000
	v_lshl_add_u64 v[226:227], s[48:49], 0, v[136:137]
	s_addc_u32 s63, s49, 0
	s_add_i32 s61, s64, s15
	global_load_lds_dwordx4 v[226:227], off
	v_lshl_add_u64 v[242:243], s[62:63], 0, v[34:35]
	s_mov_b32 m0, s61
	v_lshl_add_u64 v[244:245], s[50:51], 0, v[134:135]
	global_load_lds_dwordx4 v[242:243], off
	v_lshl_add_u64 v[242:243], s[62:63], 0, v[136:137]
	s_add_i32 m0, s61, 0x2000
	s_nop 0
	global_load_lds_dwordx4 v[242:243], off
	v_lshl_add_u64 v[242:243], s[50:51], 0, v[132:133]
	s_mov_b32 m0, s21
	s_nop 0
	global_load_lds_dwordx4 v[242:243], off
	s_mov_b32 m0, s34
	s_nop 0
	global_load_lds_dwordx4 v[244:245], off
	s_waitcnt vmcnt(8)
	s_waitcnt lgkmcnt(0)
	s_barrier
	s_setprio 1
	v_mfma_f32_16x16x32_bf16 v[64:67], v[146:149], v[202:205], v[64:67]
	v_mfma_f32_16x16x32_bf16 v[60:63], v[154:157], v[202:205], v[60:63]
	v_mfma_f32_16x16x32_bf16 v[56:59], v[146:149], v[210:213], v[56:59]
	v_mfma_f32_16x16x32_bf16 v[52:55], v[154:157], v[210:213], v[52:55]
	v_mfma_f32_16x16x32_bf16 v[40:43], v[146:149], v[218:221], v[40:43]
	v_mfma_f32_16x16x32_bf16 v[36:39], v[154:157], v[218:221], v[36:39]
	v_mfma_f32_16x16x32_bf16 v[22:25], v[146:149], v[234:237], v[22:25]
	v_mfma_f32_16x16x32_bf16 v[18:21], v[154:157], v[234:237], v[18:21]
	v_mfma_f32_16x16x32_bf16 v[64:67], v[150:153], v[206:209], v[64:67]
	v_mfma_f32_16x16x32_bf16 v[60:63], v[158:161], v[206:209], v[60:63]
	v_mfma_f32_16x16x32_bf16 v[56:59], v[150:153], v[214:217], v[56:59]
	v_mfma_f32_16x16x32_bf16 v[52:55], v[158:161], v[214:217], v[52:55]
	v_mfma_f32_16x16x32_bf16 v[40:43], v[150:153], v[222:225], v[40:43]
	v_mfma_f32_16x16x32_bf16 v[36:39], v[158:161], v[222:225], v[36:39]
	v_mfma_f32_16x16x32_bf16 v[22:25], v[150:153], v[238:241], v[22:25]
	v_mfma_f32_16x16x32_bf16 v[18:21], v[158:161], v[238:241], v[18:21]
	v_mfma_f32_16x16x32_bf16 v[48:51], v[186:189], v[202:205], v[48:51]
	v_mfma_f32_16x16x32_bf16 v[44:47], v[194:197], v[202:205], v[44:47]
	v_mfma_f32_16x16x32_bf16 v[30:33], v[186:189], v[210:213], v[30:33]
	v_mfma_f32_16x16x32_bf16 v[26:29], v[194:197], v[210:213], v[26:29]
	v_mfma_f32_16x16x32_bf16 v[14:17], v[186:189], v[218:221], v[14:17]
	v_mfma_f32_16x16x32_bf16 v[10:13], v[194:197], v[218:221], v[10:13]
	v_mfma_f32_16x16x32_bf16 v[6:9], v[186:189], v[234:237], v[6:9]
	v_mfma_f32_16x16x32_bf16 v[2:5], v[194:197], v[234:237], v[2:5]
	v_mfma_f32_16x16x32_bf16 v[48:51], v[190:193], v[206:209], v[48:51]
	v_mfma_f32_16x16x32_bf16 v[44:47], v[198:201], v[206:209], v[44:47]
	v_mfma_f32_16x16x32_bf16 v[30:33], v[190:193], v[214:217], v[30:33]
	v_mfma_f32_16x16x32_bf16 v[26:29], v[198:201], v[214:217], v[26:29]
	v_mfma_f32_16x16x32_bf16 v[14:17], v[190:193], v[222:225], v[14:17]
	v_mfma_f32_16x16x32_bf16 v[10:13], v[198:201], v[222:225], v[10:13]
	v_mfma_f32_16x16x32_bf16 v[6:9], v[190:193], v[238:241], v[6:9]
	v_mfma_f32_16x16x32_bf16 v[2:5], v[198:201], v[238:241], v[2:5]
	s_setprio 0
	s_barrier
	s_add_i32 s61, 0, 0x18000
	s_add_i32 s62, 0, 0x1c000
	v_add_u32_e32 v158, s61, v143
	v_add_u32_e32 v198, s62, v143
	ds_read_b128 v[146:149], v158
	ds_read_b128 v[150:153], v158 offset:1024
	ds_read_b128 v[154:157], v158 offset:2048
	ds_read_b128 v[158:161], v158 offset:3072
	ds_read_b128 v[186:189], v198
	ds_read_b128 v[190:193], v198 offset:1024
	ds_read_b128 v[194:197], v198 offset:2048
	ds_read_b128 v[198:201], v198 offset:3072
	s_add_u32 s50, s50, 0x80000
	s_addc_u32 s51, s51, 0
	s_mov_b32 m0, s35
	v_lshl_add_u64 v[246:247], s[50:51], 0, v[132:133]
	ds_read_b128 v[202:205], v145 offset:32768
	ds_read_b128 v[206:209], v145 offset:33792
	ds_read_b128 v[210:213], v145 offset:34816
	ds_read_b128 v[214:217], v145 offset:35840
	ds_read_b128 v[218:221], v145 offset:36864
	ds_read_b128 v[222:225], v145 offset:37888
	ds_read_b128 v[234:237], v145 offset:38912
	ds_read_b128 v[238:241], v145 offset:39936
	global_load_lds_dwordx4 v[246:247], off
	v_lshl_add_u64 v[246:247], s[50:51], 0, v[134:135]
	s_mov_b32 m0, s52
	s_nop 0
	global_load_lds_dwordx4 v[246:247], off
	s_waitcnt vmcnt(8)
	s_waitcnt lgkmcnt(0)
	s_barrier
; #define PG8_STAGE(bufoff, gbase, voff) do { _Pragma("unroll") for (int _i = 0; _i < 2; ++_i) \
;         __builtin_amdgcn_global_load_lds((const unsigned*)((const char*)(gbase) + (voff)[_i]), (PG8_LAS unsigned*)(lds + (bufoff) + ldsw + _i * 8192), 16, 0, 0); } while (0)
; #define PG8_LDA(dst, b, h) do { _Pragma("unroll") for (int m = 0; m < 4; ++m) _Pragma("unroll") for (int k = 0; k < 2; ++k) dst[m][k] = *(const PG8_LAS bf16x8*)(lds + PG8_SA(b, h) + aoff + m * 2048 + k * 1024); } while (0)
; #define PG8_WAIT_V(n) asm volatile("s_waitcnt vmcnt(" #n ")" ::: "memory")
; #define PG8_WAIT_L(n) asm volatile("s_waitcnt lgkmcnt(" #n ")" ::: "memory")
; #define PG8_BAR __builtin_amdgcn_s_barrier()
; #define PG8_SCHED __builtin_amdgcn_sched_barrier(0)
;     ...
;         for (int t = 0; t < nt; t += 2) {
;             const bool last = (t == nt - 2);
;             const char* a1 = cA + (size_t)(t + 1) * kstep;
;             const char* a2 = last ? nA : cA + (size_t)(t + 2) * kstep; const char* b2 = last ? nB : cB + (size_t)(t + 2) * kstep;
;     ...
;             PG8_WAIT_V(8); PG8_WAIT_L(0); PG8_BAR; PG8_MMA(0, 0, At, B0); PG8_MMA(0, 1, At, B1); PG8_BAR; PG8_SCHED;
;             PG8_LDA(At, 1, 1); PG8_STAGE(PG8_SB(1, 0), b3, voffB); PG8_STAGE(PG8_SB(1, 1), b3 + hstepB, voffB); PG8_STAGE(PG8_SA(1, 0), a3, voffA);
;             PG8_WAIT_V(8); PG8_WAIT_L(0); PG8_BAR; PG8_MMA(1, 0, At, B0); PG8_MMA(1, 1, At, B1); PG8_BAR; PG8_SCHED;
	s_setprio 1
	v_mfma_f32_16x16x32_bf16 v[128:131], v[146:149], v[202:205], v[128:131]
	v_mfma_f32_16x16x32_bf16 v[124:127], v[154:157], v[202:205], v[124:127]
	v_mfma_f32_16x16x32_bf16 v[120:123], v[146:149], v[210:213], v[120:123]
	v_mfma_f32_16x16x32_bf16 v[116:119], v[154:157], v[210:213], v[116:119]
	v_mfma_f32_16x16x32_bf16 v[104:107], v[146:149], v[218:221], v[104:107]
	v_mfma_f32_16x16x32_bf16 v[100:103], v[154:157], v[218:221], v[100:103]
	v_mfma_f32_16x16x32_bf16 v[88:91], v[146:149], v[234:237], v[88:91]
	v_mfma_f32_16x16x32_bf16 v[84:87], v[154:157], v[234:237], v[84:87]
	v_mfma_f32_16x16x32_bf16 v[128:131], v[150:153], v[206:209], v[128:131]
	v_mfma_f32_16x16x32_bf16 v[124:127], v[158:161], v[206:209], v[124:127]
	v_mfma_f32_16x16x32_bf16 v[120:123], v[150:153], v[214:217], v[120:123]
	v_mfma_f32_16x16x32_bf16 v[116:119], v[158:161], v[214:217], v[116:119]
	v_mfma_f32_16x16x32_bf16 v[104:107], v[150:153], v[222:225], v[104:107]
	v_mfma_f32_16x16x32_bf16 v[100:103], v[158:161], v[222:225], v[100:103]
	v_mfma_f32_16x16x32_bf16 v[88:91], v[150:153], v[238:241], v[88:91]
	v_mfma_f32_16x16x32_bf16 v[84:87], v[158:161], v[238:241], v[84:87]
	v_mfma_f32_16x16x32_bf16 v[112:115], v[186:189], v[202:205], v[112:115]
	v_mfma_f32_16x16x32_bf16 v[108:111], v[194:197], v[202:205], v[108:111]
	v_mfma_f32_16x16x32_bf16 v[96:99], v[186:189], v[210:213], v[96:99]
	v_mfma_f32_16x16x32_bf16 v[92:95], v[194:197], v[210:213], v[92:95]
	v_mfma_f32_16x16x32_bf16 v[80:83], v[186:189], v[218:221], v[80:83]
	v_mfma_f32_16x16x32_bf16 v[76:79], v[194:197], v[218:221], v[76:79]
	v_mfma_f32_16x16x32_bf16 v[72:75], v[186:189], v[234:237], v[72:75]
	v_mfma_f32_16x16x32_bf16 v[68:71], v[194:197], v[234:237], v[68:71]
	v_mfma_f32_16x16x32_bf16 v[112:115], v[190:193], v[206:209], v[112:115]
	v_mfma_f32_16x16x32_bf16 v[108:111], v[198:201], v[206:209], v[108:111]
	v_mfma_f32_16x16x32_bf16 v[96:99], v[190:193], v[214:217], v[96:99]
	v_mfma_f32_16x16x32_bf16 v[92:95], v[198:201], v[214:217], v[92:95]
	v_mfma_f32_16x16x32_bf16 v[80:83], v[190:193], v[222:225], v[80:83]
	v_mfma_f32_16x16x32_bf16 v[76:79], v[198:201], v[222:225], v[76:79]
	v_mfma_f32_16x16x32_bf16 v[72:75], v[190:193], v[238:241], v[72:75]
	v_mfma_f32_16x16x32_bf16 v[68:71], v[198:201], v[238:241], v[68:71]
	s_setprio 0
	s_barrier
	s_add_i32 s50, s61, s15
	v_lshl_add_u64 v[162:163], v[162:163], 0, s[22:23]
	s_mov_b32 m0, s50
	ds_read_b128 v[202:205], v145 offset:49152
	ds_read_b128 v[206:209], v145 offset:50176
	ds_read_b128 v[210:213], v145 offset:51200
	ds_read_b128 v[214:217], v145 offset:52224
	ds_read_b128 v[218:221], v145 offset:53248
	ds_read_b128 v[222:225], v145 offset:54272
	ds_read_b128 v[234:237], v145 offset:55296
	ds_read_b128 v[238:241], v145 offset:56320
	global_load_lds_dwordx4 v[162:163], off
	s_add_i32 m0, s50, 0x2000
	s_add_u32 s48, s48, 0x80080
	v_lshl_add_u64 v[162:163], v[226:227], 0, s[22:23]
	s_addc_u32 s49, s49, 0
	s_add_i32 s50, s62, s15
	global_load_lds_dwordx4 v[162:163], off
	v_lshl_add_u64 v[162:163], s[48:49], 0, v[34:35]
	s_mov_b32 m0, s50
	s_nop 0
	global_load_lds_dwordx4 v[162:163], off
	v_lshl_add_u64 v[162:163], s[48:49], 0, v[136:137]
	s_add_i32 m0, s50, 0x2000
	s_nop 0
	global_load_lds_dwordx4 v[162:163], off
	v_lshl_add_u64 v[162:163], v[242:243], 0, s[22:23]
	s_mov_b32 m0, s24
	s_nop 0
	global_load_lds_dwordx4 v[162:163], off
	v_lshl_add_u64 v[162:163], v[244:245], 0, s[22:23]
	s_mov_b32 m0, s53
	s_nop 0
	global_load_lds_dwordx4 v[162:163], off
	s_waitcnt vmcnt(8)
	s_waitcnt lgkmcnt(0)
	s_barrier
	s_setprio 1
	v_mfma_f32_16x16x32_bf16 v[64:67], v[146:149], v[202:205], v[64:67]
	v_mfma_f32_16x16x32_bf16 v[60:63], v[154:157], v[202:205], v[60:63]
	v_mfma_f32_16x16x32_bf16 v[56:59], v[146:149], v[210:213], v[56:59]
	v_mfma_f32_16x16x32_bf16 v[52:55], v[154:157], v[210:213], v[52:55]
	v_mfma_f32_16x16x32_bf16 v[40:43], v[146:149], v[218:221], v[40:43]
	v_mfma_f32_16x16x32_bf16 v[36:39], v[154:157], v[218:221], v[36:39]
	v_mfma_f32_16x16x32_bf16 v[22:25], v[146:149], v[234:237], v[22:25]
	v_mfma_f32_16x16x32_bf16 v[18:21], v[154:157], v[234:237], v[18:21]
	v_mfma_f32_16x16x32_bf16 v[64:67], v[150:153], v[206:209], v[64:67]
	v_mfma_f32_16x16x32_bf16 v[60:63], v[158:161], v[206:209], v[60:63]
	v_mfma_f32_16x16x32_bf16 v[56:59], v[150:153], v[214:217], v[56:59]
	v_mfma_f32_16x16x32_bf16 v[52:55], v[158:161], v[214:217], v[52:55]
	v_mfma_f32_16x16x32_bf16 v[40:43], v[150:153], v[222:225], v[40:43]
	v_mfma_f32_16x16x32_bf16 v[36:39], v[158:161], v[222:225], v[36:39]
	v_mfma_f32_16x16x32_bf16 v[22:25], v[150:153], v[238:241], v[22:25]
	v_mfma_f32_16x16x32_bf16 v[18:21], v[158:161], v[238:241], v[18:21]
	v_mfma_f32_16x16x32_bf16 v[48:51], v[186:189], v[202:205], v[48:51]
	v_mfma_f32_16x16x32_bf16 v[44:47], v[194:197], v[202:205], v[44:47]
	v_mfma_f32_16x16x32_bf16 v[30:33], v[186:189], v[210:213], v[30:33]
	v_mfma_f32_16x16x32_bf16 v[26:29], v[194:197], v[210:213], v[26:29]
	v_mfma_f32_16x16x32_bf16 v[14:17], v[186:189], v[218:221], v[14:17]
	v_mfma_f32_16x16x32_bf16 v[10:13], v[194:197], v[218:221], v[10:13]
	v_mfma_f32_16x16x32_bf16 v[6:9], v[186:189], v[234:237], v[6:9]
	v_mfma_f32_16x16x32_bf16 v[2:5], v[194:197], v[234:237], v[2:5]
	v_mfma_f32_16x16x32_bf16 v[48:51], v[190:193], v[206:209], v[48:51]
	v_mfma_f32_16x16x32_bf16 v[44:47], v[198:201], v[206:209], v[44:47]
	v_mfma_f32_16x16x32_bf16 v[30:33], v[190:193], v[214:217], v[30:33]
	v_mfma_f32_16x16x32_bf16 v[26:29], v[198:201], v[214:217], v[26:29]
	v_mfma_f32_16x16x32_bf16 v[14:17], v[190:193], v[222:225], v[14:17]
	v_mfma_f32_16x16x32_bf16 v[10:13], v[198:201], v[222:225], v[10:13]
	v_mfma_f32_16x16x32_bf16 v[6:9], v[190:193], v[238:241], v[6:9]
	v_mfma_f32_16x16x32_bf16 v[2:5], v[198:201], v[238:241], v[2:5]
	s_setprio 0
	s_barrier
	s_add_i32 s60, s60, 2
	s_add_u32 s46, s46, 0x100
	s_addc_u32 s47, s47, 0
	s_add_u32 s58, s58, 0x100
	s_addc_u32 s59, s59, 0
	s_cmp_gt_u32 s60, 29
	s_cbranch_scc0 .LBB0_2138
	s_and_b64 vcc, exec, s[28:29]
	s_cbranch_vccz .LBB0_2141
	s_barrier
